# GEMM main loops: MFMA segments hold only the 32 MFMAs between their barriers (setprio raised before the pre-MFMA barrier and dropped after the post-MFMA barrier; duplicate lgkmcnt(0) and mid setprio p
# speedup vs baseline: 1.0053x; 1.0039x over previous
; #define PG8_STAGE(bufoff, gbase, voff) do { _Pragma("unroll") for (int _i = 0; _i < 2; ++_i) \
;         __builtin_amdgcn_global_load_lds((const unsigned*)((const char*)(gbase) + (voff)[_i]), (LAS unsigned*)(lds + (bufoff) + ldsw + _i * 8192), 16, 0, 0); } while (0)
; #define PG8_LDA(dst, b, h) do { _Pragma("unroll") for (int m = 0; m < 4; ++m) _Pragma("unroll") for (int k = 0; k < 2; ++k) dst[m][k] = *(const LAS bf16x8*)(lds + PG8_SA(b, h) + aoff + m * 2048 + k * 1024); } while (0)
; #define PG8_LDB(dst, b, h) do { _Pragma("unroll") for (int n = 0; n < 2; ++n) _Pragma("unroll") for (int k = 0; k < 2; ++k) dst[n][k] = *(const LAS bf16x8*)(lds + PG8_SB(b, h) + boff + n * 2048 + k * 1024); } while (0)
; #define PG8_MMA(ai, bj, At, Bt) do { __builtin_amdgcn_s_setprio(1); _Pragma("unroll") for (int m = 0; m < 4; ++m) _Pragma("unroll") for (int n = 0; n < 2; ++n) _Pragma("unroll") for (int k = 0; k < 2; ++k) \
;         acc[ai][bj][m][n] = __builtin_amdgcn_mfma_f32_16x16x32_bf16(Bt[n][k], At[m][k], acc[ai][bj][m][n], 0, 0, 0); __builtin_amdgcn_s_setprio(0); } while (0)
; #define PG8_WAIT_V(n) asm volatile("s_waitcnt vmcnt(" #n ")" ::: "memory")
; #define PG8_WAIT_L(n) asm volatile("s_waitcnt lgkmcnt(" #n ")" ::: "memory")
; #define PG8_BAR __builtin_amdgcn_s_barrier()
; template <class Epi, class Sched, int LDA, int LDB, bool ALIGN_EPI = true>
; __device__ __forceinline__ void gemm_phase(LAS unsigned char* lds, const Gemm g, const Sched& S, const Epi& E, int wave) {
;     ...
;         for (int t = 0; t < nt; t += 2) {
;             const bool last = (t == nt - 2);
;             const char* a1 = cA + (size_t)(t + 1) * kstep;
;             const char* a2 = last ? nA : cA + (size_t)(t + 2) * kstep; const char* b2 = last ? nB : cB + (size_t)(t + 2) * kstep;
;             const char* a3 = a2 + kstep; const char* b3 = b2 + kstep;
;             PG8_LDB(B0, 0, 0); PG8_LDB(B1, 0, 1); PG8_SCHED; PG8_LDA(At, 0, 0); PG8_STAGE(PG8_SA(1, 1), a1 + hstepA, voffA);
;             PG8_WAIT_V(8); PG8_WAIT_L(0); PG8_BAR; PG8_MMA(0, 0, At, B0); PG8_MMA(0, 1, At, B1); PG8_BAR; PG8_SCHED;
;             PG8_LDA(At, 0, 1); PG8_STAGE(PG8_SB(0, 0), b2, voffB); PG8_STAGE(PG8_SB(0, 1), b2 + hstepB, voffB); PG8_STAGE(PG8_SA(0, 0), a2, voffA);
;             PG8_WAIT_V(8); PG8_WAIT_L(0); PG8_BAR; PG8_MMA(1, 0, At, B0); PG8_MMA(1, 1, At, B1); PG8_BAR; PG8_SCHED;
.LBB0_485:
	s_add_u32 s24, s18, 0x100
	s_addc_u32 s25, s19, 0
	s_add_i32 s54, 0, 0x10000
	s_cmp_eq_u32 s53, 28
	s_cselect_b32 s35, s3, s25
	s_cselect_b32 s34, s2, s24
	v_add_u32_e32 v140, s54, v143
	s_cselect_b32 s29, s1, s45
	s_cselect_b32 s28, s17, s44
	s_add_i32 s55, 0, 0x14000
	ds_read_b128 v[146:149], v140
	ds_read_b128 v[150:153], v140 offset:1024
	ds_read_b128 v[154:157], v140 offset:2048
	ds_read_b128 v[158:161], v140 offset:3072
	v_add_u32_e32 v140, s55, v143
	ds_read_b128 v[162:165], v140
	ds_read_b128 v[166:169], v140 offset:1024
	ds_read_b128 v[170:173], v140 offset:2048
	ds_read_b128 v[180:183], v140 offset:3072
	v_lshl_add_u64 v[140:141], s[18:19], 0, v[136:137]
	s_add_i32 m0, s38, 0xc000
	ds_read_b128 v[184:187], v145
	ds_read_b128 v[188:191], v145 offset:1024
	ds_read_b128 v[192:195], v145 offset:2048
	ds_read_b128 v[196:199], v145 offset:3072
	ds_read_b128 v[200:203], v145 offset:4096
	ds_read_b128 v[204:207], v145 offset:5120
	ds_read_b128 v[208:211], v145 offset:6144
	ds_read_b128 v[212:215], v145 offset:7168
	global_load_lds_dwordx4 v[140:141], off
	v_lshl_add_u64 v[140:141], s[18:19], 0, v[138:139]
	s_add_i32 m0, s38, 0xe000
	s_nop 0
	global_load_lds_dwordx4 v[140:141], off
	s_waitcnt vmcnt(8)
	s_waitcnt lgkmcnt(0)
	s_setprio 1
	s_barrier
	v_mfma_f32_16x16x32_bf16 v[126:129], v[146:149], v[184:187], v[126:129]
	v_mfma_f32_16x16x32_bf16 v[118:121], v[154:157], v[184:187], v[118:121]
	v_mfma_f32_16x16x32_bf16 v[110:113], v[146:149], v[192:195], v[110:113]
	v_mfma_f32_16x16x32_bf16 v[102:105], v[154:157], v[192:195], v[102:105]
	v_mfma_f32_16x16x32_bf16 v[94:97], v[146:149], v[200:203], v[94:97]
	v_mfma_f32_16x16x32_bf16 v[86:89], v[154:157], v[200:203], v[86:89]
	v_mfma_f32_16x16x32_bf16 v[78:81], v[146:149], v[208:211], v[78:81]
	v_mfma_f32_16x16x32_bf16 v[70:73], v[154:157], v[208:211], v[70:73]
	v_mfma_f32_16x16x32_bf16 v[126:129], v[150:153], v[188:191], v[126:129]
	v_mfma_f32_16x16x32_bf16 v[118:121], v[158:161], v[188:191], v[118:121]
	v_mfma_f32_16x16x32_bf16 v[110:113], v[150:153], v[196:199], v[110:113]
	v_mfma_f32_16x16x32_bf16 v[102:105], v[158:161], v[196:199], v[102:105]
	v_mfma_f32_16x16x32_bf16 v[94:97], v[150:153], v[204:207], v[94:97]
	v_mfma_f32_16x16x32_bf16 v[86:89], v[158:161], v[204:207], v[86:89]
	v_mfma_f32_16x16x32_bf16 v[78:81], v[150:153], v[212:215], v[78:81]
	v_mfma_f32_16x16x32_bf16 v[70:73], v[158:161], v[212:215], v[70:73]
	v_mfma_f32_16x16x32_bf16 v[122:125], v[162:165], v[184:187], v[122:125]
	v_mfma_f32_16x16x32_bf16 v[114:117], v[170:173], v[184:187], v[114:117]
	v_mfma_f32_16x16x32_bf16 v[106:109], v[162:165], v[192:195], v[106:109]
	v_mfma_f32_16x16x32_bf16 v[98:101], v[170:173], v[192:195], v[98:101]
	v_mfma_f32_16x16x32_bf16 v[90:93], v[162:165], v[200:203], v[90:93]
	v_mfma_f32_16x16x32_bf16 v[82:85], v[170:173], v[200:203], v[82:85]
	v_mfma_f32_16x16x32_bf16 v[74:77], v[162:165], v[208:211], v[74:77]
	v_mfma_f32_16x16x32_bf16 v[66:69], v[170:173], v[208:211], v[66:69]
	v_mfma_f32_16x16x32_bf16 v[122:125], v[166:169], v[188:191], v[122:125]
	v_mfma_f32_16x16x32_bf16 v[114:117], v[180:183], v[188:191], v[114:117]
	v_mfma_f32_16x16x32_bf16 v[106:109], v[166:169], v[196:199], v[106:109]
	v_mfma_f32_16x16x32_bf16 v[98:101], v[180:183], v[196:199], v[98:101]
	v_mfma_f32_16x16x32_bf16 v[90:93], v[166:169], v[204:207], v[90:93]
	v_mfma_f32_16x16x32_bf16 v[82:85], v[180:183], v[204:207], v[82:85]
	v_mfma_f32_16x16x32_bf16 v[74:77], v[166:169], v[212:215], v[74:77]
	v_mfma_f32_16x16x32_bf16 v[66:69], v[180:183], v[212:215], v[66:69]
	s_barrier
	s_setprio 0
	s_add_i32 s18, s54, s5
	v_lshl_add_u64 v[140:141], s[28:29], 0, v[0:1]
	s_mov_b32 m0, s18
	ds_read_b128 v[184:187], v145 offset:16384
	ds_read_b128 v[188:191], v145 offset:17408
	ds_read_b128 v[192:195], v145 offset:18432
	ds_read_b128 v[196:199], v145 offset:19456
	ds_read_b128 v[200:203], v145 offset:20480
	ds_read_b128 v[204:207], v145 offset:21504
	ds_read_b128 v[208:211], v145 offset:22528
	ds_read_b128 v[212:215], v145 offset:23552
	global_load_lds_dwordx4 v[140:141], off
	s_add_i32 m0, s18, 0x2000
	s_add_u32 s18, s28, 0x80000
	v_lshl_add_u64 v[174:175], s[28:29], 0, v[130:131]
	s_addc_u32 s19, s29, 0
	s_add_i32 s54, s55, s5
	global_load_lds_dwordx4 v[174:175], off
	v_lshl_add_u64 v[216:217], s[18:19], 0, v[0:1]
	s_mov_b32 m0, s54
	v_lshl_add_u64 v[218:219], s[34:35], 0, v[132:133]
	global_load_lds_dwordx4 v[216:217], off
	v_lshl_add_u64 v[216:217], s[18:19], 0, v[130:131]
	s_add_i32 m0, s54, 0x2000
	s_nop 0
	global_load_lds_dwordx4 v[216:217], off
	v_lshl_add_u64 v[216:217], s[34:35], 0, v[134:135]
	s_mov_b32 m0, s38
	s_nop 0
	global_load_lds_dwordx4 v[216:217], off
	s_mov_b32 m0, s39
	s_nop 0
	global_load_lds_dwordx4 v[218:219], off
	s_waitcnt vmcnt(8)
	s_waitcnt lgkmcnt(0)
	s_setprio 1
	s_barrier
; #define PG8_STAGE(bufoff, gbase, voff) do { _Pragma("unroll") for (int _i = 0; _i < 2; ++_i) \
;         __builtin_amdgcn_global_load_lds((const unsigned*)((const char*)(gbase) + (voff)[_i]), (LAS unsigned*)(lds + (bufoff) + ldsw + _i * 8192), 16, 0, 0); } while (0)
; #define PG8_LDA(dst, b, h) do { _Pragma("unroll") for (int m = 0; m < 4; ++m) _Pragma("unroll") for (int k = 0; k < 2; ++k) dst[m][k] = *(const LAS bf16x8*)(lds + PG8_SA(b, h) + aoff + m * 2048 + k * 1024); } while (0)
; #define PG8_LDB(dst, b, h) do { _Pragma("unroll") for (int n = 0; n < 2; ++n) _Pragma("unroll") for (int k = 0; k < 2; ++k) dst[n][k] = *(const LAS bf16x8*)(lds + PG8_SB(b, h) + boff + n * 2048 + k * 1024); } while (0)
; #define PG8_MMA(ai, bj, At, Bt) do { __builtin_amdgcn_s_setprio(1); _Pragma("unroll") for (int m = 0; m < 4; ++m) _Pragma("unroll") for (int n = 0; n < 2; ++n) _Pragma("unroll") for (int k = 0; k < 2; ++k) \
;         acc[ai][bj][m][n] = __builtin_amdgcn_mfma_f32_16x16x32_bf16(Bt[n][k], At[m][k], acc[ai][bj][m][n], 0, 0, 0); __builtin_amdgcn_s_setprio(0); } while (0)
; #define PG8_WAIT_V(n) asm volatile("s_waitcnt vmcnt(" #n ")" ::: "memory")
; #define PG8_WAIT_L(n) asm volatile("s_waitcnt lgkmcnt(" #n ")" ::: "memory")
; #define PG8_BAR __builtin_amdgcn_s_barrier()
; #define PG8_SCHED __builtin_amdgcn_sched_barrier(0)
; template <class Epi, class Sched, int LDA, int LDB, bool ALIGN_EPI = true>
; __device__ __forceinline__ void gemm_phase(LAS unsigned char* lds, const Gemm g, const Sched& S, const Epi& E, int wave) {
;     ...
;             PG8_WAIT_V(8); PG8_WAIT_L(0); PG8_BAR; PG8_MMA(1, 0, At, B0); PG8_MMA(1, 1, At, B1); PG8_BAR; PG8_SCHED;
;             PG8_LDB(B0, 1, 0); PG8_LDB(B1, 1, 1); PG8_SCHED; PG8_LDA(At, 1, 0); PG8_STAGE(PG8_SA(0, 1), a2 + hstepA, voffA);
;             PG8_WAIT_V(8); PG8_WAIT_L(0); PG8_BAR; PG8_MMA(0, 0, At, B0); PG8_MMA(0, 1, At, B1); PG8_BAR; PG8_SCHED;
	v_mfma_f32_16x16x32_bf16 v[62:65], v[146:149], v[184:187], v[62:65]
	v_mfma_f32_16x16x32_bf16 v[54:57], v[154:157], v[184:187], v[54:57]
	v_mfma_f32_16x16x32_bf16 v[46:49], v[146:149], v[192:195], v[46:49]
	v_mfma_f32_16x16x32_bf16 v[38:41], v[154:157], v[192:195], v[38:41]
	v_mfma_f32_16x16x32_bf16 v[30:33], v[146:149], v[200:203], v[30:33]
	v_mfma_f32_16x16x32_bf16 v[22:25], v[154:157], v[200:203], v[22:25]
	v_mfma_f32_16x16x32_bf16 v[14:17], v[146:149], v[208:211], v[14:17]
	v_mfma_f32_16x16x32_bf16 v[6:9], v[154:157], v[208:211], v[6:9]
	v_mfma_f32_16x16x32_bf16 v[62:65], v[150:153], v[188:191], v[62:65]
	v_mfma_f32_16x16x32_bf16 v[54:57], v[158:161], v[188:191], v[54:57]
	v_mfma_f32_16x16x32_bf16 v[46:49], v[150:153], v[196:199], v[46:49]
	v_mfma_f32_16x16x32_bf16 v[38:41], v[158:161], v[196:199], v[38:41]
	v_mfma_f32_16x16x32_bf16 v[30:33], v[150:153], v[204:207], v[30:33]
	v_mfma_f32_16x16x32_bf16 v[22:25], v[158:161], v[204:207], v[22:25]
	v_mfma_f32_16x16x32_bf16 v[14:17], v[150:153], v[212:215], v[14:17]
	v_mfma_f32_16x16x32_bf16 v[6:9], v[158:161], v[212:215], v[6:9]
	v_mfma_f32_16x16x32_bf16 v[58:61], v[162:165], v[184:187], v[58:61]
	v_mfma_f32_16x16x32_bf16 v[50:53], v[170:173], v[184:187], v[50:53]
	v_mfma_f32_16x16x32_bf16 v[42:45], v[162:165], v[192:195], v[42:45]
	v_mfma_f32_16x16x32_bf16 v[34:37], v[170:173], v[192:195], v[34:37]
	v_mfma_f32_16x16x32_bf16 v[26:29], v[162:165], v[200:203], v[26:29]
	v_mfma_f32_16x16x32_bf16 v[18:21], v[170:173], v[200:203], v[18:21]
	v_mfma_f32_16x16x32_bf16 v[10:13], v[162:165], v[208:211], v[10:13]
	v_mfma_f32_16x16x32_bf16 v[2:5], v[170:173], v[208:211], v[2:5]
	v_mfma_f32_16x16x32_bf16 v[58:61], v[166:169], v[188:191], v[58:61]
	v_mfma_f32_16x16x32_bf16 v[50:53], v[180:183], v[188:191], v[50:53]
	v_mfma_f32_16x16x32_bf16 v[42:45], v[166:169], v[196:199], v[42:45]
	v_mfma_f32_16x16x32_bf16 v[34:37], v[180:183], v[196:199], v[34:37]
	v_mfma_f32_16x16x32_bf16 v[26:29], v[166:169], v[204:207], v[26:29]
	v_mfma_f32_16x16x32_bf16 v[18:21], v[180:183], v[204:207], v[18:21]
	v_mfma_f32_16x16x32_bf16 v[10:13], v[166:169], v[212:215], v[10:13]
	v_mfma_f32_16x16x32_bf16 v[2:5], v[180:183], v[212:215], v[2:5]
	s_barrier
	s_setprio 0
	s_add_i32 s54, 0, 0x18000
	s_add_i32 s55, 0, 0x1c000
	v_add_u32_e32 v158, s54, v143
	v_add_u32_e32 v180, s55, v143
	ds_read_b128 v[146:149], v158
	ds_read_b128 v[150:153], v158 offset:1024
	ds_read_b128 v[154:157], v158 offset:2048
	ds_read_b128 v[158:161], v158 offset:3072
	ds_read_b128 v[162:165], v180
	ds_read_b128 v[166:169], v180 offset:1024
	ds_read_b128 v[170:173], v180 offset:2048
	ds_read_b128 v[180:183], v180 offset:3072
	s_add_u32 s18, s34, 0x84000
	s_addc_u32 s19, s35, 0
	s_mov_b32 m0, s46
	v_lshl_add_u64 v[220:221], s[18:19], 0, v[134:135]
	ds_read_b128 v[184:187], v145 offset:32768
	ds_read_b128 v[188:191], v145 offset:33792
	ds_read_b128 v[192:195], v145 offset:34816
	ds_read_b128 v[196:199], v145 offset:35840
	ds_read_b128 v[200:203], v145 offset:36864
	ds_read_b128 v[204:207], v145 offset:37888
	ds_read_b128 v[208:211], v145 offset:38912
	ds_read_b128 v[212:215], v145 offset:39936
	global_load_lds_dwordx4 v[220:221], off
	v_lshl_add_u64 v[220:221], s[18:19], 0, v[132:133]
	s_mov_b32 m0, s47
	s_nop 0
	global_load_lds_dwordx4 v[220:221], off
	s_waitcnt vmcnt(8)
	s_waitcnt lgkmcnt(0)
	s_setprio 1
	s_barrier
	v_mfma_f32_16x16x32_bf16 v[126:129], v[146:149], v[184:187], v[126:129]
	v_mfma_f32_16x16x32_bf16 v[118:121], v[154:157], v[184:187], v[118:121]
	v_mfma_f32_16x16x32_bf16 v[110:113], v[146:149], v[192:195], v[110:113]
	v_mfma_f32_16x16x32_bf16 v[102:105], v[154:157], v[192:195], v[102:105]
	v_mfma_f32_16x16x32_bf16 v[94:97], v[146:149], v[200:203], v[94:97]
	v_mfma_f32_16x16x32_bf16 v[86:89], v[154:157], v[200:203], v[86:89]
	v_mfma_f32_16x16x32_bf16 v[78:81], v[146:149], v[208:211], v[78:81]
	v_mfma_f32_16x16x32_bf16 v[70:73], v[154:157], v[208:211], v[70:73]
	v_mfma_f32_16x16x32_bf16 v[126:129], v[150:153], v[188:191], v[126:129]
	v_mfma_f32_16x16x32_bf16 v[118:121], v[158:161], v[188:191], v[118:121]
	v_mfma_f32_16x16x32_bf16 v[110:113], v[150:153], v[196:199], v[110:113]
	v_mfma_f32_16x16x32_bf16 v[102:105], v[158:161], v[196:199], v[102:105]
	v_mfma_f32_16x16x32_bf16 v[94:97], v[150:153], v[204:207], v[94:97]
	v_mfma_f32_16x16x32_bf16 v[86:89], v[158:161], v[204:207], v[86:89]
	v_mfma_f32_16x16x32_bf16 v[78:81], v[150:153], v[212:215], v[78:81]
	v_mfma_f32_16x16x32_bf16 v[70:73], v[158:161], v[212:215], v[70:73]
	v_mfma_f32_16x16x32_bf16 v[122:125], v[162:165], v[184:187], v[122:125]
	v_mfma_f32_16x16x32_bf16 v[114:117], v[170:173], v[184:187], v[114:117]
	v_mfma_f32_16x16x32_bf16 v[106:109], v[162:165], v[192:195], v[106:109]
	v_mfma_f32_16x16x32_bf16 v[98:101], v[170:173], v[192:195], v[98:101]
	v_mfma_f32_16x16x32_bf16 v[90:93], v[162:165], v[200:203], v[90:93]
	v_mfma_f32_16x16x32_bf16 v[82:85], v[170:173], v[200:203], v[82:85]
	v_mfma_f32_16x16x32_bf16 v[74:77], v[162:165], v[208:211], v[74:77]
	v_mfma_f32_16x16x32_bf16 v[66:69], v[170:173], v[208:211], v[66:69]
	v_mfma_f32_16x16x32_bf16 v[122:125], v[166:169], v[188:191], v[122:125]
	v_mfma_f32_16x16x32_bf16 v[114:117], v[180:183], v[188:191], v[114:117]
	v_mfma_f32_16x16x32_bf16 v[106:109], v[166:169], v[196:199], v[106:109]
	v_mfma_f32_16x16x32_bf16 v[98:101], v[180:183], v[196:199], v[98:101]
	v_mfma_f32_16x16x32_bf16 v[90:93], v[166:169], v[204:207], v[90:93]
	v_mfma_f32_16x16x32_bf16 v[82:85], v[180:183], v[204:207], v[82:85]
	v_mfma_f32_16x16x32_bf16 v[74:77], v[166:169], v[212:215], v[74:77]
	v_mfma_f32_16x16x32_bf16 v[66:69], v[180:183], v[212:215], v[66:69]
	s_barrier
; #define PG8_STAGE(bufoff, gbase, voff) do { _Pragma("unroll") for (int _i = 0; _i < 2; ++_i) \
;         __builtin_amdgcn_global_load_lds((const unsigned*)((const char*)(gbase) + (voff)[_i]), (LAS unsigned*)(lds + (bufoff) + ldsw + _i * 8192), 16, 0, 0); } while (0)
; #define PG8_LDA(dst, b, h) do { _Pragma("unroll") for (int m = 0; m < 4; ++m) _Pragma("unroll") for (int k = 0; k < 2; ++k) dst[m][k] = *(const LAS bf16x8*)(lds + PG8_SA(b, h) + aoff + m * 2048 + k * 1024); } while (0)
; #define PG8_MMA(ai, bj, At, Bt) do { __builtin_amdgcn_s_setprio(1); _Pragma("unroll") for (int m = 0; m < 4; ++m) _Pragma("unroll") for (int n = 0; n < 2; ++n) _Pragma("unroll") for (int k = 0; k < 2; ++k) \
;         acc[ai][bj][m][n] = __builtin_amdgcn_mfma_f32_16x16x32_bf16(Bt[n][k], At[m][k], acc[ai][bj][m][n], 0, 0, 0); __builtin_amdgcn_s_setprio(0); } while (0)
; #define PG8_WAIT_V(n) asm volatile("s_waitcnt vmcnt(" #n ")" ::: "memory")
; #define PG8_WAIT_L(n) asm volatile("s_waitcnt lgkmcnt(" #n ")" ::: "memory")
; #define PG8_BAR __builtin_amdgcn_s_barrier()
; #define PG8_SCHED __builtin_amdgcn_sched_barrier(0)
; template <class Epi, class Sched, int LDA, int LDB, bool ALIGN_EPI = true>
; __device__ __forceinline__ void gemm_phase(LAS unsigned char* lds, const Gemm g, const Sched& S, const Epi& E, int wave) {
;     ...
;             PG8_LDA(At, 1, 1); PG8_STAGE(PG8_SB(1, 0), b3, voffB); PG8_STAGE(PG8_SB(1, 1), b3 + hstepB, voffB); PG8_STAGE(PG8_SA(1, 0), a3, voffA);
;             PG8_WAIT_V(8); PG8_WAIT_L(0); PG8_BAR; PG8_MMA(1, 0, At, B0); PG8_MMA(1, 1, At, B1); PG8_BAR; PG8_SCHED;
;         }
;         if constexpr (ALIGN_EPI) { if (wr == 0) PG8_BAR; }
	s_setprio 0
	s_add_i32 s18, s54, s5
	v_lshl_add_u64 v[140:141], v[140:141], 0, s[6:7]
	s_mov_b32 m0, s18
	ds_read_b128 v[184:187], v145 offset:49152
	ds_read_b128 v[188:191], v145 offset:50176
	ds_read_b128 v[192:195], v145 offset:51200
	ds_read_b128 v[196:199], v145 offset:52224
	ds_read_b128 v[200:203], v145 offset:53248
	ds_read_b128 v[204:207], v145 offset:54272
	ds_read_b128 v[208:211], v145 offset:55296
	ds_read_b128 v[212:215], v145 offset:56320
	global_load_lds_dwordx4 v[140:141], off
	s_add_i32 m0, s18, 0x2000
	s_add_u32 s18, s28, 0x80080
	v_lshl_add_u64 v[140:141], v[174:175], 0, s[6:7]
	s_addc_u32 s19, s29, 0
	s_add_i32 s28, s55, s5
	global_load_lds_dwordx4 v[140:141], off
	v_lshl_add_u64 v[140:141], s[18:19], 0, v[0:1]
	s_mov_b32 m0, s28
	s_nop 0
	global_load_lds_dwordx4 v[140:141], off
	v_lshl_add_u64 v[140:141], s[18:19], 0, v[130:131]
	s_add_i32 m0, s28, 0x2000
	s_nop 0
	global_load_lds_dwordx4 v[140:141], off
	v_lshl_add_u64 v[140:141], v[216:217], 0, s[6:7]
	s_mov_b32 m0, s48
	s_nop 0
	global_load_lds_dwordx4 v[140:141], off
	v_lshl_add_u64 v[140:141], v[218:219], 0, s[6:7]
	s_mov_b32 m0, s49
	s_nop 0
	global_load_lds_dwordx4 v[140:141], off
	s_waitcnt vmcnt(8)
	s_waitcnt lgkmcnt(0)
	s_setprio 1
	s_barrier
	v_mfma_f32_16x16x32_bf16 v[62:65], v[146:149], v[184:187], v[62:65]
	v_mfma_f32_16x16x32_bf16 v[54:57], v[154:157], v[184:187], v[54:57]
	v_mfma_f32_16x16x32_bf16 v[46:49], v[146:149], v[192:195], v[46:49]
	v_mfma_f32_16x16x32_bf16 v[38:41], v[154:157], v[192:195], v[38:41]
	v_mfma_f32_16x16x32_bf16 v[30:33], v[146:149], v[200:203], v[30:33]
	v_mfma_f32_16x16x32_bf16 v[22:25], v[154:157], v[200:203], v[22:25]
	v_mfma_f32_16x16x32_bf16 v[14:17], v[146:149], v[208:211], v[14:17]
	v_mfma_f32_16x16x32_bf16 v[6:9], v[154:157], v[208:211], v[6:9]
	v_mfma_f32_16x16x32_bf16 v[62:65], v[150:153], v[188:191], v[62:65]
	v_mfma_f32_16x16x32_bf16 v[54:57], v[158:161], v[188:191], v[54:57]
	v_mfma_f32_16x16x32_bf16 v[46:49], v[150:153], v[196:199], v[46:49]
	v_mfma_f32_16x16x32_bf16 v[38:41], v[158:161], v[196:199], v[38:41]
	v_mfma_f32_16x16x32_bf16 v[30:33], v[150:153], v[204:207], v[30:33]
	v_mfma_f32_16x16x32_bf16 v[22:25], v[158:161], v[204:207], v[22:25]
	v_mfma_f32_16x16x32_bf16 v[14:17], v[150:153], v[212:215], v[14:17]
	v_mfma_f32_16x16x32_bf16 v[6:9], v[158:161], v[212:215], v[6:9]
	v_mfma_f32_16x16x32_bf16 v[58:61], v[162:165], v[184:187], v[58:61]
	v_mfma_f32_16x16x32_bf16 v[50:53], v[170:173], v[184:187], v[50:53]
	v_mfma_f32_16x16x32_bf16 v[42:45], v[162:165], v[192:195], v[42:45]
	v_mfma_f32_16x16x32_bf16 v[34:37], v[170:173], v[192:195], v[34:37]
	v_mfma_f32_16x16x32_bf16 v[26:29], v[162:165], v[200:203], v[26:29]
	v_mfma_f32_16x16x32_bf16 v[18:21], v[170:173], v[200:203], v[18:21]
	v_mfma_f32_16x16x32_bf16 v[10:13], v[162:165], v[208:211], v[10:13]
	v_mfma_f32_16x16x32_bf16 v[2:5], v[170:173], v[208:211], v[2:5]
	v_mfma_f32_16x16x32_bf16 v[58:61], v[166:169], v[188:191], v[58:61]
	v_mfma_f32_16x16x32_bf16 v[50:53], v[180:183], v[188:191], v[50:53]
	v_mfma_f32_16x16x32_bf16 v[42:45], v[166:169], v[196:199], v[42:45]
	v_mfma_f32_16x16x32_bf16 v[34:37], v[180:183], v[196:199], v[34:37]
	v_mfma_f32_16x16x32_bf16 v[26:29], v[166:169], v[204:207], v[26:29]
	v_mfma_f32_16x16x32_bf16 v[18:21], v[180:183], v[204:207], v[18:21]
	v_mfma_f32_16x16x32_bf16 v[10:13], v[166:169], v[212:215], v[10:13]
	v_mfma_f32_16x16x32_bf16 v[2:5], v[180:183], v[212:215], v[2:5]
	s_barrier
	s_setprio 0
	s_add_i32 s53, s53, 2
	s_add_u32 s44, s44, 0x100
	s_addc_u32 s45, s45, 0
	s_cmp_gt_u32 s53, 29
	s_mov_b64 s[18:19], s[24:25]
	s_cbranch_scc0 .LBB0_485
	v_readlane_b32 s6, v252, 14
	v_readlane_b32 s7, v252, 15
	s_and_b64 vcc, exec, s[6:7]
	s_cbranch_vccz .LBB0_488
	s_barrier

; #define PG8_STAGE(bufoff, gbase, voff) do { _Pragma("unroll") for (int _i = 0; _i < 2; ++_i) \
;         __builtin_amdgcn_global_load_lds((const unsigned*)((const char*)(gbase) + (voff)[_i]), (LAS unsigned*)(lds + (bufoff) + ldsw + _i * 8192), 16, 0, 0); } while (0)
; #define PG8_LDA(dst, b, h) do { _Pragma("unroll") for (int m = 0; m < 4; ++m) _Pragma("unroll") for (int k = 0; k < 2; ++k) dst[m][k] = *(const LAS bf16x8*)(lds + PG8_SA(b, h) + aoff + m * 2048 + k * 1024); } while (0)
; #define PG8_LDB(dst, b, h) do { _Pragma("unroll") for (int n = 0; n < 2; ++n) _Pragma("unroll") for (int k = 0; k < 2; ++k) dst[n][k] = *(const LAS bf16x8*)(lds + PG8_SB(b, h) + boff + n * 2048 + k * 1024); } while (0)
; #define PG8_MMA(ai, bj, At, Bt) do { __builtin_amdgcn_s_setprio(1); _Pragma("unroll") for (int m = 0; m < 4; ++m) _Pragma("unroll") for (int n = 0; n < 2; ++n) _Pragma("unroll") for (int k = 0; k < 2; ++k) \
;         acc[ai][bj][m][n] = __builtin_amdgcn_mfma_f32_16x16x32_bf16(Bt[n][k], At[m][k], acc[ai][bj][m][n], 0, 0, 0); __builtin_amdgcn_s_setprio(0); } while (0)
; #define PG8_WAIT_V(n) asm volatile("s_waitcnt vmcnt(" #n ")" ::: "memory")
; #define PG8_WAIT_L(n) asm volatile("s_waitcnt lgkmcnt(" #n ")" ::: "memory")
; #define PG8_BAR __builtin_amdgcn_s_barrier()
; template <class Epi, class Sched, int LDA, int LDB, bool ALIGN_EPI = true>
; __device__ __forceinline__ void gemm_phase(LAS unsigned char* lds, const Gemm g, const Sched& S, const Epi& E, int wave) {
;     ...
;         for (int t = 0; t < nt; t += 2) {
;             const bool last = (t == nt - 2);
;             const char* a1 = cA + (size_t)(t + 1) * kstep;
;             const char* a2 = last ? nA : cA + (size_t)(t + 2) * kstep; const char* b2 = last ? nB : cB + (size_t)(t + 2) * kstep;
;             const char* a3 = a2 + kstep; const char* b3 = b2 + kstep;
;             PG8_LDB(B0, 0, 0); PG8_LDB(B1, 0, 1); PG8_SCHED; PG8_LDA(At, 0, 0); PG8_STAGE(PG8_SA(1, 1), a1 + hstepA, voffA);
;             PG8_WAIT_V(8); PG8_WAIT_L(0); PG8_BAR; PG8_MMA(0, 0, At, B0); PG8_MMA(0, 1, At, B1); PG8_BAR; PG8_SCHED;
;             PG8_LDA(At, 0, 1); PG8_STAGE(PG8_SB(0, 0), b2, voffB); PG8_STAGE(PG8_SB(0, 1), b2 + hstepB, voffB); PG8_STAGE(PG8_SA(0, 0), a2, voffA);
;             PG8_WAIT_V(8); PG8_WAIT_L(0); PG8_BAR; PG8_MMA(1, 0, At, B0); PG8_MMA(1, 1, At, B1); PG8_BAR; PG8_SCHED;
.LBB0_1893:
	s_add_i32 s79, s46, 2
	s_add_u32 s38, s36, 0x100
	s_addc_u32 s39, s37, 0
	s_add_i32 s82, 0, 0x10000
	s_cmp_eq_u32 s25, s46
	s_cselect_b32 s49, s29, s39
	s_cselect_b32 s48, s28, s38
	s_cselect_b32 s47, s35, s78
	s_cselect_b32 s46, s34, s77
	s_add_i32 s85, 0, 0x14000
	v_add_u32_e32 v152, s82, v249
	v_add_u32_e32 v168, s85, v249
	ds_read_b128 v[130:133], v152
	ds_read_b128 v[134:137], v152 offset:1024
	ds_read_b128 v[148:151], v152 offset:2048
	ds_read_b128 v[152:155], v152 offset:3072
	ds_read_b128 v[156:159], v168
	ds_read_b128 v[160:163], v168 offset:1024
	ds_read_b128 v[164:167], v168 offset:2048
	ds_read_b128 v[168:171], v168 offset:3072
	v_lshl_add_u64 v[208:209], s[36:37], 0, v[144:145]
	s_add_i32 m0, s50, 0xc000
	ds_read_b128 v[172:175], v236
	ds_read_b128 v[180:183], v236 offset:1024
	ds_read_b128 v[184:187], v236 offset:2048
	ds_read_b128 v[188:191], v236 offset:3072
	ds_read_b128 v[192:195], v236 offset:4096
	ds_read_b128 v[196:199], v236 offset:5120
	ds_read_b128 v[200:203], v236 offset:6144
	ds_read_b128 v[204:207], v236 offset:7168
	global_load_lds_dwordx4 v[208:209], off
	v_lshl_add_u64 v[208:209], s[36:37], 0, v[146:147]
	s_add_i32 m0, s50, 0xe000
	s_nop 0
	global_load_lds_dwordx4 v[208:209], off
	s_waitcnt vmcnt(8)
	s_waitcnt lgkmcnt(0)
	s_setprio 1
	s_barrier
	v_mfma_f32_16x16x32_bf16 v[126:129], v[130:133], v[172:175], v[126:129]
	v_mfma_f32_16x16x32_bf16 v[122:125], v[148:151], v[172:175], v[122:125]
	v_mfma_f32_16x16x32_bf16 v[110:113], v[130:133], v[184:187], v[110:113]
	v_mfma_f32_16x16x32_bf16 v[106:109], v[148:151], v[184:187], v[106:109]
	v_mfma_f32_16x16x32_bf16 v[94:97], v[130:133], v[192:195], v[94:97]
	v_mfma_f32_16x16x32_bf16 v[90:93], v[148:151], v[192:195], v[90:93]
	v_mfma_f32_16x16x32_bf16 v[78:81], v[130:133], v[200:203], v[78:81]
	v_mfma_f32_16x16x32_bf16 v[74:77], v[148:151], v[200:203], v[74:77]
	v_mfma_f32_16x16x32_bf16 v[126:129], v[134:137], v[180:183], v[126:129]
	v_mfma_f32_16x16x32_bf16 v[122:125], v[152:155], v[180:183], v[122:125]
	v_mfma_f32_16x16x32_bf16 v[110:113], v[134:137], v[188:191], v[110:113]
	v_mfma_f32_16x16x32_bf16 v[106:109], v[152:155], v[188:191], v[106:109]
	v_mfma_f32_16x16x32_bf16 v[94:97], v[134:137], v[196:199], v[94:97]
	v_mfma_f32_16x16x32_bf16 v[90:93], v[152:155], v[196:199], v[90:93]
	v_mfma_f32_16x16x32_bf16 v[78:81], v[134:137], v[204:207], v[78:81]
	v_mfma_f32_16x16x32_bf16 v[74:77], v[152:155], v[204:207], v[74:77]
	v_mfma_f32_16x16x32_bf16 v[118:121], v[156:159], v[172:175], v[118:121]
	v_mfma_f32_16x16x32_bf16 v[114:117], v[164:167], v[172:175], v[114:117]
	v_mfma_f32_16x16x32_bf16 v[102:105], v[156:159], v[184:187], v[102:105]
	v_mfma_f32_16x16x32_bf16 v[98:101], v[164:167], v[184:187], v[98:101]
	v_mfma_f32_16x16x32_bf16 v[86:89], v[156:159], v[192:195], v[86:89]
	v_mfma_f32_16x16x32_bf16 v[82:85], v[164:167], v[192:195], v[82:85]
	v_mfma_f32_16x16x32_bf16 v[70:73], v[156:159], v[200:203], v[70:73]
	v_mfma_f32_16x16x32_bf16 v[66:69], v[164:167], v[200:203], v[66:69]
	v_mfma_f32_16x16x32_bf16 v[118:121], v[160:163], v[180:183], v[118:121]
	v_mfma_f32_16x16x32_bf16 v[114:117], v[168:171], v[180:183], v[114:117]
	v_mfma_f32_16x16x32_bf16 v[102:105], v[160:163], v[188:191], v[102:105]
	v_mfma_f32_16x16x32_bf16 v[98:101], v[168:171], v[188:191], v[98:101]
	v_mfma_f32_16x16x32_bf16 v[86:89], v[160:163], v[196:199], v[86:89]
	v_mfma_f32_16x16x32_bf16 v[82:85], v[168:171], v[196:199], v[82:85]
	v_mfma_f32_16x16x32_bf16 v[70:73], v[160:163], v[204:207], v[70:73]
	v_mfma_f32_16x16x32_bf16 v[66:69], v[168:171], v[204:207], v[66:69]
	s_barrier
	s_setprio 0
	s_add_i32 s36, s82, s2
	v_lshl_add_u64 v[208:209], s[46:47], 0, v[0:1]
	s_mov_b32 m0, s36
	ds_read_b128 v[172:175], v236 offset:16384
	ds_read_b128 v[180:183], v236 offset:17408
	ds_read_b128 v[184:187], v236 offset:18432
	ds_read_b128 v[188:191], v236 offset:19456
	ds_read_b128 v[192:195], v236 offset:20480
	ds_read_b128 v[196:199], v236 offset:21504
	ds_read_b128 v[200:203], v236 offset:22528
	ds_read_b128 v[204:207], v236 offset:23552
	global_load_lds_dwordx4 v[208:209], off
	s_add_i32 m0, s36, 0x2000
	s_add_u32 s36, s46, 0x160000
	v_lshl_add_u64 v[210:211], s[46:47], 0, v[142:143]
	s_addc_u32 s37, s47, 0
	s_add_i32 s82, s85, s2
	global_load_lds_dwordx4 v[210:211], off
	v_lshl_add_u64 v[212:213], s[36:37], 0, v[0:1]
	s_mov_b32 m0, s82
	v_lshl_add_u64 v[214:215], s[48:49], 0, v[140:141]
	global_load_lds_dwordx4 v[212:213], off
	v_lshl_add_u64 v[212:213], s[36:37], 0, v[142:143]
	s_add_i32 m0, s82, 0x2000
	s_nop 0
	global_load_lds_dwordx4 v[212:213], off
	v_lshl_add_u64 v[212:213], s[48:49], 0, v[138:139]
	s_mov_b32 m0, s50
	s_nop 0
	global_load_lds_dwordx4 v[212:213], off
	s_mov_b32 m0, s51
	s_nop 0
	global_load_lds_dwordx4 v[214:215], off
	s_waitcnt vmcnt(8)
	s_waitcnt lgkmcnt(0)
	s_setprio 1
	s_barrier
; #define PG8_STAGE(bufoff, gbase, voff) do { _Pragma("unroll") for (int _i = 0; _i < 2; ++_i) \
;         __builtin_amdgcn_global_load_lds((const unsigned*)((const char*)(gbase) + (voff)[_i]), (LAS unsigned*)(lds + (bufoff) + ldsw + _i * 8192), 16, 0, 0); } while (0)
; #define PG8_LDA(dst, b, h) do { _Pragma("unroll") for (int m = 0; m < 4; ++m) _Pragma("unroll") for (int k = 0; k < 2; ++k) dst[m][k] = *(const LAS bf16x8*)(lds + PG8_SA(b, h) + aoff + m * 2048 + k * 1024); } while (0)
; #define PG8_LDB(dst, b, h) do { _Pragma("unroll") for (int n = 0; n < 2; ++n) _Pragma("unroll") for (int k = 0; k < 2; ++k) dst[n][k] = *(const LAS bf16x8*)(lds + PG8_SB(b, h) + boff + n * 2048 + k * 1024); } while (0)
; #define PG8_MMA(ai, bj, At, Bt) do { __builtin_amdgcn_s_setprio(1); _Pragma("unroll") for (int m = 0; m < 4; ++m) _Pragma("unroll") for (int n = 0; n < 2; ++n) _Pragma("unroll") for (int k = 0; k < 2; ++k) \
;         acc[ai][bj][m][n] = __builtin_amdgcn_mfma_f32_16x16x32_bf16(Bt[n][k], At[m][k], acc[ai][bj][m][n], 0, 0, 0); __builtin_amdgcn_s_setprio(0); } while (0)
; #define PG8_WAIT_V(n) asm volatile("s_waitcnt vmcnt(" #n ")" ::: "memory")
; #define PG8_WAIT_L(n) asm volatile("s_waitcnt lgkmcnt(" #n ")" ::: "memory")
; #define PG8_BAR __builtin_amdgcn_s_barrier()
; #define PG8_SCHED __builtin_amdgcn_sched_barrier(0)
; template <class Epi, class Sched, int LDA, int LDB, bool ALIGN_EPI = true>
; __device__ __forceinline__ void gemm_phase(LAS unsigned char* lds, const Gemm g, const Sched& S, const Epi& E, int wave) {
;     ...
;             PG8_WAIT_V(8); PG8_WAIT_L(0); PG8_BAR; PG8_MMA(1, 0, At, B0); PG8_MMA(1, 1, At, B1); PG8_BAR; PG8_SCHED;
;             PG8_LDB(B0, 1, 0); PG8_LDB(B1, 1, 1); PG8_SCHED; PG8_LDA(At, 1, 0); PG8_STAGE(PG8_SA(0, 1), a2 + hstepA, voffA);
;             PG8_WAIT_V(8); PG8_WAIT_L(0); PG8_BAR; PG8_MMA(0, 0, At, B0); PG8_MMA(0, 1, At, B1); PG8_BAR; PG8_SCHED;
	v_mfma_f32_16x16x32_bf16 v[62:65], v[130:133], v[172:175], v[62:65]
	v_mfma_f32_16x16x32_bf16 v[58:61], v[148:151], v[172:175], v[58:61]
	v_mfma_f32_16x16x32_bf16 v[46:49], v[130:133], v[184:187], v[46:49]
	v_mfma_f32_16x16x32_bf16 v[42:45], v[148:151], v[184:187], v[42:45]
	v_mfma_f32_16x16x32_bf16 v[30:33], v[130:133], v[192:195], v[30:33]
	v_mfma_f32_16x16x32_bf16 v[26:29], v[148:151], v[192:195], v[26:29]
	v_mfma_f32_16x16x32_bf16 v[14:17], v[130:133], v[200:203], v[14:17]
	v_mfma_f32_16x16x32_bf16 v[10:13], v[148:151], v[200:203], v[10:13]
	v_mfma_f32_16x16x32_bf16 v[62:65], v[134:137], v[180:183], v[62:65]
	v_mfma_f32_16x16x32_bf16 v[58:61], v[152:155], v[180:183], v[58:61]
	v_mfma_f32_16x16x32_bf16 v[46:49], v[134:137], v[188:191], v[46:49]
	v_mfma_f32_16x16x32_bf16 v[42:45], v[152:155], v[188:191], v[42:45]
	v_mfma_f32_16x16x32_bf16 v[30:33], v[134:137], v[196:199], v[30:33]
	v_mfma_f32_16x16x32_bf16 v[26:29], v[152:155], v[196:199], v[26:29]
	v_mfma_f32_16x16x32_bf16 v[14:17], v[134:137], v[204:207], v[14:17]
	v_mfma_f32_16x16x32_bf16 v[10:13], v[152:155], v[204:207], v[10:13]
	v_mfma_f32_16x16x32_bf16 v[54:57], v[156:159], v[172:175], v[54:57]
	v_mfma_f32_16x16x32_bf16 v[50:53], v[164:167], v[172:175], v[50:53]
	v_mfma_f32_16x16x32_bf16 v[38:41], v[156:159], v[184:187], v[38:41]
	v_mfma_f32_16x16x32_bf16 v[34:37], v[164:167], v[184:187], v[34:37]
	v_mfma_f32_16x16x32_bf16 v[22:25], v[156:159], v[192:195], v[22:25]
	v_mfma_f32_16x16x32_bf16 v[18:21], v[164:167], v[192:195], v[18:21]
	v_mfma_f32_16x16x32_bf16 v[6:9], v[156:159], v[200:203], v[6:9]
	v_mfma_f32_16x16x32_bf16 v[2:5], v[164:167], v[200:203], v[2:5]
	v_mfma_f32_16x16x32_bf16 v[54:57], v[160:163], v[180:183], v[54:57]
	v_mfma_f32_16x16x32_bf16 v[50:53], v[168:171], v[180:183], v[50:53]
	v_mfma_f32_16x16x32_bf16 v[38:41], v[160:163], v[188:191], v[38:41]
	v_mfma_f32_16x16x32_bf16 v[34:37], v[168:171], v[188:191], v[34:37]
	v_mfma_f32_16x16x32_bf16 v[22:25], v[160:163], v[196:199], v[22:25]
	v_mfma_f32_16x16x32_bf16 v[18:21], v[168:171], v[196:199], v[18:21]
	v_mfma_f32_16x16x32_bf16 v[6:9], v[160:163], v[204:207], v[6:9]
	v_mfma_f32_16x16x32_bf16 v[2:5], v[168:171], v[204:207], v[2:5]
	s_barrier
	s_setprio 0
	s_add_i32 s82, 0, 0x18000
	s_add_i32 s85, 0, 0x1c000
	v_add_u32_e32 v152, s82, v249
	v_add_u32_e32 v168, s85, v249
	ds_read_b128 v[130:133], v152
	ds_read_b128 v[134:137], v152 offset:1024
	ds_read_b128 v[148:151], v152 offset:2048
	ds_read_b128 v[152:155], v152 offset:3072
	ds_read_b128 v[156:159], v168
	ds_read_b128 v[160:163], v168 offset:1024
	ds_read_b128 v[164:167], v168 offset:2048
	ds_read_b128 v[168:171], v168 offset:3072
	s_add_u32 s36, s48, 0x160000
	s_addc_u32 s37, s49, 0
	s_mov_b32 m0, s52
	v_lshl_add_u64 v[216:217], s[36:37], 0, v[138:139]
	ds_read_b128 v[172:175], v236 offset:32768
	ds_read_b128 v[180:183], v236 offset:33792
	ds_read_b128 v[184:187], v236 offset:34816
	ds_read_b128 v[188:191], v236 offset:35840
	ds_read_b128 v[192:195], v236 offset:36864
	ds_read_b128 v[196:199], v236 offset:37888
	ds_read_b128 v[200:203], v236 offset:38912
	ds_read_b128 v[204:207], v236 offset:39936
	global_load_lds_dwordx4 v[216:217], off
	v_lshl_add_u64 v[216:217], s[36:37], 0, v[140:141]
	s_mov_b32 m0, s53
	s_nop 0
	global_load_lds_dwordx4 v[216:217], off
	s_waitcnt vmcnt(8)
	s_waitcnt lgkmcnt(0)
	s_setprio 1
	s_barrier
	v_mfma_f32_16x16x32_bf16 v[126:129], v[130:133], v[172:175], v[126:129]
	v_mfma_f32_16x16x32_bf16 v[122:125], v[148:151], v[172:175], v[122:125]
	v_mfma_f32_16x16x32_bf16 v[110:113], v[130:133], v[184:187], v[110:113]
	v_mfma_f32_16x16x32_bf16 v[106:109], v[148:151], v[184:187], v[106:109]
	v_mfma_f32_16x16x32_bf16 v[94:97], v[130:133], v[192:195], v[94:97]
	v_mfma_f32_16x16x32_bf16 v[90:93], v[148:151], v[192:195], v[90:93]
	v_mfma_f32_16x16x32_bf16 v[78:81], v[130:133], v[200:203], v[78:81]
	v_mfma_f32_16x16x32_bf16 v[74:77], v[148:151], v[200:203], v[74:77]
	v_mfma_f32_16x16x32_bf16 v[126:129], v[134:137], v[180:183], v[126:129]
	v_mfma_f32_16x16x32_bf16 v[122:125], v[152:155], v[180:183], v[122:125]
	v_mfma_f32_16x16x32_bf16 v[110:113], v[134:137], v[188:191], v[110:113]
	v_mfma_f32_16x16x32_bf16 v[106:109], v[152:155], v[188:191], v[106:109]
	v_mfma_f32_16x16x32_bf16 v[94:97], v[134:137], v[196:199], v[94:97]
	v_mfma_f32_16x16x32_bf16 v[90:93], v[152:155], v[196:199], v[90:93]
	v_mfma_f32_16x16x32_bf16 v[78:81], v[134:137], v[204:207], v[78:81]
	v_mfma_f32_16x16x32_bf16 v[74:77], v[152:155], v[204:207], v[74:77]
	v_mfma_f32_16x16x32_bf16 v[118:121], v[156:159], v[172:175], v[118:121]
	v_mfma_f32_16x16x32_bf16 v[114:117], v[164:167], v[172:175], v[114:117]
	v_mfma_f32_16x16x32_bf16 v[102:105], v[156:159], v[184:187], v[102:105]
	v_mfma_f32_16x16x32_bf16 v[98:101], v[164:167], v[184:187], v[98:101]
	v_mfma_f32_16x16x32_bf16 v[86:89], v[156:159], v[192:195], v[86:89]
	v_mfma_f32_16x16x32_bf16 v[82:85], v[164:167], v[192:195], v[82:85]
	v_mfma_f32_16x16x32_bf16 v[70:73], v[156:159], v[200:203], v[70:73]
	v_mfma_f32_16x16x32_bf16 v[66:69], v[164:167], v[200:203], v[66:69]
	v_mfma_f32_16x16x32_bf16 v[118:121], v[160:163], v[180:183], v[118:121]
	v_mfma_f32_16x16x32_bf16 v[114:117], v[168:171], v[180:183], v[114:117]
	v_mfma_f32_16x16x32_bf16 v[102:105], v[160:163], v[188:191], v[102:105]
	v_mfma_f32_16x16x32_bf16 v[98:101], v[168:171], v[188:191], v[98:101]
	v_mfma_f32_16x16x32_bf16 v[86:89], v[160:163], v[196:199], v[86:89]
	v_mfma_f32_16x16x32_bf16 v[82:85], v[168:171], v[196:199], v[82:85]
	v_mfma_f32_16x16x32_bf16 v[70:73], v[160:163], v[204:207], v[70:73]
	v_mfma_f32_16x16x32_bf16 v[66:69], v[168:171], v[204:207], v[66:69]
	s_barrier
; #define PG8_STAGE(bufoff, gbase, voff) do { _Pragma("unroll") for (int _i = 0; _i < 2; ++_i) \
;         __builtin_amdgcn_global_load_lds((const unsigned*)((const char*)(gbase) + (voff)[_i]), (LAS unsigned*)(lds + (bufoff) + ldsw + _i * 8192), 16, 0, 0); } while (0)
; #define PG8_LDA(dst, b, h) do { _Pragma("unroll") for (int m = 0; m < 4; ++m) _Pragma("unroll") for (int k = 0; k < 2; ++k) dst[m][k] = *(const LAS bf16x8*)(lds + PG8_SA(b, h) + aoff + m * 2048 + k * 1024); } while (0)
; #define PG8_MMA(ai, bj, At, Bt) do { __builtin_amdgcn_s_setprio(1); _Pragma("unroll") for (int m = 0; m < 4; ++m) _Pragma("unroll") for (int n = 0; n < 2; ++n) _Pragma("unroll") for (int k = 0; k < 2; ++k) \
;         acc[ai][bj][m][n] = __builtin_amdgcn_mfma_f32_16x16x32_bf16(Bt[n][k], At[m][k], acc[ai][bj][m][n], 0, 0, 0); __builtin_amdgcn_s_setprio(0); } while (0)
; #define PG8_WAIT_V(n) asm volatile("s_waitcnt vmcnt(" #n ")" ::: "memory")
; #define PG8_WAIT_L(n) asm volatile("s_waitcnt lgkmcnt(" #n ")" ::: "memory")
; #define PG8_BAR __builtin_amdgcn_s_barrier()
; #define PG8_SCHED __builtin_amdgcn_sched_barrier(0)
; template <class Epi, class Sched, int LDA, int LDB, bool ALIGN_EPI = true>
; __device__ __forceinline__ void gemm_phase(LAS unsigned char* lds, const Gemm g, const Sched& S, const Epi& E, int wave) {
;     ...
;             PG8_LDA(At, 1, 1); PG8_STAGE(PG8_SB(1, 0), b3, voffB); PG8_STAGE(PG8_SB(1, 1), b3 + hstepB, voffB); PG8_STAGE(PG8_SA(1, 0), a3, voffA);
;             PG8_WAIT_V(8); PG8_WAIT_L(0); PG8_BAR; PG8_MMA(1, 0, At, B0); PG8_MMA(1, 1, At, B1); PG8_BAR; PG8_SCHED;
;         }
;         if constexpr (ALIGN_EPI) { if (wr == 0) PG8_BAR; }
	s_setprio 0
	s_add_i32 s36, s82, s2
	v_lshl_add_u64 v[208:209], v[208:209], 0, s[8:9]
	s_mov_b32 m0, s36
	ds_read_b128 v[172:175], v236 offset:49152
	ds_read_b128 v[180:183], v236 offset:50176
	ds_read_b128 v[184:187], v236 offset:51200
	ds_read_b128 v[188:191], v236 offset:52224
	ds_read_b128 v[192:195], v236 offset:53248
	ds_read_b128 v[196:199], v236 offset:54272
	ds_read_b128 v[200:203], v236 offset:55296
	ds_read_b128 v[204:207], v236 offset:56320
	global_load_lds_dwordx4 v[208:209], off
	s_add_i32 m0, s36, 0x2000
	s_add_u32 s36, s46, 0x160080
	v_lshl_add_u64 v[208:209], v[210:211], 0, s[8:9]
	s_addc_u32 s37, s47, 0
	s_add_i32 s46, s85, s2
	global_load_lds_dwordx4 v[208:209], off
	v_lshl_add_u64 v[208:209], s[36:37], 0, v[0:1]
	s_mov_b32 m0, s46
	s_nop 0
	global_load_lds_dwordx4 v[208:209], off
	v_lshl_add_u64 v[208:209], s[36:37], 0, v[142:143]
	s_add_i32 m0, s46, 0x2000
	s_nop 0
	global_load_lds_dwordx4 v[208:209], off
	v_lshl_add_u64 v[208:209], v[212:213], 0, s[8:9]
	s_mov_b32 m0, s5
	s_nop 0
	global_load_lds_dwordx4 v[208:209], off
	v_lshl_add_u64 v[208:209], v[214:215], 0, s[8:9]
	s_mov_b32 m0, s59
	s_nop 0
	global_load_lds_dwordx4 v[208:209], off
	s_waitcnt vmcnt(8)
	s_waitcnt lgkmcnt(0)
	s_setprio 1
	s_barrier
	v_mfma_f32_16x16x32_bf16 v[62:65], v[130:133], v[172:175], v[62:65]
	v_mfma_f32_16x16x32_bf16 v[58:61], v[148:151], v[172:175], v[58:61]
	v_mfma_f32_16x16x32_bf16 v[46:49], v[130:133], v[184:187], v[46:49]
	v_mfma_f32_16x16x32_bf16 v[42:45], v[148:151], v[184:187], v[42:45]
	v_mfma_f32_16x16x32_bf16 v[30:33], v[130:133], v[192:195], v[30:33]
	v_mfma_f32_16x16x32_bf16 v[26:29], v[148:151], v[192:195], v[26:29]
	v_mfma_f32_16x16x32_bf16 v[14:17], v[130:133], v[200:203], v[14:17]
	v_mfma_f32_16x16x32_bf16 v[10:13], v[148:151], v[200:203], v[10:13]
	v_mfma_f32_16x16x32_bf16 v[62:65], v[134:137], v[180:183], v[62:65]
	v_mfma_f32_16x16x32_bf16 v[58:61], v[152:155], v[180:183], v[58:61]
	v_mfma_f32_16x16x32_bf16 v[46:49], v[134:137], v[188:191], v[46:49]
	v_mfma_f32_16x16x32_bf16 v[42:45], v[152:155], v[188:191], v[42:45]
	v_mfma_f32_16x16x32_bf16 v[30:33], v[134:137], v[196:199], v[30:33]
	v_mfma_f32_16x16x32_bf16 v[26:29], v[152:155], v[196:199], v[26:29]
	v_mfma_f32_16x16x32_bf16 v[14:17], v[134:137], v[204:207], v[14:17]
	v_mfma_f32_16x16x32_bf16 v[10:13], v[152:155], v[204:207], v[10:13]
	v_mfma_f32_16x16x32_bf16 v[54:57], v[156:159], v[172:175], v[54:57]
	v_mfma_f32_16x16x32_bf16 v[50:53], v[164:167], v[172:175], v[50:53]
	v_mfma_f32_16x16x32_bf16 v[38:41], v[156:159], v[184:187], v[38:41]
	v_mfma_f32_16x16x32_bf16 v[34:37], v[164:167], v[184:187], v[34:37]
	v_mfma_f32_16x16x32_bf16 v[22:25], v[156:159], v[192:195], v[22:25]
	v_mfma_f32_16x16x32_bf16 v[18:21], v[164:167], v[192:195], v[18:21]
	v_mfma_f32_16x16x32_bf16 v[6:9], v[156:159], v[200:203], v[6:9]
	v_mfma_f32_16x16x32_bf16 v[2:5], v[164:167], v[200:203], v[2:5]
	v_mfma_f32_16x16x32_bf16 v[54:57], v[160:163], v[180:183], v[54:57]
	v_mfma_f32_16x16x32_bf16 v[50:53], v[168:171], v[180:183], v[50:53]
	v_mfma_f32_16x16x32_bf16 v[38:41], v[160:163], v[188:191], v[38:41]
	v_mfma_f32_16x16x32_bf16 v[34:37], v[168:171], v[188:191], v[34:37]
	v_mfma_f32_16x16x32_bf16 v[22:25], v[160:163], v[196:199], v[22:25]
	v_mfma_f32_16x16x32_bf16 v[18:21], v[168:171], v[196:199], v[18:21]
	v_mfma_f32_16x16x32_bf16 v[6:9], v[160:163], v[204:207], v[6:9]
	v_mfma_f32_16x16x32_bf16 v[2:5], v[168:171], v[204:207], v[2:5]
	s_barrier
	s_setprio 0
	s_add_u32 s77, s77, 0x100
	s_addc_u32 s78, s78, 0
	s_cmp_ge_i32 s79, s75
	s_mov_b64 s[36:37], s[38:39]
	s_mov_b32 s46, s79
	s_cbranch_scc0 .LBB0_1893
	v_readlane_b32 s2, v252, 14
	v_readlane_b32 s3, v252, 15
	s_and_b64 vcc, exec, s[2:3]
	s_cbranch_vccz .LBB0_1896
	s_barrier

; #define PG8_STAGE(bufoff, gbase, voff) do { _Pragma("unroll") for (int _i = 0; _i < 2; ++_i) \
;         __builtin_amdgcn_global_load_lds((const unsigned*)((const char*)(gbase) + (voff)[_i]), (LAS unsigned*)(lds + (bufoff) + ldsw + _i * 8192), 16, 0, 0); } while (0)
; #define PG8_LDA(dst, b, h) do { _Pragma("unroll") for (int m = 0; m < 4; ++m) _Pragma("unroll") for (int k = 0; k < 2; ++k) dst[m][k] = *(const LAS bf16x8*)(lds + PG8_SA(b, h) + aoff + m * 2048 + k * 1024); } while (0)
; #define PG8_LDB(dst, b, h) do { _Pragma("unroll") for (int n = 0; n < 2; ++n) _Pragma("unroll") for (int k = 0; k < 2; ++k) dst[n][k] = *(const LAS bf16x8*)(lds + PG8_SB(b, h) + boff + n * 2048 + k * 1024); } while (0)
; #define PG8_MMA(ai, bj, At, Bt) do { __builtin_amdgcn_s_setprio(1); _Pragma("unroll") for (int m = 0; m < 4; ++m) _Pragma("unroll") for (int n = 0; n < 2; ++n) _Pragma("unroll") for (int k = 0; k < 2; ++k) \
;         acc[ai][bj][m][n] = __builtin_amdgcn_mfma_f32_16x16x32_bf16(Bt[n][k], At[m][k], acc[ai][bj][m][n], 0, 0, 0); __builtin_amdgcn_s_setprio(0); } while (0)
; #define PG8_WAIT_V(n) asm volatile("s_waitcnt vmcnt(" #n ")" ::: "memory")
; #define PG8_WAIT_L(n) asm volatile("s_waitcnt lgkmcnt(" #n ")" ::: "memory")
; #define PG8_BAR __builtin_amdgcn_s_barrier()
; template <class Epi, class Sched, int LDA, int LDB, bool ALIGN_EPI = true>
; __device__ __forceinline__ void gemm_phase(LAS unsigned char* lds, const Gemm g, const Sched& S, const Epi& E, int wave) {
;     ...
;         for (int t = 0; t < nt; t += 2) {
;             const bool last = (t == nt - 2);
;             const char* a1 = cA + (size_t)(t + 1) * kstep;
;             const char* a2 = last ? nA : cA + (size_t)(t + 2) * kstep; const char* b2 = last ? nB : cB + (size_t)(t + 2) * kstep;
;             const char* a3 = a2 + kstep; const char* b3 = b2 + kstep;
;             PG8_LDB(B0, 0, 0); PG8_LDB(B1, 0, 1); PG8_SCHED; PG8_LDA(At, 0, 0); PG8_STAGE(PG8_SA(1, 1), a1 + hstepA, voffA);
;             PG8_WAIT_V(8); PG8_WAIT_L(0); PG8_BAR; PG8_MMA(0, 0, At, B0); PG8_MMA(0, 1, At, B1); PG8_BAR; PG8_SCHED;
;             PG8_LDA(At, 0, 1); PG8_STAGE(PG8_SB(0, 0), b2, voffB); PG8_STAGE(PG8_SB(0, 1), b2 + hstepB, voffB); PG8_STAGE(PG8_SA(0, 0), a2, voffA);
;             PG8_WAIT_V(8); PG8_WAIT_L(0); PG8_BAR; PG8_MMA(1, 0, At, B0); PG8_MMA(1, 1, At, B1); PG8_BAR; PG8_SCHED;
.LBB0_2254:
	s_add_u32 s2, s0, 0x100
	s_addc_u32 s3, s1, 0
	s_add_i32 s64, 0, 0x10000
	s_cmp_eq_u32 s59, 28
	s_cselect_b32 s29, s15, s3
	s_cselect_b32 s28, s14, s2
	v_add_u32_e32 v0, s64, v161
	s_cselect_b32 s25, s13, s58
	s_cselect_b32 s24, s48, s49
	s_add_i32 s65, 0, 0x14000
	ds_read_b128 v[144:147], v0
	ds_read_b128 v[148:151], v0 offset:1024
	ds_read_b128 v[152:155], v0 offset:2048
	ds_read_b128 v[156:159], v0 offset:3072
	v_add_u32_e32 v0, s65, v161
	ds_read_b128 v[164:167], v0
	ds_read_b128 v[168:171], v0 offset:1024
	ds_read_b128 v[172:175], v0 offset:2048
	ds_read_b128 v[180:183], v0 offset:3072
	v_lshl_add_u64 v[216:217], s[0:1], 0, v[140:141]
	s_add_i32 m0, s19, 0xc000
	ds_read_b128 v[184:187], v163
	ds_read_b128 v[188:191], v163 offset:1024
	ds_read_b128 v[192:195], v163 offset:2048
	ds_read_b128 v[196:199], v163 offset:3072
	ds_read_b128 v[200:203], v163 offset:4096
	ds_read_b128 v[204:207], v163 offset:5120
	ds_read_b128 v[208:211], v163 offset:6144
	ds_read_b128 v[212:215], v163 offset:7168
	global_load_lds_dwordx4 v[216:217], off
	v_lshl_add_u64 v[216:217], s[0:1], 0, v[142:143]
	s_add_i32 m0, s19, 0xe000
	s_nop 0
	global_load_lds_dwordx4 v[216:217], off
	s_waitcnt vmcnt(8)
	s_waitcnt lgkmcnt(0)
	s_setprio 1
	s_barrier
	v_mfma_f32_16x16x32_bf16 v[126:129], v[144:147], v[184:187], v[126:129]
	v_mfma_f32_16x16x32_bf16 v[122:125], v[152:155], v[184:187], v[122:125]
	v_mfma_f32_16x16x32_bf16 v[118:121], v[144:147], v[192:195], v[118:121]
	v_mfma_f32_16x16x32_bf16 v[114:117], v[152:155], v[192:195], v[114:117]
	v_mfma_f32_16x16x32_bf16 v[110:113], v[144:147], v[200:203], v[110:113]
	v_mfma_f32_16x16x32_bf16 v[106:109], v[152:155], v[200:203], v[106:109]
	v_mfma_f32_16x16x32_bf16 v[102:105], v[144:147], v[208:211], v[102:105]
	v_mfma_f32_16x16x32_bf16 v[98:101], v[152:155], v[208:211], v[98:101]
	v_mfma_f32_16x16x32_bf16 v[126:129], v[148:151], v[188:191], v[126:129]
	v_mfma_f32_16x16x32_bf16 v[122:125], v[156:159], v[188:191], v[122:125]
	v_mfma_f32_16x16x32_bf16 v[118:121], v[148:151], v[196:199], v[118:121]
	v_mfma_f32_16x16x32_bf16 v[114:117], v[156:159], v[196:199], v[114:117]
	v_mfma_f32_16x16x32_bf16 v[110:113], v[148:151], v[204:207], v[110:113]
	v_mfma_f32_16x16x32_bf16 v[106:109], v[156:159], v[204:207], v[106:109]
	v_mfma_f32_16x16x32_bf16 v[102:105], v[148:151], v[212:215], v[102:105]
	v_mfma_f32_16x16x32_bf16 v[98:101], v[156:159], v[212:215], v[98:101]
	v_mfma_f32_16x16x32_bf16 v[62:65], v[164:167], v[184:187], v[62:65]
	v_mfma_f32_16x16x32_bf16 v[58:61], v[172:175], v[184:187], v[58:61]
	v_mfma_f32_16x16x32_bf16 v[54:57], v[164:167], v[192:195], v[54:57]
	v_mfma_f32_16x16x32_bf16 v[50:53], v[172:175], v[192:195], v[50:53]
	v_mfma_f32_16x16x32_bf16 v[46:49], v[164:167], v[200:203], v[46:49]
	v_mfma_f32_16x16x32_bf16 v[42:45], v[172:175], v[200:203], v[42:45]
	v_mfma_f32_16x16x32_bf16 v[38:41], v[164:167], v[208:211], v[38:41]
	v_mfma_f32_16x16x32_bf16 v[34:37], v[172:175], v[208:211], v[34:37]
	v_mfma_f32_16x16x32_bf16 v[62:65], v[168:171], v[188:191], v[62:65]
	v_mfma_f32_16x16x32_bf16 v[58:61], v[180:183], v[188:191], v[58:61]
	v_mfma_f32_16x16x32_bf16 v[54:57], v[168:171], v[196:199], v[54:57]
	v_mfma_f32_16x16x32_bf16 v[50:53], v[180:183], v[196:199], v[50:53]
	v_mfma_f32_16x16x32_bf16 v[46:49], v[168:171], v[204:207], v[46:49]
	v_mfma_f32_16x16x32_bf16 v[42:45], v[180:183], v[204:207], v[42:45]
	v_mfma_f32_16x16x32_bf16 v[38:41], v[168:171], v[212:215], v[38:41]
	v_mfma_f32_16x16x32_bf16 v[34:37], v[180:183], v[212:215], v[34:37]
	s_barrier
	s_setprio 0
	s_add_i32 s0, s64, s61
	v_lshl_add_u64 v[216:217], s[24:25], 0, v[132:133]
	s_mov_b32 m0, s0
	ds_read_b128 v[184:187], v163 offset:16384
	ds_read_b128 v[188:191], v163 offset:17408
	ds_read_b128 v[192:195], v163 offset:18432
	ds_read_b128 v[196:199], v163 offset:19456
	ds_read_b128 v[200:203], v163 offset:20480
	ds_read_b128 v[204:207], v163 offset:21504
	ds_read_b128 v[208:211], v163 offset:22528
	ds_read_b128 v[212:215], v163 offset:23552
	global_load_lds_dwordx4 v[216:217], off
	s_add_i32 m0, s0, 0x2000
	s_add_u32 s0, s24, 0x80000
	v_lshl_add_u64 v[218:219], s[24:25], 0, v[136:137]
	s_addc_u32 s1, s25, 0
	s_add_i32 s64, s65, s61
	global_load_lds_dwordx4 v[218:219], off
	v_lshl_add_u64 v[220:221], s[0:1], 0, v[132:133]
	s_mov_b32 m0, s64
	v_lshl_add_u64 v[222:223], s[28:29], 0, v[134:135]
	global_load_lds_dwordx4 v[220:221], off
	v_lshl_add_u64 v[220:221], s[0:1], 0, v[136:137]
	s_add_i32 m0, s64, 0x2000
	s_nop 0
	global_load_lds_dwordx4 v[220:221], off
	v_lshl_add_u64 v[220:221], s[28:29], 0, v[130:131]
	s_mov_b32 m0, s19
	s_nop 0
	global_load_lds_dwordx4 v[220:221], off
	s_mov_b32 m0, s35
	s_nop 0
	global_load_lds_dwordx4 v[222:223], off
	s_waitcnt vmcnt(8)
	s_waitcnt lgkmcnt(0)
	s_setprio 1
	s_barrier
; #define PG8_STAGE(bufoff, gbase, voff) do { _Pragma("unroll") for (int _i = 0; _i < 2; ++_i) \
;         __builtin_amdgcn_global_load_lds((const unsigned*)((const char*)(gbase) + (voff)[_i]), (LAS unsigned*)(lds + (bufoff) + ldsw + _i * 8192), 16, 0, 0); } while (0)
; #define PG8_LDA(dst, b, h) do { _Pragma("unroll") for (int m = 0; m < 4; ++m) _Pragma("unroll") for (int k = 0; k < 2; ++k) dst[m][k] = *(const LAS bf16x8*)(lds + PG8_SA(b, h) + aoff + m * 2048 + k * 1024); } while (0)
; #define PG8_LDB(dst, b, h) do { _Pragma("unroll") for (int n = 0; n < 2; ++n) _Pragma("unroll") for (int k = 0; k < 2; ++k) dst[n][k] = *(const LAS bf16x8*)(lds + PG8_SB(b, h) + boff + n * 2048 + k * 1024); } while (0)
; #define PG8_MMA(ai, bj, At, Bt) do { __builtin_amdgcn_s_setprio(1); _Pragma("unroll") for (int m = 0; m < 4; ++m) _Pragma("unroll") for (int n = 0; n < 2; ++n) _Pragma("unroll") for (int k = 0; k < 2; ++k) \
;         acc[ai][bj][m][n] = __builtin_amdgcn_mfma_f32_16x16x32_bf16(Bt[n][k], At[m][k], acc[ai][bj][m][n], 0, 0, 0); __builtin_amdgcn_s_setprio(0); } while (0)
; #define PG8_WAIT_V(n) asm volatile("s_waitcnt vmcnt(" #n ")" ::: "memory")
; #define PG8_WAIT_L(n) asm volatile("s_waitcnt lgkmcnt(" #n ")" ::: "memory")
; #define PG8_BAR __builtin_amdgcn_s_barrier()
; #define PG8_SCHED __builtin_amdgcn_sched_barrier(0)
; template <class Epi, class Sched, int LDA, int LDB, bool ALIGN_EPI = true>
; __device__ __forceinline__ void gemm_phase(LAS unsigned char* lds, const Gemm g, const Sched& S, const Epi& E, int wave) {
;     ...
;             PG8_WAIT_V(8); PG8_WAIT_L(0); PG8_BAR; PG8_MMA(1, 0, At, B0); PG8_MMA(1, 1, At, B1); PG8_BAR; PG8_SCHED;
;             PG8_LDB(B0, 1, 0); PG8_LDB(B1, 1, 1); PG8_SCHED; PG8_LDA(At, 1, 0); PG8_STAGE(PG8_SA(0, 1), a2 + hstepA, voffA);
;             PG8_WAIT_V(8); PG8_WAIT_L(0); PG8_BAR; PG8_MMA(0, 0, At, B0); PG8_MMA(0, 1, At, B1); PG8_BAR; PG8_SCHED;
	v_mfma_f32_16x16x32_bf16 v[94:97], v[144:147], v[184:187], v[94:97]
	v_mfma_f32_16x16x32_bf16 v[90:93], v[152:155], v[184:187], v[90:93]
	v_mfma_f32_16x16x32_bf16 v[86:89], v[144:147], v[192:195], v[86:89]
	v_mfma_f32_16x16x32_bf16 v[82:85], v[152:155], v[192:195], v[82:85]
	v_mfma_f32_16x16x32_bf16 v[78:81], v[144:147], v[200:203], v[78:81]
	v_mfma_f32_16x16x32_bf16 v[74:77], v[152:155], v[200:203], v[74:77]
	v_mfma_f32_16x16x32_bf16 v[70:73], v[144:147], v[208:211], v[70:73]
	v_mfma_f32_16x16x32_bf16 v[66:69], v[152:155], v[208:211], v[66:69]
	v_mfma_f32_16x16x32_bf16 v[94:97], v[148:151], v[188:191], v[94:97]
	v_mfma_f32_16x16x32_bf16 v[90:93], v[156:159], v[188:191], v[90:93]
	v_mfma_f32_16x16x32_bf16 v[86:89], v[148:151], v[196:199], v[86:89]
	v_mfma_f32_16x16x32_bf16 v[82:85], v[156:159], v[196:199], v[82:85]
	v_mfma_f32_16x16x32_bf16 v[78:81], v[148:151], v[204:207], v[78:81]
	v_mfma_f32_16x16x32_bf16 v[74:77], v[156:159], v[204:207], v[74:77]
	v_mfma_f32_16x16x32_bf16 v[70:73], v[148:151], v[212:215], v[70:73]
	v_mfma_f32_16x16x32_bf16 v[66:69], v[156:159], v[212:215], v[66:69]
	v_mfma_f32_16x16x32_bf16 v[30:33], v[164:167], v[184:187], v[30:33]
	v_mfma_f32_16x16x32_bf16 v[26:29], v[172:175], v[184:187], v[26:29]
	v_mfma_f32_16x16x32_bf16 v[22:25], v[164:167], v[192:195], v[22:25]
	v_mfma_f32_16x16x32_bf16 v[18:21], v[172:175], v[192:195], v[18:21]
	v_mfma_f32_16x16x32_bf16 v[14:17], v[164:167], v[200:203], v[14:17]
	v_mfma_f32_16x16x32_bf16 v[10:13], v[172:175], v[200:203], v[10:13]
	v_mfma_f32_16x16x32_bf16 v[6:9], v[164:167], v[208:211], v[6:9]
	v_mfma_f32_16x16x32_bf16 v[2:5], v[172:175], v[208:211], v[2:5]
	v_mfma_f32_16x16x32_bf16 v[30:33], v[168:171], v[188:191], v[30:33]
	v_mfma_f32_16x16x32_bf16 v[26:29], v[180:183], v[188:191], v[26:29]
	v_mfma_f32_16x16x32_bf16 v[22:25], v[168:171], v[196:199], v[22:25]
	v_mfma_f32_16x16x32_bf16 v[18:21], v[180:183], v[196:199], v[18:21]
	v_mfma_f32_16x16x32_bf16 v[14:17], v[168:171], v[204:207], v[14:17]
	v_mfma_f32_16x16x32_bf16 v[10:13], v[180:183], v[204:207], v[10:13]
	v_mfma_f32_16x16x32_bf16 v[6:9], v[168:171], v[212:215], v[6:9]
	v_mfma_f32_16x16x32_bf16 v[2:5], v[180:183], v[212:215], v[2:5]
	s_barrier
	s_setprio 0
	s_add_i32 s64, 0, 0x18000
	v_add_u32_e32 v0, s64, v161
	s_add_i32 s65, 0, 0x1c000
	ds_read_b128 v[144:147], v0
	ds_read_b128 v[148:151], v0 offset:1024
	ds_read_b128 v[152:155], v0 offset:2048
	ds_read_b128 v[156:159], v0 offset:3072
	v_add_u32_e32 v0, s65, v161
	ds_read_b128 v[164:167], v0
	ds_read_b128 v[168:171], v0 offset:1024
	ds_read_b128 v[172:175], v0 offset:2048
	ds_read_b128 v[180:183], v0 offset:3072
	s_add_u32 s0, s28, 0x84000
	s_addc_u32 s1, s29, 0
	s_mov_b32 m0, s36
	v_lshl_add_u64 v[224:225], s[0:1], 0, v[130:131]
	ds_read_b128 v[184:187], v163 offset:32768
	ds_read_b128 v[188:191], v163 offset:33792
	ds_read_b128 v[192:195], v163 offset:34816
	ds_read_b128 v[196:199], v163 offset:35840
	ds_read_b128 v[200:203], v163 offset:36864
	ds_read_b128 v[204:207], v163 offset:37888
	ds_read_b128 v[208:211], v163 offset:38912
	ds_read_b128 v[212:215], v163 offset:39936
	global_load_lds_dwordx4 v[224:225], off
	v_lshl_add_u64 v[224:225], s[0:1], 0, v[134:135]
	s_mov_b32 m0, s37
	s_nop 0
	global_load_lds_dwordx4 v[224:225], off
	s_waitcnt vmcnt(8)
	s_waitcnt lgkmcnt(0)
	s_setprio 1
	s_barrier
	v_mfma_f32_16x16x32_bf16 v[126:129], v[144:147], v[184:187], v[126:129]
	v_mfma_f32_16x16x32_bf16 v[122:125], v[152:155], v[184:187], v[122:125]
	v_mfma_f32_16x16x32_bf16 v[118:121], v[144:147], v[192:195], v[118:121]
	v_mfma_f32_16x16x32_bf16 v[114:117], v[152:155], v[192:195], v[114:117]
	v_mfma_f32_16x16x32_bf16 v[110:113], v[144:147], v[200:203], v[110:113]
	v_mfma_f32_16x16x32_bf16 v[106:109], v[152:155], v[200:203], v[106:109]
	v_mfma_f32_16x16x32_bf16 v[102:105], v[144:147], v[208:211], v[102:105]
	v_mfma_f32_16x16x32_bf16 v[98:101], v[152:155], v[208:211], v[98:101]
	v_mfma_f32_16x16x32_bf16 v[126:129], v[148:151], v[188:191], v[126:129]
	v_mfma_f32_16x16x32_bf16 v[122:125], v[156:159], v[188:191], v[122:125]
	v_mfma_f32_16x16x32_bf16 v[118:121], v[148:151], v[196:199], v[118:121]
	v_mfma_f32_16x16x32_bf16 v[114:117], v[156:159], v[196:199], v[114:117]
	v_mfma_f32_16x16x32_bf16 v[110:113], v[148:151], v[204:207], v[110:113]
	v_mfma_f32_16x16x32_bf16 v[106:109], v[156:159], v[204:207], v[106:109]
	v_mfma_f32_16x16x32_bf16 v[102:105], v[148:151], v[212:215], v[102:105]
	v_mfma_f32_16x16x32_bf16 v[98:101], v[156:159], v[212:215], v[98:101]
	v_mfma_f32_16x16x32_bf16 v[62:65], v[164:167], v[184:187], v[62:65]
	v_mfma_f32_16x16x32_bf16 v[58:61], v[172:175], v[184:187], v[58:61]
	v_mfma_f32_16x16x32_bf16 v[54:57], v[164:167], v[192:195], v[54:57]
	v_mfma_f32_16x16x32_bf16 v[50:53], v[172:175], v[192:195], v[50:53]
	v_mfma_f32_16x16x32_bf16 v[46:49], v[164:167], v[200:203], v[46:49]
	v_mfma_f32_16x16x32_bf16 v[42:45], v[172:175], v[200:203], v[42:45]
	v_mfma_f32_16x16x32_bf16 v[38:41], v[164:167], v[208:211], v[38:41]
	v_mfma_f32_16x16x32_bf16 v[34:37], v[172:175], v[208:211], v[34:37]
	v_mfma_f32_16x16x32_bf16 v[62:65], v[168:171], v[188:191], v[62:65]
	v_mfma_f32_16x16x32_bf16 v[58:61], v[180:183], v[188:191], v[58:61]
	v_mfma_f32_16x16x32_bf16 v[54:57], v[168:171], v[196:199], v[54:57]
	v_mfma_f32_16x16x32_bf16 v[50:53], v[180:183], v[196:199], v[50:53]
	v_mfma_f32_16x16x32_bf16 v[46:49], v[168:171], v[204:207], v[46:49]
	v_mfma_f32_16x16x32_bf16 v[42:45], v[180:183], v[204:207], v[42:45]
	v_mfma_f32_16x16x32_bf16 v[38:41], v[168:171], v[212:215], v[38:41]
	v_mfma_f32_16x16x32_bf16 v[34:37], v[180:183], v[212:215], v[34:37]
	s_barrier
; #define PG8_STAGE(bufoff, gbase, voff) do { _Pragma("unroll") for (int _i = 0; _i < 2; ++_i) \
;         __builtin_amdgcn_global_load_lds((const unsigned*)((const char*)(gbase) + (voff)[_i]), (LAS unsigned*)(lds + (bufoff) + ldsw + _i * 8192), 16, 0, 0); } while (0)
; #define PG8_LDA(dst, b, h) do { _Pragma("unroll") for (int m = 0; m < 4; ++m) _Pragma("unroll") for (int k = 0; k < 2; ++k) dst[m][k] = *(const LAS bf16x8*)(lds + PG8_SA(b, h) + aoff + m * 2048 + k * 1024); } while (0)
; #define PG8_MMA(ai, bj, At, Bt) do { __builtin_amdgcn_s_setprio(1); _Pragma("unroll") for (int m = 0; m < 4; ++m) _Pragma("unroll") for (int n = 0; n < 2; ++n) _Pragma("unroll") for (int k = 0; k < 2; ++k) \
;         acc[ai][bj][m][n] = __builtin_amdgcn_mfma_f32_16x16x32_bf16(Bt[n][k], At[m][k], acc[ai][bj][m][n], 0, 0, 0); __builtin_amdgcn_s_setprio(0); } while (0)
; #define PG8_WAIT_V(n) asm volatile("s_waitcnt vmcnt(" #n ")" ::: "memory")
; #define PG8_WAIT_L(n) asm volatile("s_waitcnt lgkmcnt(" #n ")" ::: "memory")
; #define PG8_BAR __builtin_amdgcn_s_barrier()
; #define PG8_SCHED __builtin_amdgcn_sched_barrier(0)
; template <class Epi, class Sched, int LDA, int LDB, bool ALIGN_EPI = true>
; __device__ __forceinline__ void gemm_phase(LAS unsigned char* lds, const Gemm g, const Sched& S, const Epi& E, int wave) {
;     ...
;             PG8_LDA(At, 1, 1); PG8_STAGE(PG8_SB(1, 0), b3, voffB); PG8_STAGE(PG8_SB(1, 1), b3 + hstepB, voffB); PG8_STAGE(PG8_SA(1, 0), a3, voffA);
;             PG8_WAIT_V(8); PG8_WAIT_L(0); PG8_BAR; PG8_MMA(1, 0, At, B0); PG8_MMA(1, 1, At, B1); PG8_BAR; PG8_SCHED;
;         }
;         if constexpr (ALIGN_EPI) { if (wr == 0) PG8_BAR; }
	s_setprio 0
	s_add_i32 s0, s64, s61
	v_lshl_add_u64 v[216:217], v[216:217], 0, s[70:71]
	s_mov_b32 m0, s0
	ds_read_b128 v[184:187], v163 offset:49152
	ds_read_b128 v[188:191], v163 offset:50176
	ds_read_b128 v[192:195], v163 offset:51200
	ds_read_b128 v[196:199], v163 offset:52224
	ds_read_b128 v[200:203], v163 offset:53248
	ds_read_b128 v[204:207], v163 offset:54272
	ds_read_b128 v[208:211], v163 offset:55296
	ds_read_b128 v[212:215], v163 offset:56320
	global_load_lds_dwordx4 v[216:217], off
	s_add_i32 m0, s0, 0x2000
	s_add_u32 s0, s24, 0x80080
	v_lshl_add_u64 v[216:217], v[218:219], 0, s[70:71]
	s_addc_u32 s1, s25, 0
	s_add_i32 s24, s65, s61
	global_load_lds_dwordx4 v[216:217], off
	v_lshl_add_u64 v[216:217], s[0:1], 0, v[132:133]
	s_mov_b32 m0, s24
	s_nop 0
	global_load_lds_dwordx4 v[216:217], off
	v_lshl_add_u64 v[216:217], s[0:1], 0, v[136:137]
	s_add_i32 m0, s24, 0x2000
	s_nop 0
	global_load_lds_dwordx4 v[216:217], off
	v_lshl_add_u64 v[216:217], v[220:221], 0, s[70:71]
	s_mov_b32 m0, s38
	s_nop 0
	global_load_lds_dwordx4 v[216:217], off
	v_lshl_add_u64 v[216:217], v[222:223], 0, s[70:71]
	s_mov_b32 m0, s39
	s_nop 0
	global_load_lds_dwordx4 v[216:217], off
	s_waitcnt vmcnt(8)
	s_waitcnt lgkmcnt(0)
	s_setprio 1
	s_barrier
	v_mfma_f32_16x16x32_bf16 v[94:97], v[144:147], v[184:187], v[94:97]
	v_mfma_f32_16x16x32_bf16 v[90:93], v[152:155], v[184:187], v[90:93]
	v_mfma_f32_16x16x32_bf16 v[86:89], v[144:147], v[192:195], v[86:89]
	v_mfma_f32_16x16x32_bf16 v[82:85], v[152:155], v[192:195], v[82:85]
	v_mfma_f32_16x16x32_bf16 v[78:81], v[144:147], v[200:203], v[78:81]
	v_mfma_f32_16x16x32_bf16 v[74:77], v[152:155], v[200:203], v[74:77]
	v_mfma_f32_16x16x32_bf16 v[70:73], v[144:147], v[208:211], v[70:73]
	v_mfma_f32_16x16x32_bf16 v[66:69], v[152:155], v[208:211], v[66:69]
	v_mfma_f32_16x16x32_bf16 v[94:97], v[148:151], v[188:191], v[94:97]
	v_mfma_f32_16x16x32_bf16 v[90:93], v[156:159], v[188:191], v[90:93]
	v_mfma_f32_16x16x32_bf16 v[86:89], v[148:151], v[196:199], v[86:89]
	v_mfma_f32_16x16x32_bf16 v[82:85], v[156:159], v[196:199], v[82:85]
	v_mfma_f32_16x16x32_bf16 v[78:81], v[148:151], v[204:207], v[78:81]
	v_mfma_f32_16x16x32_bf16 v[74:77], v[156:159], v[204:207], v[74:77]
	v_mfma_f32_16x16x32_bf16 v[70:73], v[148:151], v[212:215], v[70:73]
	v_mfma_f32_16x16x32_bf16 v[66:69], v[156:159], v[212:215], v[66:69]
	v_mfma_f32_16x16x32_bf16 v[30:33], v[164:167], v[184:187], v[30:33]
	v_mfma_f32_16x16x32_bf16 v[26:29], v[172:175], v[184:187], v[26:29]
	v_mfma_f32_16x16x32_bf16 v[22:25], v[164:167], v[192:195], v[22:25]
	v_mfma_f32_16x16x32_bf16 v[18:21], v[172:175], v[192:195], v[18:21]
	v_mfma_f32_16x16x32_bf16 v[14:17], v[164:167], v[200:203], v[14:17]
	v_mfma_f32_16x16x32_bf16 v[10:13], v[172:175], v[200:203], v[10:13]
	v_mfma_f32_16x16x32_bf16 v[6:9], v[164:167], v[208:211], v[6:9]
	v_mfma_f32_16x16x32_bf16 v[2:5], v[172:175], v[208:211], v[2:5]
	v_mfma_f32_16x16x32_bf16 v[30:33], v[168:171], v[188:191], v[30:33]
	v_mfma_f32_16x16x32_bf16 v[26:29], v[180:183], v[188:191], v[26:29]
	v_mfma_f32_16x16x32_bf16 v[22:25], v[168:171], v[196:199], v[22:25]
	v_mfma_f32_16x16x32_bf16 v[18:21], v[180:183], v[196:199], v[18:21]
	v_mfma_f32_16x16x32_bf16 v[14:17], v[168:171], v[204:207], v[14:17]
	v_mfma_f32_16x16x32_bf16 v[10:13], v[180:183], v[204:207], v[10:13]
	v_mfma_f32_16x16x32_bf16 v[6:9], v[168:171], v[212:215], v[6:9]
	v_mfma_f32_16x16x32_bf16 v[2:5], v[180:183], v[212:215], v[2:5]
	s_barrier
	s_setprio 0
	s_add_i32 s59, s59, 2
	s_add_u32 s49, s49, 0x100
	s_addc_u32 s58, s58, 0
	s_cmp_gt_u32 s59, 29
	s_mov_b64 s[0:1], s[2:3]
	s_cbranch_scc0 .LBB0_2254
	v_readlane_b32 s0, v252, 14
	v_readlane_b32 s1, v252, 15
	s_and_b64 vcc, exec, s[0:1]
	s_cbranch_vccz .LBB0_2257
	s_barrier

; #define PG8_STAGE(bufoff, gbase, voff) do { _Pragma("unroll") for (int _i = 0; _i < 2; ++_i) \
;         __builtin_amdgcn_global_load_lds((const unsigned*)((const char*)(gbase) + (voff)[_i]), (LAS unsigned*)(lds + (bufoff) + ldsw + _i * 8192), 16, 0, 0); } while (0)
; #define PG8_LDA(dst, b, h) do { _Pragma("unroll") for (int m = 0; m < 4; ++m) _Pragma("unroll") for (int k = 0; k < 2; ++k) dst[m][k] = *(const LAS bf16x8*)(lds + PG8_SA(b, h) + aoff + m * 2048 + k * 1024); } while (0)
; #define PG8_LDB(dst, b, h) do { _Pragma("unroll") for (int n = 0; n < 2; ++n) _Pragma("unroll") for (int k = 0; k < 2; ++k) dst[n][k] = *(const LAS bf16x8*)(lds + PG8_SB(b, h) + boff + n * 2048 + k * 1024); } while (0)
; #define PG8_MMA(ai, bj, At, Bt) do { __builtin_amdgcn_s_setprio(1); _Pragma("unroll") for (int m = 0; m < 4; ++m) _Pragma("unroll") for (int n = 0; n < 2; ++n) _Pragma("unroll") for (int k = 0; k < 2; ++k) \
;         acc[ai][bj][m][n] = __builtin_amdgcn_mfma_f32_16x16x32_bf16(Bt[n][k], At[m][k], acc[ai][bj][m][n], 0, 0, 0); __builtin_amdgcn_s_setprio(0); } while (0)
; #define PG8_WAIT_V(n) asm volatile("s_waitcnt vmcnt(" #n ")" ::: "memory")
; #define PG8_WAIT_L(n) asm volatile("s_waitcnt lgkmcnt(" #n ")" ::: "memory")
; #define PG8_BAR __builtin_amdgcn_s_barrier()
; template <class Epi, class Sched, int LDA, int LDB, bool ALIGN_EPI = true>
; __device__ __forceinline__ void gemm_phase(LAS unsigned char* lds, const Gemm g, const Sched& S, const Epi& E, int wave) {
;     ...
;         for (int t = 0; t < nt; t += 2) {
;             const bool last = (t == nt - 2);
;             const char* a1 = cA + (size_t)(t + 1) * kstep;
;             const char* a2 = last ? nA : cA + (size_t)(t + 2) * kstep; const char* b2 = last ? nB : cB + (size_t)(t + 2) * kstep;
;             const char* a3 = a2 + kstep; const char* b3 = b2 + kstep;
;             PG8_LDB(B0, 0, 0); PG8_LDB(B1, 0, 1); PG8_SCHED; PG8_LDA(At, 0, 0); PG8_STAGE(PG8_SA(1, 1), a1 + hstepA, voffA);
;             PG8_WAIT_V(8); PG8_WAIT_L(0); PG8_BAR; PG8_MMA(0, 0, At, B0); PG8_MMA(0, 1, At, B1); PG8_BAR; PG8_SCHED;
;             PG8_LDA(At, 0, 1); PG8_STAGE(PG8_SB(0, 0), b2, voffB); PG8_STAGE(PG8_SB(0, 1), b2 + hstepB, voffB); PG8_STAGE(PG8_SA(0, 0), a2, voffA);
;             PG8_WAIT_V(8); PG8_WAIT_L(0); PG8_BAR; PG8_MMA(1, 0, At, B0); PG8_MMA(1, 1, At, B1); PG8_BAR; PG8_SCHED;
.LBB0_2415:
	s_add_u32 s12, s10, 0xfff80080
	s_addc_u32 s13, s11, -1
	s_add_i32 s39, 0, 0x10000
	s_cmp_eq_u32 s38, 28
	s_cselect_b32 s15, s1, s13
	s_cselect_b32 s14, s3, s12
	v_add_u32_e32 v140, s39, v143
	s_cselect_b32 s13, s7, s37
	s_cselect_b32 s12, s6, s36
	s_add_i32 s46, 0, 0x14000
	ds_read_b128 v[146:149], v140
	ds_read_b128 v[150:153], v140 offset:1024
	ds_read_b128 v[154:157], v140 offset:2048
	ds_read_b128 v[158:161], v140 offset:3072
	v_add_u32_e32 v140, s46, v143
	ds_read_b128 v[162:165], v140
	ds_read_b128 v[166:169], v140 offset:1024
	ds_read_b128 v[170:173], v140 offset:2048
	ds_read_b128 v[180:183], v140 offset:3072
	v_lshl_add_u64 v[140:141], s[10:11], 0, v[136:137]
	s_add_i32 m0, s18, 0xc000
	ds_read_b128 v[184:187], v145
	ds_read_b128 v[188:191], v145 offset:1024
	ds_read_b128 v[192:195], v145 offset:2048
	ds_read_b128 v[196:199], v145 offset:3072
	ds_read_b128 v[200:203], v145 offset:4096
	ds_read_b128 v[204:207], v145 offset:5120
	ds_read_b128 v[208:211], v145 offset:6144
	ds_read_b128 v[212:215], v145 offset:7168
	global_load_lds_dwordx4 v[140:141], off
	v_lshl_add_u64 v[140:141], s[10:11], 0, v[138:139]
	s_add_i32 m0, s18, 0xe000
	s_nop 0
	global_load_lds_dwordx4 v[140:141], off
	s_waitcnt vmcnt(8)
	s_waitcnt lgkmcnt(0)
	s_setprio 1
	s_barrier
	v_mfma_f32_16x16x32_bf16 v[126:129], v[146:149], v[184:187], v[126:129]
	v_mfma_f32_16x16x32_bf16 v[122:125], v[154:157], v[184:187], v[122:125]
	v_mfma_f32_16x16x32_bf16 v[114:117], v[146:149], v[192:195], v[114:117]
	v_mfma_f32_16x16x32_bf16 v[106:109], v[154:157], v[192:195], v[106:109]
	v_mfma_f32_16x16x32_bf16 v[98:101], v[146:149], v[200:203], v[98:101]
	v_mfma_f32_16x16x32_bf16 v[90:93], v[154:157], v[200:203], v[90:93]
	v_mfma_f32_16x16x32_bf16 v[82:85], v[146:149], v[208:211], v[82:85]
	v_mfma_f32_16x16x32_bf16 v[74:77], v[154:157], v[208:211], v[74:77]
	v_mfma_f32_16x16x32_bf16 v[126:129], v[150:153], v[188:191], v[126:129]
	v_mfma_f32_16x16x32_bf16 v[122:125], v[158:161], v[188:191], v[122:125]
	v_mfma_f32_16x16x32_bf16 v[114:117], v[150:153], v[196:199], v[114:117]
	v_mfma_f32_16x16x32_bf16 v[106:109], v[158:161], v[196:199], v[106:109]
	v_mfma_f32_16x16x32_bf16 v[98:101], v[150:153], v[204:207], v[98:101]
	v_mfma_f32_16x16x32_bf16 v[90:93], v[158:161], v[204:207], v[90:93]
	v_mfma_f32_16x16x32_bf16 v[82:85], v[150:153], v[212:215], v[82:85]
	v_mfma_f32_16x16x32_bf16 v[74:77], v[158:161], v[212:215], v[74:77]
	v_mfma_f32_16x16x32_bf16 v[118:121], v[162:165], v[184:187], v[118:121]
	v_mfma_f32_16x16x32_bf16 v[110:113], v[170:173], v[184:187], v[110:113]
	v_mfma_f32_16x16x32_bf16 v[102:105], v[162:165], v[192:195], v[102:105]
	v_mfma_f32_16x16x32_bf16 v[94:97], v[170:173], v[192:195], v[94:97]
	v_mfma_f32_16x16x32_bf16 v[86:89], v[162:165], v[200:203], v[86:89]
	v_mfma_f32_16x16x32_bf16 v[78:81], v[170:173], v[200:203], v[78:81]
	v_mfma_f32_16x16x32_bf16 v[70:73], v[162:165], v[208:211], v[70:73]
	v_mfma_f32_16x16x32_bf16 v[66:69], v[170:173], v[208:211], v[66:69]
	v_mfma_f32_16x16x32_bf16 v[118:121], v[166:169], v[188:191], v[118:121]
	v_mfma_f32_16x16x32_bf16 v[110:113], v[180:183], v[188:191], v[110:113]
	v_mfma_f32_16x16x32_bf16 v[102:105], v[166:169], v[196:199], v[102:105]
	v_mfma_f32_16x16x32_bf16 v[94:97], v[180:183], v[196:199], v[94:97]
	v_mfma_f32_16x16x32_bf16 v[86:89], v[166:169], v[204:207], v[86:89]
	v_mfma_f32_16x16x32_bf16 v[78:81], v[180:183], v[204:207], v[78:81]
	v_mfma_f32_16x16x32_bf16 v[70:73], v[166:169], v[212:215], v[70:73]
	v_mfma_f32_16x16x32_bf16 v[66:69], v[180:183], v[212:215], v[66:69]
	s_barrier
	s_setprio 0
	s_add_i32 s39, s39, s47
	v_lshl_add_u64 v[140:141], s[12:13], 0, v[0:1]
	s_mov_b32 m0, s39
	ds_read_b128 v[184:187], v145 offset:16384
	ds_read_b128 v[188:191], v145 offset:17408
	ds_read_b128 v[192:195], v145 offset:18432
	ds_read_b128 v[196:199], v145 offset:19456
	ds_read_b128 v[200:203], v145 offset:20480
	ds_read_b128 v[204:207], v145 offset:21504
	ds_read_b128 v[208:211], v145 offset:22528
	ds_read_b128 v[212:215], v145 offset:23552
	global_load_lds_dwordx4 v[140:141], off
	s_add_i32 m0, s39, 0x2000
	s_add_u32 s44, s12, 0x84000
	v_lshl_add_u64 v[174:175], s[12:13], 0, v[134:135]
	s_addc_u32 s45, s13, 0
	s_add_i32 s39, s46, s47
	global_load_lds_dwordx4 v[174:175], off
	v_lshl_add_u64 v[216:217], s[44:45], 0, v[0:1]
	s_mov_b32 m0, s39
	v_lshl_add_u64 v[218:219], s[14:15], 0, v[132:133]
	global_load_lds_dwordx4 v[216:217], off
	v_lshl_add_u64 v[216:217], s[44:45], 0, v[134:135]
	s_add_i32 m0, s39, 0x2000
	s_nop 0
	global_load_lds_dwordx4 v[216:217], off
	v_lshl_add_u64 v[216:217], s[14:15], 0, v[130:131]
	s_mov_b32 m0, s18
	s_nop 0
	global_load_lds_dwordx4 v[216:217], off
	s_mov_b32 m0, s19
	s_nop 0
	global_load_lds_dwordx4 v[218:219], off
	s_waitcnt vmcnt(8)
	s_waitcnt lgkmcnt(0)
	s_setprio 1
	s_barrier
; #define PG8_STAGE(bufoff, gbase, voff) do { _Pragma("unroll") for (int _i = 0; _i < 2; ++_i) \
;         __builtin_amdgcn_global_load_lds((const unsigned*)((const char*)(gbase) + (voff)[_i]), (LAS unsigned*)(lds + (bufoff) + ldsw + _i * 8192), 16, 0, 0); } while (0)
; #define PG8_LDA(dst, b, h) do { _Pragma("unroll") for (int m = 0; m < 4; ++m) _Pragma("unroll") for (int k = 0; k < 2; ++k) dst[m][k] = *(const LAS bf16x8*)(lds + PG8_SA(b, h) + aoff + m * 2048 + k * 1024); } while (0)
; #define PG8_LDB(dst, b, h) do { _Pragma("unroll") for (int n = 0; n < 2; ++n) _Pragma("unroll") for (int k = 0; k < 2; ++k) dst[n][k] = *(const LAS bf16x8*)(lds + PG8_SB(b, h) + boff + n * 2048 + k * 1024); } while (0)
; #define PG8_MMA(ai, bj, At, Bt) do { __builtin_amdgcn_s_setprio(1); _Pragma("unroll") for (int m = 0; m < 4; ++m) _Pragma("unroll") for (int n = 0; n < 2; ++n) _Pragma("unroll") for (int k = 0; k < 2; ++k) \
;         acc[ai][bj][m][n] = __builtin_amdgcn_mfma_f32_16x16x32_bf16(Bt[n][k], At[m][k], acc[ai][bj][m][n], 0, 0, 0); __builtin_amdgcn_s_setprio(0); } while (0)
; #define PG8_WAIT_V(n) asm volatile("s_waitcnt vmcnt(" #n ")" ::: "memory")
; #define PG8_WAIT_L(n) asm volatile("s_waitcnt lgkmcnt(" #n ")" ::: "memory")
; #define PG8_BAR __builtin_amdgcn_s_barrier()
; #define PG8_SCHED __builtin_amdgcn_sched_barrier(0)
; template <class Epi, class Sched, int LDA, int LDB, bool ALIGN_EPI = true>
; __device__ __forceinline__ void gemm_phase(LAS unsigned char* lds, const Gemm g, const Sched& S, const Epi& E, int wave) {
;     ...
;             PG8_WAIT_V(8); PG8_WAIT_L(0); PG8_BAR; PG8_MMA(1, 0, At, B0); PG8_MMA(1, 1, At, B1); PG8_BAR; PG8_SCHED;
;             PG8_LDB(B0, 1, 0); PG8_LDB(B1, 1, 1); PG8_SCHED; PG8_LDA(At, 1, 0); PG8_STAGE(PG8_SA(0, 1), a2 + hstepA, voffA);
;             PG8_WAIT_V(8); PG8_WAIT_L(0); PG8_BAR; PG8_MMA(0, 0, At, B0); PG8_MMA(0, 1, At, B1); PG8_BAR; PG8_SCHED;
	v_mfma_f32_16x16x32_bf16 v[62:65], v[146:149], v[184:187], v[62:65]
	v_mfma_f32_16x16x32_bf16 v[58:61], v[154:157], v[184:187], v[58:61]
	v_mfma_f32_16x16x32_bf16 v[50:53], v[146:149], v[192:195], v[50:53]
	v_mfma_f32_16x16x32_bf16 v[42:45], v[154:157], v[192:195], v[42:45]
	v_mfma_f32_16x16x32_bf16 v[34:37], v[146:149], v[200:203], v[34:37]
	v_mfma_f32_16x16x32_bf16 v[26:29], v[154:157], v[200:203], v[26:29]
	v_mfma_f32_16x16x32_bf16 v[18:21], v[146:149], v[208:211], v[18:21]
	v_mfma_f32_16x16x32_bf16 v[10:13], v[154:157], v[208:211], v[10:13]
	v_mfma_f32_16x16x32_bf16 v[62:65], v[150:153], v[188:191], v[62:65]
	v_mfma_f32_16x16x32_bf16 v[58:61], v[158:161], v[188:191], v[58:61]
	v_mfma_f32_16x16x32_bf16 v[50:53], v[150:153], v[196:199], v[50:53]
	v_mfma_f32_16x16x32_bf16 v[42:45], v[158:161], v[196:199], v[42:45]
	v_mfma_f32_16x16x32_bf16 v[34:37], v[150:153], v[204:207], v[34:37]
	v_mfma_f32_16x16x32_bf16 v[26:29], v[158:161], v[204:207], v[26:29]
	v_mfma_f32_16x16x32_bf16 v[18:21], v[150:153], v[212:215], v[18:21]
	v_mfma_f32_16x16x32_bf16 v[10:13], v[158:161], v[212:215], v[10:13]
	v_mfma_f32_16x16x32_bf16 v[54:57], v[162:165], v[184:187], v[54:57]
	v_mfma_f32_16x16x32_bf16 v[46:49], v[170:173], v[184:187], v[46:49]
	v_mfma_f32_16x16x32_bf16 v[38:41], v[162:165], v[192:195], v[38:41]
	v_mfma_f32_16x16x32_bf16 v[30:33], v[170:173], v[192:195], v[30:33]
	v_mfma_f32_16x16x32_bf16 v[22:25], v[162:165], v[200:203], v[22:25]
	v_mfma_f32_16x16x32_bf16 v[14:17], v[170:173], v[200:203], v[14:17]
	v_mfma_f32_16x16x32_bf16 v[6:9], v[162:165], v[208:211], v[6:9]
	v_mfma_f32_16x16x32_bf16 v[2:5], v[170:173], v[208:211], v[2:5]
	v_mfma_f32_16x16x32_bf16 v[54:57], v[166:169], v[188:191], v[54:57]
	v_mfma_f32_16x16x32_bf16 v[46:49], v[180:183], v[188:191], v[46:49]
	v_mfma_f32_16x16x32_bf16 v[38:41], v[166:169], v[196:199], v[38:41]
	v_mfma_f32_16x16x32_bf16 v[30:33], v[180:183], v[196:199], v[30:33]
	v_mfma_f32_16x16x32_bf16 v[22:25], v[166:169], v[204:207], v[22:25]
	v_mfma_f32_16x16x32_bf16 v[14:17], v[180:183], v[204:207], v[14:17]
	v_mfma_f32_16x16x32_bf16 v[6:9], v[166:169], v[212:215], v[6:9]
	v_mfma_f32_16x16x32_bf16 v[2:5], v[180:183], v[212:215], v[2:5]
	s_barrier
	s_setprio 0
	s_add_i32 s39, 0, 0x18000
	s_add_i32 s44, 0, 0x1c000
	v_add_u32_e32 v158, s39, v143
	v_add_u32_e32 v180, s44, v143
	ds_read_b128 v[146:149], v158
	ds_read_b128 v[150:153], v158 offset:1024
	ds_read_b128 v[154:157], v158 offset:2048
	ds_read_b128 v[158:161], v158 offset:3072
	ds_read_b128 v[162:165], v180
	ds_read_b128 v[166:169], v180 offset:1024
	ds_read_b128 v[170:173], v180 offset:2048
	ds_read_b128 v[180:183], v180 offset:3072
	s_add_u32 s14, s14, 0x80000
	s_addc_u32 s15, s15, 0
	s_mov_b32 m0, s24
	v_lshl_add_u64 v[220:221], s[14:15], 0, v[130:131]
	ds_read_b128 v[184:187], v145 offset:32768
	ds_read_b128 v[188:191], v145 offset:33792
	ds_read_b128 v[192:195], v145 offset:34816
	ds_read_b128 v[196:199], v145 offset:35840
	ds_read_b128 v[200:203], v145 offset:36864
	ds_read_b128 v[204:207], v145 offset:37888
	ds_read_b128 v[208:211], v145 offset:38912
	ds_read_b128 v[212:215], v145 offset:39936
	global_load_lds_dwordx4 v[220:221], off
	v_lshl_add_u64 v[220:221], s[14:15], 0, v[132:133]
	s_mov_b32 m0, s25
	s_nop 0
	global_load_lds_dwordx4 v[220:221], off
	s_waitcnt vmcnt(8)
	s_waitcnt lgkmcnt(0)
	s_setprio 1
	s_barrier
	v_mfma_f32_16x16x32_bf16 v[126:129], v[146:149], v[184:187], v[126:129]
	v_mfma_f32_16x16x32_bf16 v[122:125], v[154:157], v[184:187], v[122:125]
	v_mfma_f32_16x16x32_bf16 v[114:117], v[146:149], v[192:195], v[114:117]
	v_mfma_f32_16x16x32_bf16 v[106:109], v[154:157], v[192:195], v[106:109]
	v_mfma_f32_16x16x32_bf16 v[98:101], v[146:149], v[200:203], v[98:101]
	v_mfma_f32_16x16x32_bf16 v[90:93], v[154:157], v[200:203], v[90:93]
	v_mfma_f32_16x16x32_bf16 v[82:85], v[146:149], v[208:211], v[82:85]
	v_mfma_f32_16x16x32_bf16 v[74:77], v[154:157], v[208:211], v[74:77]
	v_mfma_f32_16x16x32_bf16 v[126:129], v[150:153], v[188:191], v[126:129]
	v_mfma_f32_16x16x32_bf16 v[122:125], v[158:161], v[188:191], v[122:125]
	v_mfma_f32_16x16x32_bf16 v[114:117], v[150:153], v[196:199], v[114:117]
	v_mfma_f32_16x16x32_bf16 v[106:109], v[158:161], v[196:199], v[106:109]
	v_mfma_f32_16x16x32_bf16 v[98:101], v[150:153], v[204:207], v[98:101]
	v_mfma_f32_16x16x32_bf16 v[90:93], v[158:161], v[204:207], v[90:93]
	v_mfma_f32_16x16x32_bf16 v[82:85], v[150:153], v[212:215], v[82:85]
	v_mfma_f32_16x16x32_bf16 v[74:77], v[158:161], v[212:215], v[74:77]
	v_mfma_f32_16x16x32_bf16 v[118:121], v[162:165], v[184:187], v[118:121]
	v_mfma_f32_16x16x32_bf16 v[110:113], v[170:173], v[184:187], v[110:113]
	v_mfma_f32_16x16x32_bf16 v[102:105], v[162:165], v[192:195], v[102:105]
	v_mfma_f32_16x16x32_bf16 v[94:97], v[170:173], v[192:195], v[94:97]
	v_mfma_f32_16x16x32_bf16 v[86:89], v[162:165], v[200:203], v[86:89]
	v_mfma_f32_16x16x32_bf16 v[78:81], v[170:173], v[200:203], v[78:81]
	v_mfma_f32_16x16x32_bf16 v[70:73], v[162:165], v[208:211], v[70:73]
	v_mfma_f32_16x16x32_bf16 v[66:69], v[170:173], v[208:211], v[66:69]
	v_mfma_f32_16x16x32_bf16 v[118:121], v[166:169], v[188:191], v[118:121]
	v_mfma_f32_16x16x32_bf16 v[110:113], v[180:183], v[188:191], v[110:113]
	v_mfma_f32_16x16x32_bf16 v[102:105], v[166:169], v[196:199], v[102:105]
	v_mfma_f32_16x16x32_bf16 v[94:97], v[180:183], v[196:199], v[94:97]
	v_mfma_f32_16x16x32_bf16 v[86:89], v[166:169], v[204:207], v[86:89]
	v_mfma_f32_16x16x32_bf16 v[78:81], v[180:183], v[204:207], v[78:81]
	v_mfma_f32_16x16x32_bf16 v[70:73], v[166:169], v[212:215], v[70:73]
	v_mfma_f32_16x16x32_bf16 v[66:69], v[180:183], v[212:215], v[66:69]
	s_barrier
; #define PG8_STAGE(bufoff, gbase, voff) do { _Pragma("unroll") for (int _i = 0; _i < 2; ++_i) \
;         __builtin_amdgcn_global_load_lds((const unsigned*)((const char*)(gbase) + (voff)[_i]), (LAS unsigned*)(lds + (bufoff) + ldsw + _i * 8192), 16, 0, 0); } while (0)
; #define PG8_LDA(dst, b, h) do { _Pragma("unroll") for (int m = 0; m < 4; ++m) _Pragma("unroll") for (int k = 0; k < 2; ++k) dst[m][k] = *(const LAS bf16x8*)(lds + PG8_SA(b, h) + aoff + m * 2048 + k * 1024); } while (0)
; #define PG8_MMA(ai, bj, At, Bt) do { __builtin_amdgcn_s_setprio(1); _Pragma("unroll") for (int m = 0; m < 4; ++m) _Pragma("unroll") for (int n = 0; n < 2; ++n) _Pragma("unroll") for (int k = 0; k < 2; ++k) \
;         acc[ai][bj][m][n] = __builtin_amdgcn_mfma_f32_16x16x32_bf16(Bt[n][k], At[m][k], acc[ai][bj][m][n], 0, 0, 0); __builtin_amdgcn_s_setprio(0); } while (0)
; #define PG8_WAIT_V(n) asm volatile("s_waitcnt vmcnt(" #n ")" ::: "memory")
; #define PG8_WAIT_L(n) asm volatile("s_waitcnt lgkmcnt(" #n ")" ::: "memory")
; #define PG8_BAR __builtin_amdgcn_s_barrier()
; #define PG8_SCHED __builtin_amdgcn_sched_barrier(0)
; template <class Epi, class Sched, int LDA, int LDB, bool ALIGN_EPI = true>
; __device__ __forceinline__ void gemm_phase(LAS unsigned char* lds, const Gemm g, const Sched& S, const Epi& E, int wave) {
;     ...
;             PG8_LDA(At, 1, 1); PG8_STAGE(PG8_SB(1, 0), b3, voffB); PG8_STAGE(PG8_SB(1, 1), b3 + hstepB, voffB); PG8_STAGE(PG8_SA(1, 0), a3, voffA);
;             PG8_WAIT_V(8); PG8_WAIT_L(0); PG8_BAR; PG8_MMA(1, 0, At, B0); PG8_MMA(1, 1, At, B1); PG8_BAR; PG8_SCHED;
;         }
;         if constexpr (ALIGN_EPI) { if (wr == 0) PG8_BAR; }
	s_setprio 0
	s_add_i32 s14, s39, s47
	v_lshl_add_u64 v[140:141], v[140:141], 0, s[48:49]
	s_mov_b32 m0, s14
	ds_read_b128 v[184:187], v145 offset:49152
	ds_read_b128 v[188:191], v145 offset:50176
	ds_read_b128 v[192:195], v145 offset:51200
	ds_read_b128 v[196:199], v145 offset:52224
	ds_read_b128 v[200:203], v145 offset:53248
	ds_read_b128 v[204:207], v145 offset:54272
	ds_read_b128 v[208:211], v145 offset:55296
	ds_read_b128 v[212:215], v145 offset:56320
	global_load_lds_dwordx4 v[140:141], off
	s_add_i32 m0, s14, 0x2000
	s_add_u32 s12, s12, 0x84080
	v_lshl_add_u64 v[140:141], v[174:175], 0, s[48:49]
	s_addc_u32 s13, s13, 0
	s_add_i32 s14, s44, s47
	global_load_lds_dwordx4 v[140:141], off
	v_lshl_add_u64 v[140:141], s[12:13], 0, v[0:1]
	s_mov_b32 m0, s14
	s_nop 0
	global_load_lds_dwordx4 v[140:141], off
	v_lshl_add_u64 v[140:141], s[12:13], 0, v[134:135]
	s_add_i32 m0, s14, 0x2000
	s_nop 0
	global_load_lds_dwordx4 v[140:141], off
	v_lshl_add_u64 v[140:141], v[216:217], 0, s[48:49]
	s_mov_b32 m0, s26
	s_nop 0
	global_load_lds_dwordx4 v[140:141], off
	v_lshl_add_u64 v[140:141], v[218:219], 0, s[48:49]
	s_mov_b32 m0, s27
	s_nop 0
	global_load_lds_dwordx4 v[140:141], off
	s_waitcnt vmcnt(8)
	s_waitcnt lgkmcnt(0)
	s_setprio 1
	s_barrier
	v_mfma_f32_16x16x32_bf16 v[62:65], v[146:149], v[184:187], v[62:65]
	v_mfma_f32_16x16x32_bf16 v[58:61], v[154:157], v[184:187], v[58:61]
	v_mfma_f32_16x16x32_bf16 v[50:53], v[146:149], v[192:195], v[50:53]
	v_mfma_f32_16x16x32_bf16 v[42:45], v[154:157], v[192:195], v[42:45]
	v_mfma_f32_16x16x32_bf16 v[34:37], v[146:149], v[200:203], v[34:37]
	v_mfma_f32_16x16x32_bf16 v[26:29], v[154:157], v[200:203], v[26:29]
	v_mfma_f32_16x16x32_bf16 v[18:21], v[146:149], v[208:211], v[18:21]
	v_mfma_f32_16x16x32_bf16 v[10:13], v[154:157], v[208:211], v[10:13]
	v_mfma_f32_16x16x32_bf16 v[62:65], v[150:153], v[188:191], v[62:65]
	v_mfma_f32_16x16x32_bf16 v[58:61], v[158:161], v[188:191], v[58:61]
	v_mfma_f32_16x16x32_bf16 v[50:53], v[150:153], v[196:199], v[50:53]
	v_mfma_f32_16x16x32_bf16 v[42:45], v[158:161], v[196:199], v[42:45]
	v_mfma_f32_16x16x32_bf16 v[34:37], v[150:153], v[204:207], v[34:37]
	v_mfma_f32_16x16x32_bf16 v[26:29], v[158:161], v[204:207], v[26:29]
	v_mfma_f32_16x16x32_bf16 v[18:21], v[150:153], v[212:215], v[18:21]
	v_mfma_f32_16x16x32_bf16 v[10:13], v[158:161], v[212:215], v[10:13]
	v_mfma_f32_16x16x32_bf16 v[54:57], v[162:165], v[184:187], v[54:57]
	v_mfma_f32_16x16x32_bf16 v[46:49], v[170:173], v[184:187], v[46:49]
	v_mfma_f32_16x16x32_bf16 v[38:41], v[162:165], v[192:195], v[38:41]
	v_mfma_f32_16x16x32_bf16 v[30:33], v[170:173], v[192:195], v[30:33]
	v_mfma_f32_16x16x32_bf16 v[22:25], v[162:165], v[200:203], v[22:25]
	v_mfma_f32_16x16x32_bf16 v[14:17], v[170:173], v[200:203], v[14:17]
	v_mfma_f32_16x16x32_bf16 v[6:9], v[162:165], v[208:211], v[6:9]
	v_mfma_f32_16x16x32_bf16 v[2:5], v[170:173], v[208:211], v[2:5]
	v_mfma_f32_16x16x32_bf16 v[54:57], v[166:169], v[188:191], v[54:57]
	v_mfma_f32_16x16x32_bf16 v[46:49], v[180:183], v[188:191], v[46:49]
	v_mfma_f32_16x16x32_bf16 v[38:41], v[166:169], v[196:199], v[38:41]
	v_mfma_f32_16x16x32_bf16 v[30:33], v[180:183], v[196:199], v[30:33]
	v_mfma_f32_16x16x32_bf16 v[22:25], v[166:169], v[204:207], v[22:25]
	v_mfma_f32_16x16x32_bf16 v[14:17], v[180:183], v[204:207], v[14:17]
	v_mfma_f32_16x16x32_bf16 v[6:9], v[166:169], v[212:215], v[6:9]
	v_mfma_f32_16x16x32_bf16 v[2:5], v[180:183], v[212:215], v[2:5]
	s_barrier
	s_setprio 0
	s_add_i32 s38, s38, 2
	s_add_u32 s10, s10, 0x100
	s_addc_u32 s11, s11, 0
	s_add_u32 s36, s36, 0x100
	s_addc_u32 s37, s37, 0
	s_cmp_gt_u32 s38, 29
	s_cbranch_scc0 .LBB0_2415
	v_readlane_b32 s10, v252, 14
	v_readlane_b32 s11, v252, 15
	s_and_b64 vcc, exec, s[10:11]
	s_cbranch_vccz .LBB0_2418
	s_barrier

; #define PG8_STAGE(bufoff, gbase, voff) do { _Pragma("unroll") for (int _i = 0; _i < 2; ++_i) \
;         __builtin_amdgcn_global_load_lds((const unsigned*)((const char*)(gbase) + (voff)[_i]), (LAS unsigned*)(lds + (bufoff) + ldsw + _i * 8192), 16, 0, 0); } while (0)
; #define PG8_LDA(dst, b, h) do { _Pragma("unroll") for (int m = 0; m < 4; ++m) _Pragma("unroll") for (int k = 0; k < 2; ++k) dst[m][k] = *(const LAS bf16x8*)(lds + PG8_SA(b, h) + aoff + m * 2048 + k * 1024); } while (0)
; #define PG8_LDB(dst, b, h) do { _Pragma("unroll") for (int n = 0; n < 2; ++n) _Pragma("unroll") for (int k = 0; k < 2; ++k) dst[n][k] = *(const LAS bf16x8*)(lds + PG8_SB(b, h) + boff + n * 2048 + k * 1024); } while (0)
; #define PG8_MMA(ai, bj, At, Bt) do { __builtin_amdgcn_s_setprio(1); _Pragma("unroll") for (int m = 0; m < 4; ++m) _Pragma("unroll") for (int n = 0; n < 2; ++n) _Pragma("unroll") for (int k = 0; k < 2; ++k) \
;         acc[ai][bj][m][n] = __builtin_amdgcn_mfma_f32_16x16x32_bf16(Bt[n][k], At[m][k], acc[ai][bj][m][n], 0, 0, 0); __builtin_amdgcn_s_setprio(0); } while (0)
; #define PG8_WAIT_V(n) asm volatile("s_waitcnt vmcnt(" #n ")" ::: "memory")
; #define PG8_WAIT_L(n) asm volatile("s_waitcnt lgkmcnt(" #n ")" ::: "memory")
; #define PG8_BAR __builtin_amdgcn_s_barrier()
; template <class Epi, class Sched, int LDA, int LDB, bool ALIGN_EPI = true>
; __device__ __forceinline__ void gemm_phase(LAS unsigned char* lds, const Gemm g, const Sched& S, const Epi& E, int wave) {
;     ...
;         for (int t = 0; t < nt; t += 2) {
;             const bool last = (t == nt - 2);
;             const char* a1 = cA + (size_t)(t + 1) * kstep;
;             const char* a2 = last ? nA : cA + (size_t)(t + 2) * kstep; const char* b2 = last ? nB : cB + (size_t)(t + 2) * kstep;
;             const char* a3 = a2 + kstep; const char* b3 = b2 + kstep;
;             PG8_LDB(B0, 0, 0); PG8_LDB(B1, 0, 1); PG8_SCHED; PG8_LDA(At, 0, 0); PG8_STAGE(PG8_SA(1, 1), a1 + hstepA, voffA);
;             PG8_WAIT_V(8); PG8_WAIT_L(0); PG8_BAR; PG8_MMA(0, 0, At, B0); PG8_MMA(0, 1, At, B1); PG8_BAR; PG8_SCHED;
;             PG8_LDA(At, 0, 1); PG8_STAGE(PG8_SB(0, 0), b2, voffB); PG8_STAGE(PG8_SB(0, 1), b2 + hstepB, voffB); PG8_STAGE(PG8_SA(0, 0), a2, voffA);
;             PG8_WAIT_V(8); PG8_WAIT_L(0); PG8_BAR; PG8_MMA(1, 0, At, B0); PG8_MMA(1, 1, At, B1); PG8_BAR; PG8_SCHED;
.LBB0_2513:
	s_add_u32 s14, s12, 0xfff80080
	s_addc_u32 s15, s13, -1
	s_add_i32 s44, 0, 0x10000
	s_cmp_eq_u32 s39, 28
	s_cselect_b32 s17, s1, s15
	s_cselect_b32 s16, s3, s14
	v_add_u32_e32 v140, s44, v143
	s_cselect_b32 s15, s9, s38
	s_cselect_b32 s14, s8, s37
	s_add_i32 s46, 0, 0x14000
	ds_read_b128 v[146:149], v140
	ds_read_b128 v[150:153], v140 offset:1024
	ds_read_b128 v[154:157], v140 offset:2048
	ds_read_b128 v[158:161], v140 offset:3072
	v_add_u32_e32 v140, s46, v143
	ds_read_b128 v[162:165], v140
	ds_read_b128 v[166:169], v140 offset:1024
	ds_read_b128 v[170:173], v140 offset:2048
	ds_read_b128 v[180:183], v140 offset:3072
	v_lshl_add_u64 v[140:141], s[12:13], 0, v[136:137]
	s_add_i32 m0, s24, 0xc000
	ds_read_b128 v[184:187], v145
	ds_read_b128 v[188:191], v145 offset:1024
	ds_read_b128 v[192:195], v145 offset:2048
	ds_read_b128 v[196:199], v145 offset:3072
	ds_read_b128 v[200:203], v145 offset:4096
	ds_read_b128 v[204:207], v145 offset:5120
	ds_read_b128 v[208:211], v145 offset:6144
	ds_read_b128 v[212:215], v145 offset:7168
	global_load_lds_dwordx4 v[140:141], off
	v_lshl_add_u64 v[140:141], s[12:13], 0, v[138:139]
	s_add_i32 m0, s24, 0xe000
	s_nop 0
	global_load_lds_dwordx4 v[140:141], off
	s_waitcnt vmcnt(8)
	s_waitcnt lgkmcnt(0)
	s_setprio 1
	s_barrier
	v_mfma_f32_16x16x32_bf16 v[126:129], v[146:149], v[184:187], v[126:129]
	v_mfma_f32_16x16x32_bf16 v[122:125], v[154:157], v[184:187], v[122:125]
	v_mfma_f32_16x16x32_bf16 v[114:117], v[146:149], v[192:195], v[114:117]
	v_mfma_f32_16x16x32_bf16 v[106:109], v[154:157], v[192:195], v[106:109]
	v_mfma_f32_16x16x32_bf16 v[98:101], v[146:149], v[200:203], v[98:101]
	v_mfma_f32_16x16x32_bf16 v[90:93], v[154:157], v[200:203], v[90:93]
	v_mfma_f32_16x16x32_bf16 v[82:85], v[146:149], v[208:211], v[82:85]
	v_mfma_f32_16x16x32_bf16 v[74:77], v[154:157], v[208:211], v[74:77]
	v_mfma_f32_16x16x32_bf16 v[126:129], v[150:153], v[188:191], v[126:129]
	v_mfma_f32_16x16x32_bf16 v[122:125], v[158:161], v[188:191], v[122:125]
	v_mfma_f32_16x16x32_bf16 v[114:117], v[150:153], v[196:199], v[114:117]
	v_mfma_f32_16x16x32_bf16 v[106:109], v[158:161], v[196:199], v[106:109]
	v_mfma_f32_16x16x32_bf16 v[98:101], v[150:153], v[204:207], v[98:101]
	v_mfma_f32_16x16x32_bf16 v[90:93], v[158:161], v[204:207], v[90:93]
	v_mfma_f32_16x16x32_bf16 v[82:85], v[150:153], v[212:215], v[82:85]
	v_mfma_f32_16x16x32_bf16 v[74:77], v[158:161], v[212:215], v[74:77]
	v_mfma_f32_16x16x32_bf16 v[118:121], v[162:165], v[184:187], v[118:121]
	v_mfma_f32_16x16x32_bf16 v[110:113], v[170:173], v[184:187], v[110:113]
	v_mfma_f32_16x16x32_bf16 v[102:105], v[162:165], v[192:195], v[102:105]
	v_mfma_f32_16x16x32_bf16 v[94:97], v[170:173], v[192:195], v[94:97]
	v_mfma_f32_16x16x32_bf16 v[86:89], v[162:165], v[200:203], v[86:89]
	v_mfma_f32_16x16x32_bf16 v[78:81], v[170:173], v[200:203], v[78:81]
	v_mfma_f32_16x16x32_bf16 v[70:73], v[162:165], v[208:211], v[70:73]
	v_mfma_f32_16x16x32_bf16 v[66:69], v[170:173], v[208:211], v[66:69]
	v_mfma_f32_16x16x32_bf16 v[118:121], v[166:169], v[188:191], v[118:121]
	v_mfma_f32_16x16x32_bf16 v[110:113], v[180:183], v[188:191], v[110:113]
	v_mfma_f32_16x16x32_bf16 v[102:105], v[166:169], v[196:199], v[102:105]
	v_mfma_f32_16x16x32_bf16 v[94:97], v[180:183], v[196:199], v[94:97]
	v_mfma_f32_16x16x32_bf16 v[86:89], v[166:169], v[204:207], v[86:89]
	v_mfma_f32_16x16x32_bf16 v[78:81], v[180:183], v[204:207], v[78:81]
	v_mfma_f32_16x16x32_bf16 v[70:73], v[166:169], v[212:215], v[70:73]
	v_mfma_f32_16x16x32_bf16 v[66:69], v[180:183], v[212:215], v[66:69]
	s_barrier
	s_setprio 0
	s_add_i32 s44, s44, s47
	v_lshl_add_u64 v[140:141], s[14:15], 0, v[0:1]
	s_mov_b32 m0, s44
	ds_read_b128 v[184:187], v145 offset:16384
	ds_read_b128 v[188:191], v145 offset:17408
	ds_read_b128 v[192:195], v145 offset:18432
	ds_read_b128 v[196:199], v145 offset:19456
	ds_read_b128 v[200:203], v145 offset:20480
	ds_read_b128 v[204:207], v145 offset:21504
	ds_read_b128 v[208:211], v145 offset:22528
	ds_read_b128 v[212:215], v145 offset:23552
	global_load_lds_dwordx4 v[140:141], off
	s_add_i32 m0, s44, 0x2000
	s_add_u32 s44, s14, 0x84000
	v_lshl_add_u64 v[174:175], s[14:15], 0, v[134:135]
	s_addc_u32 s45, s15, 0
	s_add_i32 s46, s46, s47
	global_load_lds_dwordx4 v[174:175], off
	v_lshl_add_u64 v[216:217], s[44:45], 0, v[0:1]
	s_mov_b32 m0, s46
	v_lshl_add_u64 v[218:219], s[16:17], 0, v[132:133]
	global_load_lds_dwordx4 v[216:217], off
	v_lshl_add_u64 v[216:217], s[44:45], 0, v[134:135]
	s_add_i32 m0, s46, 0x2000
	s_nop 0
	global_load_lds_dwordx4 v[216:217], off
	v_lshl_add_u64 v[216:217], s[16:17], 0, v[130:131]
	s_mov_b32 m0, s24
	s_nop 0
	global_load_lds_dwordx4 v[216:217], off
	s_mov_b32 m0, s25
	s_nop 0
	global_load_lds_dwordx4 v[218:219], off
	s_waitcnt vmcnt(8)
	s_waitcnt lgkmcnt(0)
	s_setprio 1
	s_barrier
; #define PG8_STAGE(bufoff, gbase, voff) do { _Pragma("unroll") for (int _i = 0; _i < 2; ++_i) \
;         __builtin_amdgcn_global_load_lds((const unsigned*)((const char*)(gbase) + (voff)[_i]), (LAS unsigned*)(lds + (bufoff) + ldsw + _i * 8192), 16, 0, 0); } while (0)
; #define PG8_LDA(dst, b, h) do { _Pragma("unroll") for (int m = 0; m < 4; ++m) _Pragma("unroll") for (int k = 0; k < 2; ++k) dst[m][k] = *(const LAS bf16x8*)(lds + PG8_SA(b, h) + aoff + m * 2048 + k * 1024); } while (0)
; #define PG8_LDB(dst, b, h) do { _Pragma("unroll") for (int n = 0; n < 2; ++n) _Pragma("unroll") for (int k = 0; k < 2; ++k) dst[n][k] = *(const LAS bf16x8*)(lds + PG8_SB(b, h) + boff + n * 2048 + k * 1024); } while (0)
; #define PG8_MMA(ai, bj, At, Bt) do { __builtin_amdgcn_s_setprio(1); _Pragma("unroll") for (int m = 0; m < 4; ++m) _Pragma("unroll") for (int n = 0; n < 2; ++n) _Pragma("unroll") for (int k = 0; k < 2; ++k) \
;         acc[ai][bj][m][n] = __builtin_amdgcn_mfma_f32_16x16x32_bf16(Bt[n][k], At[m][k], acc[ai][bj][m][n], 0, 0, 0); __builtin_amdgcn_s_setprio(0); } while (0)
; #define PG8_WAIT_V(n) asm volatile("s_waitcnt vmcnt(" #n ")" ::: "memory")
; #define PG8_WAIT_L(n) asm volatile("s_waitcnt lgkmcnt(" #n ")" ::: "memory")
; #define PG8_BAR __builtin_amdgcn_s_barrier()
; #define PG8_SCHED __builtin_amdgcn_sched_barrier(0)
; template <class Epi, class Sched, int LDA, int LDB, bool ALIGN_EPI = true>
; __device__ __forceinline__ void gemm_phase(LAS unsigned char* lds, const Gemm g, const Sched& S, const Epi& E, int wave) {
;     ...
;             PG8_WAIT_V(8); PG8_WAIT_L(0); PG8_BAR; PG8_MMA(1, 0, At, B0); PG8_MMA(1, 1, At, B1); PG8_BAR; PG8_SCHED;
;             PG8_LDB(B0, 1, 0); PG8_LDB(B1, 1, 1); PG8_SCHED; PG8_LDA(At, 1, 0); PG8_STAGE(PG8_SA(0, 1), a2 + hstepA, voffA);
;             PG8_WAIT_V(8); PG8_WAIT_L(0); PG8_BAR; PG8_MMA(0, 0, At, B0); PG8_MMA(0, 1, At, B1); PG8_BAR; PG8_SCHED;
	v_mfma_f32_16x16x32_bf16 v[62:65], v[146:149], v[184:187], v[62:65]
	v_mfma_f32_16x16x32_bf16 v[58:61], v[154:157], v[184:187], v[58:61]
	v_mfma_f32_16x16x32_bf16 v[50:53], v[146:149], v[192:195], v[50:53]
	v_mfma_f32_16x16x32_bf16 v[42:45], v[154:157], v[192:195], v[42:45]
	v_mfma_f32_16x16x32_bf16 v[34:37], v[146:149], v[200:203], v[34:37]
	v_mfma_f32_16x16x32_bf16 v[26:29], v[154:157], v[200:203], v[26:29]
	v_mfma_f32_16x16x32_bf16 v[18:21], v[146:149], v[208:211], v[18:21]
	v_mfma_f32_16x16x32_bf16 v[10:13], v[154:157], v[208:211], v[10:13]
	v_mfma_f32_16x16x32_bf16 v[62:65], v[150:153], v[188:191], v[62:65]
	v_mfma_f32_16x16x32_bf16 v[58:61], v[158:161], v[188:191], v[58:61]
	v_mfma_f32_16x16x32_bf16 v[50:53], v[150:153], v[196:199], v[50:53]
	v_mfma_f32_16x16x32_bf16 v[42:45], v[158:161], v[196:199], v[42:45]
	v_mfma_f32_16x16x32_bf16 v[34:37], v[150:153], v[204:207], v[34:37]
	v_mfma_f32_16x16x32_bf16 v[26:29], v[158:161], v[204:207], v[26:29]
	v_mfma_f32_16x16x32_bf16 v[18:21], v[150:153], v[212:215], v[18:21]
	v_mfma_f32_16x16x32_bf16 v[10:13], v[158:161], v[212:215], v[10:13]
	v_mfma_f32_16x16x32_bf16 v[54:57], v[162:165], v[184:187], v[54:57]
	v_mfma_f32_16x16x32_bf16 v[46:49], v[170:173], v[184:187], v[46:49]
	v_mfma_f32_16x16x32_bf16 v[38:41], v[162:165], v[192:195], v[38:41]
	v_mfma_f32_16x16x32_bf16 v[30:33], v[170:173], v[192:195], v[30:33]
	v_mfma_f32_16x16x32_bf16 v[22:25], v[162:165], v[200:203], v[22:25]
	v_mfma_f32_16x16x32_bf16 v[14:17], v[170:173], v[200:203], v[14:17]
	v_mfma_f32_16x16x32_bf16 v[6:9], v[162:165], v[208:211], v[6:9]
	v_mfma_f32_16x16x32_bf16 v[2:5], v[170:173], v[208:211], v[2:5]
	v_mfma_f32_16x16x32_bf16 v[54:57], v[166:169], v[188:191], v[54:57]
	v_mfma_f32_16x16x32_bf16 v[46:49], v[180:183], v[188:191], v[46:49]
	v_mfma_f32_16x16x32_bf16 v[38:41], v[166:169], v[196:199], v[38:41]
	v_mfma_f32_16x16x32_bf16 v[30:33], v[180:183], v[196:199], v[30:33]
	v_mfma_f32_16x16x32_bf16 v[22:25], v[166:169], v[204:207], v[22:25]
	v_mfma_f32_16x16x32_bf16 v[14:17], v[180:183], v[204:207], v[14:17]
	v_mfma_f32_16x16x32_bf16 v[6:9], v[166:169], v[212:215], v[6:9]
	v_mfma_f32_16x16x32_bf16 v[2:5], v[180:183], v[212:215], v[2:5]
	s_barrier
	s_setprio 0
	s_add_i32 s44, 0, 0x18000
	s_add_i32 s45, 0, 0x1c000
	v_add_u32_e32 v158, s44, v143
	v_add_u32_e32 v180, s45, v143
	ds_read_b128 v[146:149], v158
	ds_read_b128 v[150:153], v158 offset:1024
	ds_read_b128 v[154:157], v158 offset:2048
	ds_read_b128 v[158:161], v158 offset:3072
	ds_read_b128 v[162:165], v180
	ds_read_b128 v[166:169], v180 offset:1024
	ds_read_b128 v[170:173], v180 offset:2048
	ds_read_b128 v[180:183], v180 offset:3072
	s_add_u32 s16, s16, 0x80000
	s_addc_u32 s17, s17, 0
	s_mov_b32 m0, s26
	v_lshl_add_u64 v[220:221], s[16:17], 0, v[130:131]
	ds_read_b128 v[184:187], v145 offset:32768
	ds_read_b128 v[188:191], v145 offset:33792
	ds_read_b128 v[192:195], v145 offset:34816
	ds_read_b128 v[196:199], v145 offset:35840
	ds_read_b128 v[200:203], v145 offset:36864
	ds_read_b128 v[204:207], v145 offset:37888
	ds_read_b128 v[208:211], v145 offset:38912
	ds_read_b128 v[212:215], v145 offset:39936
	global_load_lds_dwordx4 v[220:221], off
	v_lshl_add_u64 v[220:221], s[16:17], 0, v[132:133]
	s_mov_b32 m0, s27
	s_nop 0
	global_load_lds_dwordx4 v[220:221], off
	s_waitcnt vmcnt(8)
	s_waitcnt lgkmcnt(0)
	s_setprio 1
	s_barrier
	v_mfma_f32_16x16x32_bf16 v[126:129], v[146:149], v[184:187], v[126:129]
	v_mfma_f32_16x16x32_bf16 v[122:125], v[154:157], v[184:187], v[122:125]
	v_mfma_f32_16x16x32_bf16 v[114:117], v[146:149], v[192:195], v[114:117]
	v_mfma_f32_16x16x32_bf16 v[106:109], v[154:157], v[192:195], v[106:109]
	v_mfma_f32_16x16x32_bf16 v[98:101], v[146:149], v[200:203], v[98:101]
	v_mfma_f32_16x16x32_bf16 v[90:93], v[154:157], v[200:203], v[90:93]
	v_mfma_f32_16x16x32_bf16 v[82:85], v[146:149], v[208:211], v[82:85]
	v_mfma_f32_16x16x32_bf16 v[74:77], v[154:157], v[208:211], v[74:77]
	v_mfma_f32_16x16x32_bf16 v[126:129], v[150:153], v[188:191], v[126:129]
	v_mfma_f32_16x16x32_bf16 v[122:125], v[158:161], v[188:191], v[122:125]
	v_mfma_f32_16x16x32_bf16 v[114:117], v[150:153], v[196:199], v[114:117]
	v_mfma_f32_16x16x32_bf16 v[106:109], v[158:161], v[196:199], v[106:109]
	v_mfma_f32_16x16x32_bf16 v[98:101], v[150:153], v[204:207], v[98:101]
	v_mfma_f32_16x16x32_bf16 v[90:93], v[158:161], v[204:207], v[90:93]
	v_mfma_f32_16x16x32_bf16 v[82:85], v[150:153], v[212:215], v[82:85]
	v_mfma_f32_16x16x32_bf16 v[74:77], v[158:161], v[212:215], v[74:77]
	v_mfma_f32_16x16x32_bf16 v[118:121], v[162:165], v[184:187], v[118:121]
	v_mfma_f32_16x16x32_bf16 v[110:113], v[170:173], v[184:187], v[110:113]
	v_mfma_f32_16x16x32_bf16 v[102:105], v[162:165], v[192:195], v[102:105]
	v_mfma_f32_16x16x32_bf16 v[94:97], v[170:173], v[192:195], v[94:97]
	v_mfma_f32_16x16x32_bf16 v[86:89], v[162:165], v[200:203], v[86:89]
	v_mfma_f32_16x16x32_bf16 v[78:81], v[170:173], v[200:203], v[78:81]
	v_mfma_f32_16x16x32_bf16 v[70:73], v[162:165], v[208:211], v[70:73]
	v_mfma_f32_16x16x32_bf16 v[66:69], v[170:173], v[208:211], v[66:69]
	v_mfma_f32_16x16x32_bf16 v[118:121], v[166:169], v[188:191], v[118:121]
	v_mfma_f32_16x16x32_bf16 v[110:113], v[180:183], v[188:191], v[110:113]
	v_mfma_f32_16x16x32_bf16 v[102:105], v[166:169], v[196:199], v[102:105]
	v_mfma_f32_16x16x32_bf16 v[94:97], v[180:183], v[196:199], v[94:97]
	v_mfma_f32_16x16x32_bf16 v[86:89], v[166:169], v[204:207], v[86:89]
	v_mfma_f32_16x16x32_bf16 v[78:81], v[180:183], v[204:207], v[78:81]
	v_mfma_f32_16x16x32_bf16 v[70:73], v[166:169], v[212:215], v[70:73]
	v_mfma_f32_16x16x32_bf16 v[66:69], v[180:183], v[212:215], v[66:69]
	s_barrier
; #define PG8_STAGE(bufoff, gbase, voff) do { _Pragma("unroll") for (int _i = 0; _i < 2; ++_i) \
;         __builtin_amdgcn_global_load_lds((const unsigned*)((const char*)(gbase) + (voff)[_i]), (LAS unsigned*)(lds + (bufoff) + ldsw + _i * 8192), 16, 0, 0); } while (0)
; #define PG8_LDA(dst, b, h) do { _Pragma("unroll") for (int m = 0; m < 4; ++m) _Pragma("unroll") for (int k = 0; k < 2; ++k) dst[m][k] = *(const LAS bf16x8*)(lds + PG8_SA(b, h) + aoff + m * 2048 + k * 1024); } while (0)
; #define PG8_MMA(ai, bj, At, Bt) do { __builtin_amdgcn_s_setprio(1); _Pragma("unroll") for (int m = 0; m < 4; ++m) _Pragma("unroll") for (int n = 0; n < 2; ++n) _Pragma("unroll") for (int k = 0; k < 2; ++k) \
;         acc[ai][bj][m][n] = __builtin_amdgcn_mfma_f32_16x16x32_bf16(Bt[n][k], At[m][k], acc[ai][bj][m][n], 0, 0, 0); __builtin_amdgcn_s_setprio(0); } while (0)
; #define PG8_WAIT_V(n) asm volatile("s_waitcnt vmcnt(" #n ")" ::: "memory")
; #define PG8_WAIT_L(n) asm volatile("s_waitcnt lgkmcnt(" #n ")" ::: "memory")
; #define PG8_BAR __builtin_amdgcn_s_barrier()
; #define PG8_SCHED __builtin_amdgcn_sched_barrier(0)
; template <class Epi, class Sched, int LDA, int LDB, bool ALIGN_EPI = true>
; __device__ __forceinline__ void gemm_phase(LAS unsigned char* lds, const Gemm g, const Sched& S, const Epi& E, int wave) {
;     ...
;             PG8_LDA(At, 1, 1); PG8_STAGE(PG8_SB(1, 0), b3, voffB); PG8_STAGE(PG8_SB(1, 1), b3 + hstepB, voffB); PG8_STAGE(PG8_SA(1, 0), a3, voffA);
;             PG8_WAIT_V(8); PG8_WAIT_L(0); PG8_BAR; PG8_MMA(1, 0, At, B0); PG8_MMA(1, 1, At, B1); PG8_BAR; PG8_SCHED;
;         }
;         if constexpr (ALIGN_EPI) { if (wr == 0) PG8_BAR; }
	s_setprio 0
	s_add_i32 s16, s44, s47
	v_lshl_add_u64 v[140:141], v[140:141], 0, s[72:73]
	s_mov_b32 m0, s16
	ds_read_b128 v[184:187], v145 offset:49152
	ds_read_b128 v[188:191], v145 offset:50176
	ds_read_b128 v[192:195], v145 offset:51200
	ds_read_b128 v[196:199], v145 offset:52224
	ds_read_b128 v[200:203], v145 offset:53248
	ds_read_b128 v[204:207], v145 offset:54272
	ds_read_b128 v[208:211], v145 offset:55296
	ds_read_b128 v[212:215], v145 offset:56320
	global_load_lds_dwordx4 v[140:141], off
	s_add_i32 m0, s16, 0x2000
	s_add_u32 s14, s14, 0x84080
	v_lshl_add_u64 v[140:141], v[174:175], 0, s[72:73]
	s_addc_u32 s15, s15, 0
	s_add_i32 s16, s45, s47
	global_load_lds_dwordx4 v[140:141], off
	v_lshl_add_u64 v[140:141], s[14:15], 0, v[0:1]
	s_mov_b32 m0, s16
	s_nop 0
	global_load_lds_dwordx4 v[140:141], off
	v_lshl_add_u64 v[140:141], s[14:15], 0, v[134:135]
	s_add_i32 m0, s16, 0x2000
	s_nop 0
	global_load_lds_dwordx4 v[140:141], off
	v_lshl_add_u64 v[140:141], v[216:217], 0, s[72:73]
	s_mov_b32 m0, s28
	s_nop 0
	global_load_lds_dwordx4 v[140:141], off
	v_lshl_add_u64 v[140:141], v[218:219], 0, s[72:73]
	s_mov_b32 m0, s29
	s_nop 0
	global_load_lds_dwordx4 v[140:141], off
	s_waitcnt vmcnt(8)
	s_waitcnt lgkmcnt(0)
	s_setprio 1
	s_barrier
	v_mfma_f32_16x16x32_bf16 v[62:65], v[146:149], v[184:187], v[62:65]
	v_mfma_f32_16x16x32_bf16 v[58:61], v[154:157], v[184:187], v[58:61]
	v_mfma_f32_16x16x32_bf16 v[50:53], v[146:149], v[192:195], v[50:53]
	v_mfma_f32_16x16x32_bf16 v[42:45], v[154:157], v[192:195], v[42:45]
	v_mfma_f32_16x16x32_bf16 v[34:37], v[146:149], v[200:203], v[34:37]
	v_mfma_f32_16x16x32_bf16 v[26:29], v[154:157], v[200:203], v[26:29]
	v_mfma_f32_16x16x32_bf16 v[18:21], v[146:149], v[208:211], v[18:21]
	v_mfma_f32_16x16x32_bf16 v[10:13], v[154:157], v[208:211], v[10:13]
	v_mfma_f32_16x16x32_bf16 v[62:65], v[150:153], v[188:191], v[62:65]
	v_mfma_f32_16x16x32_bf16 v[58:61], v[158:161], v[188:191], v[58:61]
	v_mfma_f32_16x16x32_bf16 v[50:53], v[150:153], v[196:199], v[50:53]
	v_mfma_f32_16x16x32_bf16 v[42:45], v[158:161], v[196:199], v[42:45]
	v_mfma_f32_16x16x32_bf16 v[34:37], v[150:153], v[204:207], v[34:37]
	v_mfma_f32_16x16x32_bf16 v[26:29], v[158:161], v[204:207], v[26:29]
	v_mfma_f32_16x16x32_bf16 v[18:21], v[150:153], v[212:215], v[18:21]
	v_mfma_f32_16x16x32_bf16 v[10:13], v[158:161], v[212:215], v[10:13]
	v_mfma_f32_16x16x32_bf16 v[54:57], v[162:165], v[184:187], v[54:57]
	v_mfma_f32_16x16x32_bf16 v[46:49], v[170:173], v[184:187], v[46:49]
	v_mfma_f32_16x16x32_bf16 v[38:41], v[162:165], v[192:195], v[38:41]
	v_mfma_f32_16x16x32_bf16 v[30:33], v[170:173], v[192:195], v[30:33]
	v_mfma_f32_16x16x32_bf16 v[22:25], v[162:165], v[200:203], v[22:25]
	v_mfma_f32_16x16x32_bf16 v[14:17], v[170:173], v[200:203], v[14:17]
	v_mfma_f32_16x16x32_bf16 v[6:9], v[162:165], v[208:211], v[6:9]
	v_mfma_f32_16x16x32_bf16 v[2:5], v[170:173], v[208:211], v[2:5]
	v_mfma_f32_16x16x32_bf16 v[54:57], v[166:169], v[188:191], v[54:57]
	v_mfma_f32_16x16x32_bf16 v[46:49], v[180:183], v[188:191], v[46:49]
	v_mfma_f32_16x16x32_bf16 v[38:41], v[166:169], v[196:199], v[38:41]
	v_mfma_f32_16x16x32_bf16 v[30:33], v[180:183], v[196:199], v[30:33]
	v_mfma_f32_16x16x32_bf16 v[22:25], v[166:169], v[204:207], v[22:25]
	v_mfma_f32_16x16x32_bf16 v[14:17], v[180:183], v[204:207], v[14:17]
	v_mfma_f32_16x16x32_bf16 v[6:9], v[166:169], v[212:215], v[6:9]
	v_mfma_f32_16x16x32_bf16 v[2:5], v[180:183], v[212:215], v[2:5]
	s_barrier
	s_setprio 0
	s_add_i32 s39, s39, 2
	s_add_u32 s12, s12, 0x100
	s_addc_u32 s13, s13, 0
	s_add_u32 s37, s37, 0x100
	s_addc_u32 s38, s38, 0
	s_cmp_gt_u32 s39, 29
	s_cbranch_scc0 .LBB0_2513
	v_readlane_b32 s12, v252, 14
	v_readlane_b32 s13, v252, 15
	s_and_b64 vcc, exec, s[12:13]
	s_cbranch_vccz .LBB0_2516
	s_barrier

; #define PG8_STAGE(bufoff, gbase, voff) do { _Pragma("unroll") for (int _i = 0; _i < 2; ++_i) \
;         __builtin_amdgcn_global_load_lds((const unsigned*)((const char*)(gbase) + (voff)[_i]), (LAS unsigned*)(lds + (bufoff) + ldsw + _i * 8192), 16, 0, 0); } while (0)
; #define PG8_LDA(dst, b, h) do { _Pragma("unroll") for (int m = 0; m < 4; ++m) _Pragma("unroll") for (int k = 0; k < 2; ++k) dst[m][k] = *(const LAS bf16x8*)(lds + PG8_SA(b, h) + aoff + m * 2048 + k * 1024); } while (0)
; #define PG8_LDB(dst, b, h) do { _Pragma("unroll") for (int n = 0; n < 2; ++n) _Pragma("unroll") for (int k = 0; k < 2; ++k) dst[n][k] = *(const LAS bf16x8*)(lds + PG8_SB(b, h) + boff + n * 2048 + k * 1024); } while (0)
; #define PG8_MMA(ai, bj, At, Bt) do { __builtin_amdgcn_s_setprio(1); _Pragma("unroll") for (int m = 0; m < 4; ++m) _Pragma("unroll") for (int n = 0; n < 2; ++n) _Pragma("unroll") for (int k = 0; k < 2; ++k) \
;         acc[ai][bj][m][n] = __builtin_amdgcn_mfma_f32_16x16x32_bf16(Bt[n][k], At[m][k], acc[ai][bj][m][n], 0, 0, 0); __builtin_amdgcn_s_setprio(0); } while (0)
; #define PG8_WAIT_V(n) asm volatile("s_waitcnt vmcnt(" #n ")" ::: "memory")
; #define PG8_WAIT_L(n) asm volatile("s_waitcnt lgkmcnt(" #n ")" ::: "memory")
; #define PG8_BAR __builtin_amdgcn_s_barrier()
; #define PG8_SCHED __builtin_amdgcn_sched_barrier(0)
; template <class Epi, class Sched, int LDA, int LDB, bool ALIGN_EPI = true>
; __device__ __forceinline__ void gemm_phase(LAS unsigned char* lds, const Gemm g, const Sched& S, const Epi& E, int wave) {
;     ...
;             const bool last = (t == nt - 2);
;             const char* a1 = cA + (size_t)(t + 1) * kstep;
;             const char* a2 = last ? nA : cA + (size_t)(t + 2) * kstep; const char* b2 = last ? nB : cB + (size_t)(t + 2) * kstep;
;             const char* a3 = a2 + kstep; const char* b3 = b2 + kstep;
;             PG8_LDB(B0, 0, 0); PG8_LDB(B1, 0, 1); PG8_SCHED; PG8_LDA(At, 0, 0); PG8_STAGE(PG8_SA(1, 1), a1 + hstepA, voffA);
;             PG8_WAIT_V(8); PG8_WAIT_L(0); PG8_BAR; PG8_MMA(0, 0, At, B0); PG8_MMA(0, 1, At, B1); PG8_BAR; PG8_SCHED;
;             PG8_LDA(At, 0, 1); PG8_STAGE(PG8_SB(0, 0), b2, voffB); PG8_STAGE(PG8_SB(0, 1), b2 + hstepB, voffB); PG8_STAGE(PG8_SA(0, 0), a2, voffA);
;             PG8_WAIT_V(8); PG8_WAIT_L(0); PG8_BAR; PG8_MMA(1, 0, At, B0); PG8_MMA(1, 1, At, B1); PG8_BAR; PG8_SCHED;
.LBB0_2551:
	s_add_u32 s2, s0, 0x100
	s_addc_u32 s3, s1, 0
	s_add_i32 s50, 0, 0x10000
	s_cmp_eq_u32 s49, 8
	s_cselect_b32 s17, s11, s3
	s_cselect_b32 s16, s10, s2
	v_add_u32_e32 v0, s50, v154
	s_cselect_b32 s15, s13, s47
	s_cselect_b32 s14, s12, s46
	s_add_i32 s51, 0, 0x14000
	ds_read_b128 v[130:133], v0
	ds_read_b128 v[148:151], v0 offset:1024
	ds_read_b128 v[158:161], v0 offset:2048
	ds_read_b128 v[162:165], v0 offset:3072
	v_add_u32_e32 v0, s51, v154
	ds_read_b128 v[166:169], v0
	ds_read_b128 v[170:173], v0 offset:1024
	ds_read_b128 v[180:183], v0 offset:2048
	ds_read_b128 v[184:187], v0 offset:3072
	v_lshl_add_u64 v[152:153], s[0:1], 0, v[144:145]
	s_add_i32 m0, s28, 0xc000
	ds_read_b128 v[188:191], v156
	ds_read_b128 v[192:195], v156 offset:1024
	ds_read_b128 v[196:199], v156 offset:2048
	ds_read_b128 v[200:203], v156 offset:3072
	ds_read_b128 v[204:207], v156 offset:4096
	ds_read_b128 v[208:211], v156 offset:5120
	ds_read_b128 v[212:215], v156 offset:6144
	ds_read_b128 v[216:219], v156 offset:7168
	global_load_lds_dwordx4 v[152:153], off
	v_lshl_add_u64 v[152:153], s[0:1], 0, v[146:147]
	s_add_i32 m0, s28, 0xe000
	s_nop 0
	global_load_lds_dwordx4 v[152:153], off
	s_waitcnt vmcnt(8)
	s_waitcnt lgkmcnt(0)
	s_setprio 1
	s_barrier
	v_mfma_f32_16x16x32_bf16 v[126:129], v[130:133], v[188:191], v[126:129]
	v_mfma_f32_16x16x32_bf16 v[122:125], v[158:161], v[188:191], v[122:125]
	v_mfma_f32_16x16x32_bf16 v[118:121], v[130:133], v[196:199], v[118:121]
	v_mfma_f32_16x16x32_bf16 v[114:117], v[158:161], v[196:199], v[114:117]
	v_mfma_f32_16x16x32_bf16 v[110:113], v[130:133], v[204:207], v[110:113]
	v_mfma_f32_16x16x32_bf16 v[106:109], v[158:161], v[204:207], v[106:109]
	v_mfma_f32_16x16x32_bf16 v[102:105], v[130:133], v[212:215], v[102:105]
	v_mfma_f32_16x16x32_bf16 v[98:101], v[158:161], v[212:215], v[98:101]
	v_mfma_f32_16x16x32_bf16 v[126:129], v[148:151], v[192:195], v[126:129]
	v_mfma_f32_16x16x32_bf16 v[122:125], v[162:165], v[192:195], v[122:125]
	v_mfma_f32_16x16x32_bf16 v[118:121], v[148:151], v[200:203], v[118:121]
	v_mfma_f32_16x16x32_bf16 v[114:117], v[162:165], v[200:203], v[114:117]
	v_mfma_f32_16x16x32_bf16 v[110:113], v[148:151], v[208:211], v[110:113]
	v_mfma_f32_16x16x32_bf16 v[106:109], v[162:165], v[208:211], v[106:109]
	v_mfma_f32_16x16x32_bf16 v[102:105], v[148:151], v[216:219], v[102:105]
	v_mfma_f32_16x16x32_bf16 v[98:101], v[162:165], v[216:219], v[98:101]
	v_mfma_f32_16x16x32_bf16 v[62:65], v[166:169], v[188:191], v[62:65]
	v_mfma_f32_16x16x32_bf16 v[58:61], v[180:183], v[188:191], v[58:61]
	v_mfma_f32_16x16x32_bf16 v[54:57], v[166:169], v[196:199], v[54:57]
	v_mfma_f32_16x16x32_bf16 v[50:53], v[180:183], v[196:199], v[50:53]
	v_mfma_f32_16x16x32_bf16 v[46:49], v[166:169], v[204:207], v[46:49]
	v_mfma_f32_16x16x32_bf16 v[42:45], v[180:183], v[204:207], v[42:45]
	v_mfma_f32_16x16x32_bf16 v[38:41], v[166:169], v[212:215], v[38:41]
	v_mfma_f32_16x16x32_bf16 v[34:37], v[180:183], v[212:215], v[34:37]
	v_mfma_f32_16x16x32_bf16 v[62:65], v[170:173], v[192:195], v[62:65]
	v_mfma_f32_16x16x32_bf16 v[58:61], v[184:187], v[192:195], v[58:61]
	v_mfma_f32_16x16x32_bf16 v[54:57], v[170:173], v[200:203], v[54:57]
	v_mfma_f32_16x16x32_bf16 v[50:53], v[184:187], v[200:203], v[50:53]
	v_mfma_f32_16x16x32_bf16 v[46:49], v[170:173], v[208:211], v[46:49]
	v_mfma_f32_16x16x32_bf16 v[42:45], v[184:187], v[208:211], v[42:45]
	v_mfma_f32_16x16x32_bf16 v[38:41], v[170:173], v[216:219], v[38:41]
	v_mfma_f32_16x16x32_bf16 v[34:37], v[184:187], v[216:219], v[34:37]
	s_barrier
	s_setprio 0
	s_add_i32 s0, s50, s54
	v_lshl_add_u64 v[152:153], s[14:15], 0, v[136:137]
	s_mov_b32 m0, s0
	ds_read_b128 v[188:191], v156 offset:16384
	ds_read_b128 v[192:195], v156 offset:17408
	ds_read_b128 v[196:199], v156 offset:18432
	ds_read_b128 v[200:203], v156 offset:19456
	ds_read_b128 v[204:207], v156 offset:20480
	ds_read_b128 v[208:211], v156 offset:21504
	ds_read_b128 v[212:215], v156 offset:22528
	ds_read_b128 v[216:219], v156 offset:23552
	global_load_lds_dwordx4 v[152:153], off
	s_add_i32 m0, s0, 0x2000
	s_add_u32 s0, s14, 0x30000
	v_lshl_add_u64 v[174:175], s[14:15], 0, v[140:141]
	s_addc_u32 s1, s15, 0
	s_add_i32 s50, s51, s54
	global_load_lds_dwordx4 v[174:175], off
	v_lshl_add_u64 v[220:221], s[0:1], 0, v[136:137]
	s_mov_b32 m0, s50
	v_lshl_add_u64 v[222:223], s[16:17], 0, v[138:139]
	global_load_lds_dwordx4 v[220:221], off
	v_lshl_add_u64 v[220:221], s[0:1], 0, v[140:141]
	s_add_i32 m0, s50, 0x2000
	s_nop 0
	global_load_lds_dwordx4 v[220:221], off
	v_lshl_add_u64 v[220:221], s[16:17], 0, v[134:135]
	s_mov_b32 m0, s28
	s_nop 0
	global_load_lds_dwordx4 v[220:221], off
	s_mov_b32 m0, s29
	s_nop 0
	global_load_lds_dwordx4 v[222:223], off
	s_waitcnt vmcnt(8)
	s_waitcnt lgkmcnt(0)
	s_setprio 1
	s_barrier
; #define PG8_STAGE(bufoff, gbase, voff) do { _Pragma("unroll") for (int _i = 0; _i < 2; ++_i) \
;         __builtin_amdgcn_global_load_lds((const unsigned*)((const char*)(gbase) + (voff)[_i]), (LAS unsigned*)(lds + (bufoff) + ldsw + _i * 8192), 16, 0, 0); } while (0)
; #define PG8_LDA(dst, b, h) do { _Pragma("unroll") for (int m = 0; m < 4; ++m) _Pragma("unroll") for (int k = 0; k < 2; ++k) dst[m][k] = *(const LAS bf16x8*)(lds + PG8_SA(b, h) + aoff + m * 2048 + k * 1024); } while (0)
; #define PG8_LDB(dst, b, h) do { _Pragma("unroll") for (int n = 0; n < 2; ++n) _Pragma("unroll") for (int k = 0; k < 2; ++k) dst[n][k] = *(const LAS bf16x8*)(lds + PG8_SB(b, h) + boff + n * 2048 + k * 1024); } while (0)
; #define PG8_MMA(ai, bj, At, Bt) do { __builtin_amdgcn_s_setprio(1); _Pragma("unroll") for (int m = 0; m < 4; ++m) _Pragma("unroll") for (int n = 0; n < 2; ++n) _Pragma("unroll") for (int k = 0; k < 2; ++k) \
;         acc[ai][bj][m][n] = __builtin_amdgcn_mfma_f32_16x16x32_bf16(Bt[n][k], At[m][k], acc[ai][bj][m][n], 0, 0, 0); __builtin_amdgcn_s_setprio(0); } while (0)
; #define PG8_WAIT_V(n) asm volatile("s_waitcnt vmcnt(" #n ")" ::: "memory")
; #define PG8_WAIT_L(n) asm volatile("s_waitcnt lgkmcnt(" #n ")" ::: "memory")
; #define PG8_BAR __builtin_amdgcn_s_barrier()
; #define PG8_SCHED __builtin_amdgcn_sched_barrier(0)
; template <class Epi, class Sched, int LDA, int LDB, bool ALIGN_EPI = true>
; __device__ __forceinline__ void gemm_phase(LAS unsigned char* lds, const Gemm g, const Sched& S, const Epi& E, int wave) {
;     ...
;             PG8_WAIT_V(8); PG8_WAIT_L(0); PG8_BAR; PG8_MMA(1, 0, At, B0); PG8_MMA(1, 1, At, B1); PG8_BAR; PG8_SCHED;
;             PG8_LDB(B0, 1, 0); PG8_LDB(B1, 1, 1); PG8_SCHED; PG8_LDA(At, 1, 0); PG8_STAGE(PG8_SA(0, 1), a2 + hstepA, voffA);
;             PG8_WAIT_V(8); PG8_WAIT_L(0); PG8_BAR; PG8_MMA(0, 0, At, B0); PG8_MMA(0, 1, At, B1); PG8_BAR; PG8_SCHED;
	v_mfma_f32_16x16x32_bf16 v[94:97], v[130:133], v[188:191], v[94:97]
	v_mfma_f32_16x16x32_bf16 v[90:93], v[158:161], v[188:191], v[90:93]
	v_mfma_f32_16x16x32_bf16 v[86:89], v[130:133], v[196:199], v[86:89]
	v_mfma_f32_16x16x32_bf16 v[82:85], v[158:161], v[196:199], v[82:85]
	v_mfma_f32_16x16x32_bf16 v[78:81], v[130:133], v[204:207], v[78:81]
	v_mfma_f32_16x16x32_bf16 v[74:77], v[158:161], v[204:207], v[74:77]
	v_mfma_f32_16x16x32_bf16 v[70:73], v[130:133], v[212:215], v[70:73]
	v_mfma_f32_16x16x32_bf16 v[66:69], v[158:161], v[212:215], v[66:69]
	v_mfma_f32_16x16x32_bf16 v[94:97], v[148:151], v[192:195], v[94:97]
	v_mfma_f32_16x16x32_bf16 v[90:93], v[162:165], v[192:195], v[90:93]
	v_mfma_f32_16x16x32_bf16 v[86:89], v[148:151], v[200:203], v[86:89]
	v_mfma_f32_16x16x32_bf16 v[82:85], v[162:165], v[200:203], v[82:85]
	v_mfma_f32_16x16x32_bf16 v[78:81], v[148:151], v[208:211], v[78:81]
	v_mfma_f32_16x16x32_bf16 v[74:77], v[162:165], v[208:211], v[74:77]
	v_mfma_f32_16x16x32_bf16 v[70:73], v[148:151], v[216:219], v[70:73]
	v_mfma_f32_16x16x32_bf16 v[66:69], v[162:165], v[216:219], v[66:69]
	v_mfma_f32_16x16x32_bf16 v[30:33], v[166:169], v[188:191], v[30:33]
	v_mfma_f32_16x16x32_bf16 v[26:29], v[180:183], v[188:191], v[26:29]
	v_mfma_f32_16x16x32_bf16 v[22:25], v[166:169], v[196:199], v[22:25]
	v_mfma_f32_16x16x32_bf16 v[18:21], v[180:183], v[196:199], v[18:21]
	v_mfma_f32_16x16x32_bf16 v[14:17], v[166:169], v[204:207], v[14:17]
	v_mfma_f32_16x16x32_bf16 v[10:13], v[180:183], v[204:207], v[10:13]
	v_mfma_f32_16x16x32_bf16 v[6:9], v[166:169], v[212:215], v[6:9]
	v_mfma_f32_16x16x32_bf16 v[2:5], v[180:183], v[212:215], v[2:5]
	v_mfma_f32_16x16x32_bf16 v[30:33], v[170:173], v[192:195], v[30:33]
	v_mfma_f32_16x16x32_bf16 v[26:29], v[184:187], v[192:195], v[26:29]
	v_mfma_f32_16x16x32_bf16 v[22:25], v[170:173], v[200:203], v[22:25]
	v_mfma_f32_16x16x32_bf16 v[18:21], v[184:187], v[200:203], v[18:21]
	v_mfma_f32_16x16x32_bf16 v[14:17], v[170:173], v[208:211], v[14:17]
	v_mfma_f32_16x16x32_bf16 v[10:13], v[184:187], v[208:211], v[10:13]
	v_mfma_f32_16x16x32_bf16 v[6:9], v[170:173], v[216:219], v[6:9]
	v_mfma_f32_16x16x32_bf16 v[2:5], v[184:187], v[216:219], v[2:5]
	s_barrier
	s_setprio 0
	s_add_i32 s50, 0, 0x18000
	v_add_u32_e32 v0, s50, v154
	s_add_i32 s51, 0, 0x1c000
	ds_read_b128 v[130:133], v0
	ds_read_b128 v[148:151], v0 offset:1024
	ds_read_b128 v[158:161], v0 offset:2048
	ds_read_b128 v[162:165], v0 offset:3072
	v_add_u32_e32 v0, s51, v154
	ds_read_b128 v[166:169], v0
	ds_read_b128 v[170:173], v0 offset:1024
	ds_read_b128 v[180:183], v0 offset:2048
	ds_read_b128 v[184:187], v0 offset:3072
	s_add_u32 s0, s16, 0x30000
	s_addc_u32 s1, s17, 0
	s_mov_b32 m0, s34
	v_lshl_add_u64 v[224:225], s[0:1], 0, v[134:135]
	ds_read_b128 v[188:191], v156 offset:32768
	ds_read_b128 v[192:195], v156 offset:33792
	ds_read_b128 v[196:199], v156 offset:34816
	ds_read_b128 v[200:203], v156 offset:35840
	ds_read_b128 v[204:207], v156 offset:36864
	ds_read_b128 v[208:211], v156 offset:37888
	ds_read_b128 v[212:215], v156 offset:38912
	ds_read_b128 v[216:219], v156 offset:39936
	global_load_lds_dwordx4 v[224:225], off
	v_lshl_add_u64 v[224:225], s[0:1], 0, v[138:139]
	s_mov_b32 m0, s35
	s_nop 0
	global_load_lds_dwordx4 v[224:225], off
	s_waitcnt vmcnt(8)
	s_waitcnt lgkmcnt(0)
	s_setprio 1
	s_barrier
	v_mfma_f32_16x16x32_bf16 v[126:129], v[130:133], v[188:191], v[126:129]
	v_mfma_f32_16x16x32_bf16 v[122:125], v[158:161], v[188:191], v[122:125]
	v_mfma_f32_16x16x32_bf16 v[118:121], v[130:133], v[196:199], v[118:121]
	v_mfma_f32_16x16x32_bf16 v[114:117], v[158:161], v[196:199], v[114:117]
	v_mfma_f32_16x16x32_bf16 v[110:113], v[130:133], v[204:207], v[110:113]
	v_mfma_f32_16x16x32_bf16 v[106:109], v[158:161], v[204:207], v[106:109]
	v_mfma_f32_16x16x32_bf16 v[102:105], v[130:133], v[212:215], v[102:105]
	v_mfma_f32_16x16x32_bf16 v[98:101], v[158:161], v[212:215], v[98:101]
	v_mfma_f32_16x16x32_bf16 v[126:129], v[148:151], v[192:195], v[126:129]
	v_mfma_f32_16x16x32_bf16 v[122:125], v[162:165], v[192:195], v[122:125]
	v_mfma_f32_16x16x32_bf16 v[118:121], v[148:151], v[200:203], v[118:121]
	v_mfma_f32_16x16x32_bf16 v[114:117], v[162:165], v[200:203], v[114:117]
	v_mfma_f32_16x16x32_bf16 v[110:113], v[148:151], v[208:211], v[110:113]
	v_mfma_f32_16x16x32_bf16 v[106:109], v[162:165], v[208:211], v[106:109]
	v_mfma_f32_16x16x32_bf16 v[102:105], v[148:151], v[216:219], v[102:105]
	v_mfma_f32_16x16x32_bf16 v[98:101], v[162:165], v[216:219], v[98:101]
	v_mfma_f32_16x16x32_bf16 v[62:65], v[166:169], v[188:191], v[62:65]
	v_mfma_f32_16x16x32_bf16 v[58:61], v[180:183], v[188:191], v[58:61]
	v_mfma_f32_16x16x32_bf16 v[54:57], v[166:169], v[196:199], v[54:57]
	v_mfma_f32_16x16x32_bf16 v[50:53], v[180:183], v[196:199], v[50:53]
	v_mfma_f32_16x16x32_bf16 v[46:49], v[166:169], v[204:207], v[46:49]
	v_mfma_f32_16x16x32_bf16 v[42:45], v[180:183], v[204:207], v[42:45]
	v_mfma_f32_16x16x32_bf16 v[38:41], v[166:169], v[212:215], v[38:41]
	v_mfma_f32_16x16x32_bf16 v[34:37], v[180:183], v[212:215], v[34:37]
	v_mfma_f32_16x16x32_bf16 v[62:65], v[170:173], v[192:195], v[62:65]
	v_mfma_f32_16x16x32_bf16 v[58:61], v[184:187], v[192:195], v[58:61]
	v_mfma_f32_16x16x32_bf16 v[54:57], v[170:173], v[200:203], v[54:57]
	v_mfma_f32_16x16x32_bf16 v[50:53], v[184:187], v[200:203], v[50:53]
	v_mfma_f32_16x16x32_bf16 v[46:49], v[170:173], v[208:211], v[46:49]
	v_mfma_f32_16x16x32_bf16 v[42:45], v[184:187], v[208:211], v[42:45]
	v_mfma_f32_16x16x32_bf16 v[38:41], v[170:173], v[216:219], v[38:41]
	v_mfma_f32_16x16x32_bf16 v[34:37], v[184:187], v[216:219], v[34:37]
	s_barrier
; #define PG8_STAGE(bufoff, gbase, voff) do { _Pragma("unroll") for (int _i = 0; _i < 2; ++_i) \
;         __builtin_amdgcn_global_load_lds((const unsigned*)((const char*)(gbase) + (voff)[_i]), (LAS unsigned*)(lds + (bufoff) + ldsw + _i * 8192), 16, 0, 0); } while (0)
; #define PG8_LDA(dst, b, h) do { _Pragma("unroll") for (int m = 0; m < 4; ++m) _Pragma("unroll") for (int k = 0; k < 2; ++k) dst[m][k] = *(const LAS bf16x8*)(lds + PG8_SA(b, h) + aoff + m * 2048 + k * 1024); } while (0)
; #define PG8_MMA(ai, bj, At, Bt) do { __builtin_amdgcn_s_setprio(1); _Pragma("unroll") for (int m = 0; m < 4; ++m) _Pragma("unroll") for (int n = 0; n < 2; ++n) _Pragma("unroll") for (int k = 0; k < 2; ++k) \
;         acc[ai][bj][m][n] = __builtin_amdgcn_mfma_f32_16x16x32_bf16(Bt[n][k], At[m][k], acc[ai][bj][m][n], 0, 0, 0); __builtin_amdgcn_s_setprio(0); } while (0)
; #define PG8_WAIT_V(n) asm volatile("s_waitcnt vmcnt(" #n ")" ::: "memory")
; #define PG8_WAIT_L(n) asm volatile("s_waitcnt lgkmcnt(" #n ")" ::: "memory")
; #define PG8_BAR __builtin_amdgcn_s_barrier()
; #define PG8_SCHED __builtin_amdgcn_sched_barrier(0)
; template <class Epi, class Sched, int LDA, int LDB, bool ALIGN_EPI = true>
; __device__ __forceinline__ void gemm_phase(LAS unsigned char* lds, const Gemm g, const Sched& S, const Epi& E, int wave) {
;     ...
;             PG8_LDA(At, 1, 1); PG8_STAGE(PG8_SB(1, 0), b3, voffB); PG8_STAGE(PG8_SB(1, 1), b3 + hstepB, voffB); PG8_STAGE(PG8_SA(1, 0), a3, voffA);
;             PG8_WAIT_V(8); PG8_WAIT_L(0); PG8_BAR; PG8_MMA(1, 0, At, B0); PG8_MMA(1, 1, At, B1); PG8_BAR; PG8_SCHED;
;         }
	s_setprio 0
	s_add_i32 s0, s50, s54
	v_lshl_add_u64 v[152:153], v[152:153], 0, s[72:73]
	s_mov_b32 m0, s0
	ds_read_b128 v[188:191], v156 offset:49152
	ds_read_b128 v[192:195], v156 offset:50176
	ds_read_b128 v[196:199], v156 offset:51200
	ds_read_b128 v[200:203], v156 offset:52224
	ds_read_b128 v[204:207], v156 offset:53248
	ds_read_b128 v[208:211], v156 offset:54272
	ds_read_b128 v[212:215], v156 offset:55296
	ds_read_b128 v[216:219], v156 offset:56320
	global_load_lds_dwordx4 v[152:153], off
	s_add_i32 m0, s0, 0x2000
	s_add_u32 s0, s14, 0x30080
	v_lshl_add_u64 v[152:153], v[174:175], 0, s[72:73]
	s_addc_u32 s1, s15, 0
	s_add_i32 s14, s51, s54
	global_load_lds_dwordx4 v[152:153], off
	v_lshl_add_u64 v[152:153], s[0:1], 0, v[136:137]
	s_mov_b32 m0, s14
	s_nop 0
	global_load_lds_dwordx4 v[152:153], off
	v_lshl_add_u64 v[152:153], s[0:1], 0, v[140:141]
	s_add_i32 m0, s14, 0x2000
	s_nop 0
	global_load_lds_dwordx4 v[152:153], off
	v_lshl_add_u64 v[152:153], v[220:221], 0, s[72:73]
	s_mov_b32 m0, s36
	s_nop 0
	global_load_lds_dwordx4 v[152:153], off
	v_lshl_add_u64 v[152:153], v[222:223], 0, s[72:73]
	s_mov_b32 m0, s37
	s_nop 0
	global_load_lds_dwordx4 v[152:153], off
	s_waitcnt vmcnt(8)
	s_waitcnt lgkmcnt(0)
	s_setprio 1
	s_barrier
	v_mfma_f32_16x16x32_bf16 v[94:97], v[130:133], v[188:191], v[94:97]
	v_mfma_f32_16x16x32_bf16 v[90:93], v[158:161], v[188:191], v[90:93]
	v_mfma_f32_16x16x32_bf16 v[86:89], v[130:133], v[196:199], v[86:89]
	v_mfma_f32_16x16x32_bf16 v[82:85], v[158:161], v[196:199], v[82:85]
	v_mfma_f32_16x16x32_bf16 v[78:81], v[130:133], v[204:207], v[78:81]
	v_mfma_f32_16x16x32_bf16 v[74:77], v[158:161], v[204:207], v[74:77]
	v_mfma_f32_16x16x32_bf16 v[70:73], v[130:133], v[212:215], v[70:73]
	v_mfma_f32_16x16x32_bf16 v[66:69], v[158:161], v[212:215], v[66:69]
	v_mfma_f32_16x16x32_bf16 v[94:97], v[148:151], v[192:195], v[94:97]
	v_mfma_f32_16x16x32_bf16 v[90:93], v[162:165], v[192:195], v[90:93]
	v_mfma_f32_16x16x32_bf16 v[86:89], v[148:151], v[200:203], v[86:89]
	v_mfma_f32_16x16x32_bf16 v[82:85], v[162:165], v[200:203], v[82:85]
	v_mfma_f32_16x16x32_bf16 v[78:81], v[148:151], v[208:211], v[78:81]
	v_mfma_f32_16x16x32_bf16 v[74:77], v[162:165], v[208:211], v[74:77]
	v_mfma_f32_16x16x32_bf16 v[70:73], v[148:151], v[216:219], v[70:73]
	v_mfma_f32_16x16x32_bf16 v[66:69], v[162:165], v[216:219], v[66:69]
	v_mfma_f32_16x16x32_bf16 v[30:33], v[166:169], v[188:191], v[30:33]
	v_mfma_f32_16x16x32_bf16 v[26:29], v[180:183], v[188:191], v[26:29]
	v_mfma_f32_16x16x32_bf16 v[22:25], v[166:169], v[196:199], v[22:25]
	v_mfma_f32_16x16x32_bf16 v[18:21], v[180:183], v[196:199], v[18:21]
	v_mfma_f32_16x16x32_bf16 v[14:17], v[166:169], v[204:207], v[14:17]
	v_mfma_f32_16x16x32_bf16 v[10:13], v[180:183], v[204:207], v[10:13]
	v_mfma_f32_16x16x32_bf16 v[6:9], v[166:169], v[212:215], v[6:9]
	v_mfma_f32_16x16x32_bf16 v[2:5], v[180:183], v[212:215], v[2:5]
	v_mfma_f32_16x16x32_bf16 v[30:33], v[170:173], v[192:195], v[30:33]
	v_mfma_f32_16x16x32_bf16 v[26:29], v[184:187], v[192:195], v[26:29]
	v_mfma_f32_16x16x32_bf16 v[22:25], v[170:173], v[200:203], v[22:25]
	v_mfma_f32_16x16x32_bf16 v[18:21], v[184:187], v[200:203], v[18:21]
	v_mfma_f32_16x16x32_bf16 v[14:17], v[170:173], v[208:211], v[14:17]
	v_mfma_f32_16x16x32_bf16 v[10:13], v[184:187], v[208:211], v[10:13]
	v_mfma_f32_16x16x32_bf16 v[6:9], v[170:173], v[216:219], v[6:9]
	v_mfma_f32_16x16x32_bf16 v[2:5], v[184:187], v[216:219], v[2:5]
	s_barrier
	s_setprio 0
	s_add_i32 s49, s49, 2
	s_add_u32 s46, s46, 0x100
	s_addc_u32 s47, s47, 0
	s_cmp_gt_u32 s49, 9
	s_mov_b64 s[0:1], s[2:3]
	s_cbranch_scc0 .LBB0_2551
	v_readlane_b32 s0, v252, 14
	v_readlane_b32 s1, v252, 15
	s_and_b64 vcc, exec, s[0:1]
	s_cbranch_vccz .LBB0_2554
	s_barrier

; #define PG8_STAGE(bufoff, gbase, voff) do { _Pragma("unroll") for (int _i = 0; _i < 2; ++_i) \
;         __builtin_amdgcn_global_load_lds((const unsigned*)((const char*)(gbase) + (voff)[_i]), (LAS unsigned*)(lds + (bufoff) + ldsw + _i * 8192), 16, 0, 0); } while (0)
; #define PG8_LDA(dst, b, h) do { _Pragma("unroll") for (int m = 0; m < 4; ++m) _Pragma("unroll") for (int k = 0; k < 2; ++k) dst[m][k] = *(const LAS bf16x8*)(lds + PG8_SA(b, h) + aoff + m * 2048 + k * 1024); } while (0)
; #define PG8_LDB(dst, b, h) do { _Pragma("unroll") for (int n = 0; n < 2; ++n) _Pragma("unroll") for (int k = 0; k < 2; ++k) dst[n][k] = *(const LAS bf16x8*)(lds + PG8_SB(b, h) + boff + n * 2048 + k * 1024); } while (0)
; #define PG8_MMA(ai, bj, At, Bt) do { __builtin_amdgcn_s_setprio(1); _Pragma("unroll") for (int m = 0; m < 4; ++m) _Pragma("unroll") for (int n = 0; n < 2; ++n) _Pragma("unroll") for (int k = 0; k < 2; ++k) \
;         acc[ai][bj][m][n] = __builtin_amdgcn_mfma_f32_16x16x32_bf16(Bt[n][k], At[m][k], acc[ai][bj][m][n], 0, 0, 0); __builtin_amdgcn_s_setprio(0); } while (0)
; #define PG8_WAIT_V(n) asm volatile("s_waitcnt vmcnt(" #n ")" ::: "memory")
; #define PG8_WAIT_L(n) asm volatile("s_waitcnt lgkmcnt(" #n ")" ::: "memory")
; #define PG8_BAR __builtin_amdgcn_s_barrier()
; #define PG8_SCHED __builtin_amdgcn_sched_barrier(0)
; template <class Epi, class Sched, int LDA, int LDB, bool ALIGN_EPI = true>
; __device__ __forceinline__ void gemm_phase(LAS unsigned char* lds, const Gemm g, const Sched& S, const Epi& E, int wave) {
;     ...
;             const bool last = (t == nt - 2);
;             const char* a1 = cA + (size_t)(t + 1) * kstep;
;             const char* a2 = last ? nA : cA + (size_t)(t + 2) * kstep; const char* b2 = last ? nB : cB + (size_t)(t + 2) * kstep;
;             const char* a3 = a2 + kstep; const char* b3 = b2 + kstep;
;             PG8_LDB(B0, 0, 0); PG8_LDB(B1, 0, 1); PG8_SCHED; PG8_LDA(At, 0, 0); PG8_STAGE(PG8_SA(1, 1), a1 + hstepA, voffA);
;             PG8_WAIT_V(8); PG8_WAIT_L(0); PG8_BAR; PG8_MMA(0, 0, At, B0); PG8_MMA(0, 1, At, B1); PG8_BAR; PG8_SCHED;
;             PG8_LDA(At, 0, 1); PG8_STAGE(PG8_SB(0, 0), b2, voffB); PG8_STAGE(PG8_SB(0, 1), b2 + hstepB, voffB); PG8_STAGE(PG8_SA(0, 0), a2, voffA);
;             PG8_WAIT_V(8); PG8_WAIT_L(0); PG8_BAR; PG8_MMA(1, 0, At, B0); PG8_MMA(1, 1, At, B1); PG8_BAR; PG8_SCHED;
.LBB0_2619:
	s_add_u32 s16, s14, 0xfffe0080
	s_addc_u32 s17, s15, -1
	s_add_i32 s53, 0, 0x10000
	s_cmp_eq_u32 s52, 4
	s_cselect_b32 s19, s7, s17
	s_cselect_b32 s18, s13, s16
	v_add_u32_e32 v0, s53, v150
	s_cselect_b32 s17, s3, s51
	s_cselect_b32 s16, s44, s45
	s_add_i32 s58, 0, 0x14000
	ds_read_b128 v[144:147], v0
	ds_read_b128 v[152:155], v0 offset:1024
	ds_read_b128 v[156:159], v0 offset:2048
	ds_read_b128 v[160:163], v0 offset:3072
	v_add_u32_e32 v0, s58, v150
	ds_read_b128 v[164:167], v0
	ds_read_b128 v[168:171], v0 offset:1024
	ds_read_b128 v[172:175], v0 offset:2048
	ds_read_b128 v[180:183], v0 offset:3072
	v_lshl_add_u64 v[148:149], s[14:15], 0, v[140:141]
	s_add_i32 m0, s36, 0xc000
	ds_read_b128 v[184:187], v151
	ds_read_b128 v[188:191], v151 offset:1024
	ds_read_b128 v[192:195], v151 offset:2048
	ds_read_b128 v[196:199], v151 offset:3072
	ds_read_b128 v[200:203], v151 offset:4096
	ds_read_b128 v[204:207], v151 offset:5120
	ds_read_b128 v[208:211], v151 offset:6144
	ds_read_b128 v[212:215], v151 offset:7168
	global_load_lds_dwordx4 v[148:149], off
	v_lshl_add_u64 v[148:149], s[14:15], 0, v[142:143]
	s_add_i32 m0, s36, 0xe000
	s_nop 0
	global_load_lds_dwordx4 v[148:149], off
	s_waitcnt vmcnt(8)
	s_waitcnt lgkmcnt(0)
	s_setprio 1
	s_barrier
	v_mfma_f32_16x16x32_bf16 v[126:129], v[144:147], v[184:187], v[126:129]
	v_mfma_f32_16x16x32_bf16 v[122:125], v[156:159], v[184:187], v[122:125]
	v_mfma_f32_16x16x32_bf16 v[118:121], v[144:147], v[192:195], v[118:121]
	v_mfma_f32_16x16x32_bf16 v[114:117], v[156:159], v[192:195], v[114:117]
	v_mfma_f32_16x16x32_bf16 v[110:113], v[144:147], v[200:203], v[110:113]
	v_mfma_f32_16x16x32_bf16 v[106:109], v[156:159], v[200:203], v[106:109]
	v_mfma_f32_16x16x32_bf16 v[102:105], v[144:147], v[208:211], v[102:105]
	v_mfma_f32_16x16x32_bf16 v[98:101], v[156:159], v[208:211], v[98:101]
	v_mfma_f32_16x16x32_bf16 v[126:129], v[152:155], v[188:191], v[126:129]
	v_mfma_f32_16x16x32_bf16 v[122:125], v[160:163], v[188:191], v[122:125]
	v_mfma_f32_16x16x32_bf16 v[118:121], v[152:155], v[196:199], v[118:121]
	v_mfma_f32_16x16x32_bf16 v[114:117], v[160:163], v[196:199], v[114:117]
	v_mfma_f32_16x16x32_bf16 v[110:113], v[152:155], v[204:207], v[110:113]
	v_mfma_f32_16x16x32_bf16 v[106:109], v[160:163], v[204:207], v[106:109]
	v_mfma_f32_16x16x32_bf16 v[102:105], v[152:155], v[212:215], v[102:105]
	v_mfma_f32_16x16x32_bf16 v[98:101], v[160:163], v[212:215], v[98:101]
	v_mfma_f32_16x16x32_bf16 v[62:65], v[164:167], v[184:187], v[62:65]
	v_mfma_f32_16x16x32_bf16 v[58:61], v[172:175], v[184:187], v[58:61]
	v_mfma_f32_16x16x32_bf16 v[54:57], v[164:167], v[192:195], v[54:57]
	v_mfma_f32_16x16x32_bf16 v[50:53], v[172:175], v[192:195], v[50:53]
	v_mfma_f32_16x16x32_bf16 v[46:49], v[164:167], v[200:203], v[46:49]
	v_mfma_f32_16x16x32_bf16 v[42:45], v[172:175], v[200:203], v[42:45]
	v_mfma_f32_16x16x32_bf16 v[38:41], v[164:167], v[208:211], v[38:41]
	v_mfma_f32_16x16x32_bf16 v[34:37], v[172:175], v[208:211], v[34:37]
	v_mfma_f32_16x16x32_bf16 v[62:65], v[168:171], v[188:191], v[62:65]
	v_mfma_f32_16x16x32_bf16 v[58:61], v[180:183], v[188:191], v[58:61]
	v_mfma_f32_16x16x32_bf16 v[54:57], v[168:171], v[196:199], v[54:57]
	v_mfma_f32_16x16x32_bf16 v[50:53], v[180:183], v[196:199], v[50:53]
	v_mfma_f32_16x16x32_bf16 v[46:49], v[168:171], v[204:207], v[46:49]
	v_mfma_f32_16x16x32_bf16 v[42:45], v[180:183], v[204:207], v[42:45]
	v_mfma_f32_16x16x32_bf16 v[38:41], v[168:171], v[212:215], v[38:41]
	v_mfma_f32_16x16x32_bf16 v[34:37], v[180:183], v[212:215], v[34:37]
	s_barrier
	s_setprio 0
	s_add_i32 s53, s53, s59
	v_lshl_add_u64 v[148:149], s[16:17], 0, v[132:133]
	s_mov_b32 m0, s53
	ds_read_b128 v[184:187], v151 offset:16384
	ds_read_b128 v[188:191], v151 offset:17408
	ds_read_b128 v[192:195], v151 offset:18432
	ds_read_b128 v[196:199], v151 offset:19456
	ds_read_b128 v[200:203], v151 offset:20480
	ds_read_b128 v[204:207], v151 offset:21504
	ds_read_b128 v[208:211], v151 offset:22528
	ds_read_b128 v[212:215], v151 offset:23552
	global_load_lds_dwordx4 v[148:149], off
	s_add_i32 m0, s53, 0x2000
	s_add_u32 s54, s16, 0x20000
	v_lshl_add_u64 v[216:217], s[16:17], 0, v[136:137]
	s_addc_u32 s55, s17, 0
	s_add_i32 s53, s58, s59
	global_load_lds_dwordx4 v[216:217], off
	v_lshl_add_u64 v[218:219], s[54:55], 0, v[132:133]
	s_mov_b32 m0, s53
	v_lshl_add_u64 v[220:221], s[18:19], 0, v[134:135]
	global_load_lds_dwordx4 v[218:219], off
	v_lshl_add_u64 v[218:219], s[54:55], 0, v[136:137]
	s_add_i32 m0, s53, 0x2000
	s_nop 0
	global_load_lds_dwordx4 v[218:219], off
	v_lshl_add_u64 v[218:219], s[18:19], 0, v[130:131]
	s_mov_b32 m0, s36
	s_nop 0
	global_load_lds_dwordx4 v[218:219], off
	s_mov_b32 m0, s37
	s_nop 0
	global_load_lds_dwordx4 v[220:221], off
	s_waitcnt vmcnt(8)
	s_waitcnt lgkmcnt(0)
	s_setprio 1
	s_barrier
; #define PG8_STAGE(bufoff, gbase, voff) do { _Pragma("unroll") for (int _i = 0; _i < 2; ++_i) \
;         __builtin_amdgcn_global_load_lds((const unsigned*)((const char*)(gbase) + (voff)[_i]), (LAS unsigned*)(lds + (bufoff) + ldsw + _i * 8192), 16, 0, 0); } while (0)
; #define PG8_LDA(dst, b, h) do { _Pragma("unroll") for (int m = 0; m < 4; ++m) _Pragma("unroll") for (int k = 0; k < 2; ++k) dst[m][k] = *(const LAS bf16x8*)(lds + PG8_SA(b, h) + aoff + m * 2048 + k * 1024); } while (0)
; #define PG8_LDB(dst, b, h) do { _Pragma("unroll") for (int n = 0; n < 2; ++n) _Pragma("unroll") for (int k = 0; k < 2; ++k) dst[n][k] = *(const LAS bf16x8*)(lds + PG8_SB(b, h) + boff + n * 2048 + k * 1024); } while (0)
; #define PG8_MMA(ai, bj, At, Bt) do { __builtin_amdgcn_s_setprio(1); _Pragma("unroll") for (int m = 0; m < 4; ++m) _Pragma("unroll") for (int n = 0; n < 2; ++n) _Pragma("unroll") for (int k = 0; k < 2; ++k) \
;         acc[ai][bj][m][n] = __builtin_amdgcn_mfma_f32_16x16x32_bf16(Bt[n][k], At[m][k], acc[ai][bj][m][n], 0, 0, 0); __builtin_amdgcn_s_setprio(0); } while (0)
; #define PG8_WAIT_V(n) asm volatile("s_waitcnt vmcnt(" #n ")" ::: "memory")
; #define PG8_WAIT_L(n) asm volatile("s_waitcnt lgkmcnt(" #n ")" ::: "memory")
; #define PG8_BAR __builtin_amdgcn_s_barrier()
; #define PG8_SCHED __builtin_amdgcn_sched_barrier(0)
; template <class Epi, class Sched, int LDA, int LDB, bool ALIGN_EPI = true>
; __device__ __forceinline__ void gemm_phase(LAS unsigned char* lds, const Gemm g, const Sched& S, const Epi& E, int wave) {
;     ...
;             PG8_WAIT_V(8); PG8_WAIT_L(0); PG8_BAR; PG8_MMA(1, 0, At, B0); PG8_MMA(1, 1, At, B1); PG8_BAR; PG8_SCHED;
;             PG8_LDB(B0, 1, 0); PG8_LDB(B1, 1, 1); PG8_SCHED; PG8_LDA(At, 1, 0); PG8_STAGE(PG8_SA(0, 1), a2 + hstepA, voffA);
;             PG8_WAIT_V(8); PG8_WAIT_L(0); PG8_BAR; PG8_MMA(0, 0, At, B0); PG8_MMA(0, 1, At, B1); PG8_BAR; PG8_SCHED;
	v_mfma_f32_16x16x32_bf16 v[94:97], v[144:147], v[184:187], v[94:97]
	v_mfma_f32_16x16x32_bf16 v[90:93], v[156:159], v[184:187], v[90:93]
	v_mfma_f32_16x16x32_bf16 v[86:89], v[144:147], v[192:195], v[86:89]
	v_mfma_f32_16x16x32_bf16 v[82:85], v[156:159], v[192:195], v[82:85]
	v_mfma_f32_16x16x32_bf16 v[78:81], v[144:147], v[200:203], v[78:81]
	v_mfma_f32_16x16x32_bf16 v[74:77], v[156:159], v[200:203], v[74:77]
	v_mfma_f32_16x16x32_bf16 v[70:73], v[144:147], v[208:211], v[70:73]
	v_mfma_f32_16x16x32_bf16 v[66:69], v[156:159], v[208:211], v[66:69]
	v_mfma_f32_16x16x32_bf16 v[94:97], v[152:155], v[188:191], v[94:97]
	v_mfma_f32_16x16x32_bf16 v[90:93], v[160:163], v[188:191], v[90:93]
	v_mfma_f32_16x16x32_bf16 v[86:89], v[152:155], v[196:199], v[86:89]
	v_mfma_f32_16x16x32_bf16 v[82:85], v[160:163], v[196:199], v[82:85]
	v_mfma_f32_16x16x32_bf16 v[78:81], v[152:155], v[204:207], v[78:81]
	v_mfma_f32_16x16x32_bf16 v[74:77], v[160:163], v[204:207], v[74:77]
	v_mfma_f32_16x16x32_bf16 v[70:73], v[152:155], v[212:215], v[70:73]
	v_mfma_f32_16x16x32_bf16 v[66:69], v[160:163], v[212:215], v[66:69]
	v_mfma_f32_16x16x32_bf16 v[30:33], v[164:167], v[184:187], v[30:33]
	v_mfma_f32_16x16x32_bf16 v[26:29], v[172:175], v[184:187], v[26:29]
	v_mfma_f32_16x16x32_bf16 v[22:25], v[164:167], v[192:195], v[22:25]
	v_mfma_f32_16x16x32_bf16 v[18:21], v[172:175], v[192:195], v[18:21]
	v_mfma_f32_16x16x32_bf16 v[14:17], v[164:167], v[200:203], v[14:17]
	v_mfma_f32_16x16x32_bf16 v[10:13], v[172:175], v[200:203], v[10:13]
	v_mfma_f32_16x16x32_bf16 v[6:9], v[164:167], v[208:211], v[6:9]
	v_mfma_f32_16x16x32_bf16 v[2:5], v[172:175], v[208:211], v[2:5]
	v_mfma_f32_16x16x32_bf16 v[30:33], v[168:171], v[188:191], v[30:33]
	v_mfma_f32_16x16x32_bf16 v[26:29], v[180:183], v[188:191], v[26:29]
	v_mfma_f32_16x16x32_bf16 v[22:25], v[168:171], v[196:199], v[22:25]
	v_mfma_f32_16x16x32_bf16 v[18:21], v[180:183], v[196:199], v[18:21]
	v_mfma_f32_16x16x32_bf16 v[14:17], v[168:171], v[204:207], v[14:17]
	v_mfma_f32_16x16x32_bf16 v[10:13], v[180:183], v[204:207], v[10:13]
	v_mfma_f32_16x16x32_bf16 v[6:9], v[168:171], v[212:215], v[6:9]
	v_mfma_f32_16x16x32_bf16 v[2:5], v[180:183], v[212:215], v[2:5]
	s_barrier
	s_setprio 0
	s_add_i32 s53, 0, 0x18000
	v_add_u32_e32 v0, s53, v150
	s_add_i32 s54, 0, 0x1c000
	ds_read_b128 v[144:147], v0
	ds_read_b128 v[152:155], v0 offset:1024
	ds_read_b128 v[156:159], v0 offset:2048
	ds_read_b128 v[160:163], v0 offset:3072
	v_add_u32_e32 v0, s54, v150
	ds_read_b128 v[164:167], v0
	ds_read_b128 v[168:171], v0 offset:1024
	ds_read_b128 v[172:175], v0 offset:2048
	ds_read_b128 v[180:183], v0 offset:3072
	s_add_u32 s18, s18, 0x20000
	s_addc_u32 s19, s19, 0
	s_mov_b32 m0, s38
	v_lshl_add_u64 v[222:223], s[18:19], 0, v[130:131]
	ds_read_b128 v[184:187], v151 offset:32768
	ds_read_b128 v[188:191], v151 offset:33792
	ds_read_b128 v[192:195], v151 offset:34816
	ds_read_b128 v[196:199], v151 offset:35840
	ds_read_b128 v[200:203], v151 offset:36864
	ds_read_b128 v[204:207], v151 offset:37888
	ds_read_b128 v[208:211], v151 offset:38912
	ds_read_b128 v[212:215], v151 offset:39936
	global_load_lds_dwordx4 v[222:223], off
	v_lshl_add_u64 v[222:223], s[18:19], 0, v[134:135]
	s_mov_b32 m0, s39
	s_nop 0
	global_load_lds_dwordx4 v[222:223], off
	s_waitcnt vmcnt(8)
	s_waitcnt lgkmcnt(0)
	s_setprio 1
	s_barrier
	v_mfma_f32_16x16x32_bf16 v[126:129], v[144:147], v[184:187], v[126:129]
	v_mfma_f32_16x16x32_bf16 v[122:125], v[156:159], v[184:187], v[122:125]
	v_mfma_f32_16x16x32_bf16 v[118:121], v[144:147], v[192:195], v[118:121]
	v_mfma_f32_16x16x32_bf16 v[114:117], v[156:159], v[192:195], v[114:117]
	v_mfma_f32_16x16x32_bf16 v[110:113], v[144:147], v[200:203], v[110:113]
	v_mfma_f32_16x16x32_bf16 v[106:109], v[156:159], v[200:203], v[106:109]
	v_mfma_f32_16x16x32_bf16 v[102:105], v[144:147], v[208:211], v[102:105]
	v_mfma_f32_16x16x32_bf16 v[98:101], v[156:159], v[208:211], v[98:101]
	v_mfma_f32_16x16x32_bf16 v[126:129], v[152:155], v[188:191], v[126:129]
	v_mfma_f32_16x16x32_bf16 v[122:125], v[160:163], v[188:191], v[122:125]
	v_mfma_f32_16x16x32_bf16 v[118:121], v[152:155], v[196:199], v[118:121]
	v_mfma_f32_16x16x32_bf16 v[114:117], v[160:163], v[196:199], v[114:117]
	v_mfma_f32_16x16x32_bf16 v[110:113], v[152:155], v[204:207], v[110:113]
	v_mfma_f32_16x16x32_bf16 v[106:109], v[160:163], v[204:207], v[106:109]
	v_mfma_f32_16x16x32_bf16 v[102:105], v[152:155], v[212:215], v[102:105]
	v_mfma_f32_16x16x32_bf16 v[98:101], v[160:163], v[212:215], v[98:101]
	v_mfma_f32_16x16x32_bf16 v[62:65], v[164:167], v[184:187], v[62:65]
	v_mfma_f32_16x16x32_bf16 v[58:61], v[172:175], v[184:187], v[58:61]
	v_mfma_f32_16x16x32_bf16 v[54:57], v[164:167], v[192:195], v[54:57]
	v_mfma_f32_16x16x32_bf16 v[50:53], v[172:175], v[192:195], v[50:53]
	v_mfma_f32_16x16x32_bf16 v[46:49], v[164:167], v[200:203], v[46:49]
	v_mfma_f32_16x16x32_bf16 v[42:45], v[172:175], v[200:203], v[42:45]
	v_mfma_f32_16x16x32_bf16 v[38:41], v[164:167], v[208:211], v[38:41]
	v_mfma_f32_16x16x32_bf16 v[34:37], v[172:175], v[208:211], v[34:37]
	v_mfma_f32_16x16x32_bf16 v[62:65], v[168:171], v[188:191], v[62:65]
	v_mfma_f32_16x16x32_bf16 v[58:61], v[180:183], v[188:191], v[58:61]
	v_mfma_f32_16x16x32_bf16 v[54:57], v[168:171], v[196:199], v[54:57]
	v_mfma_f32_16x16x32_bf16 v[50:53], v[180:183], v[196:199], v[50:53]
	v_mfma_f32_16x16x32_bf16 v[46:49], v[168:171], v[204:207], v[46:49]
	v_mfma_f32_16x16x32_bf16 v[42:45], v[180:183], v[204:207], v[42:45]
	v_mfma_f32_16x16x32_bf16 v[38:41], v[168:171], v[212:215], v[38:41]
	v_mfma_f32_16x16x32_bf16 v[34:37], v[180:183], v[212:215], v[34:37]
	s_barrier
; #define PG8_STAGE(bufoff, gbase, voff) do { _Pragma("unroll") for (int _i = 0; _i < 2; ++_i) \
;         __builtin_amdgcn_global_load_lds((const unsigned*)((const char*)(gbase) + (voff)[_i]), (LAS unsigned*)(lds + (bufoff) + ldsw + _i * 8192), 16, 0, 0); } while (0)
; #define PG8_LDA(dst, b, h) do { _Pragma("unroll") for (int m = 0; m < 4; ++m) _Pragma("unroll") for (int k = 0; k < 2; ++k) dst[m][k] = *(const LAS bf16x8*)(lds + PG8_SA(b, h) + aoff + m * 2048 + k * 1024); } while (0)
; #define PG8_MMA(ai, bj, At, Bt) do { __builtin_amdgcn_s_setprio(1); _Pragma("unroll") for (int m = 0; m < 4; ++m) _Pragma("unroll") for (int n = 0; n < 2; ++n) _Pragma("unroll") for (int k = 0; k < 2; ++k) \
;         acc[ai][bj][m][n] = __builtin_amdgcn_mfma_f32_16x16x32_bf16(Bt[n][k], At[m][k], acc[ai][bj][m][n], 0, 0, 0); __builtin_amdgcn_s_setprio(0); } while (0)
; #define PG8_WAIT_V(n) asm volatile("s_waitcnt vmcnt(" #n ")" ::: "memory")
; #define PG8_WAIT_L(n) asm volatile("s_waitcnt lgkmcnt(" #n ")" ::: "memory")
; #define PG8_BAR __builtin_amdgcn_s_barrier()
; #define PG8_SCHED __builtin_amdgcn_sched_barrier(0)
; template <class Epi, class Sched, int LDA, int LDB, bool ALIGN_EPI = true>
; __device__ __forceinline__ void gemm_phase(LAS unsigned char* lds, const Gemm g, const Sched& S, const Epi& E, int wave) {
;     ...
;             PG8_LDA(At, 1, 1); PG8_STAGE(PG8_SB(1, 0), b3, voffB); PG8_STAGE(PG8_SB(1, 1), b3 + hstepB, voffB); PG8_STAGE(PG8_SA(1, 0), a3, voffA);
;             PG8_WAIT_V(8); PG8_WAIT_L(0); PG8_BAR; PG8_MMA(1, 0, At, B0); PG8_MMA(1, 1, At, B1); PG8_BAR; PG8_SCHED;
;         }
	s_setprio 0
	s_add_i32 s18, s53, s59
	v_lshl_add_u64 v[148:149], v[148:149], 0, s[70:71]
	s_mov_b32 m0, s18
	ds_read_b128 v[184:187], v151 offset:49152
	ds_read_b128 v[188:191], v151 offset:50176
	ds_read_b128 v[192:195], v151 offset:51200
	ds_read_b128 v[196:199], v151 offset:52224
	ds_read_b128 v[200:203], v151 offset:53248
	ds_read_b128 v[204:207], v151 offset:54272
	ds_read_b128 v[208:211], v151 offset:55296
	ds_read_b128 v[212:215], v151 offset:56320
	global_load_lds_dwordx4 v[148:149], off
	s_add_i32 m0, s18, 0x2000
	s_add_u32 s16, s16, 0x20080
	v_lshl_add_u64 v[148:149], v[216:217], 0, s[70:71]
	s_addc_u32 s17, s17, 0
	s_add_i32 s18, s54, s59
	global_load_lds_dwordx4 v[148:149], off
	v_lshl_add_u64 v[148:149], s[16:17], 0, v[132:133]
	s_mov_b32 m0, s18
	s_nop 0
	global_load_lds_dwordx4 v[148:149], off
	v_lshl_add_u64 v[148:149], s[16:17], 0, v[136:137]
	s_add_i32 m0, s18, 0x2000
	s_nop 0
	global_load_lds_dwordx4 v[148:149], off
	v_lshl_add_u64 v[148:149], v[218:219], 0, s[70:71]
	s_mov_b32 m0, s46
	s_nop 0
	global_load_lds_dwordx4 v[148:149], off
	v_lshl_add_u64 v[148:149], v[220:221], 0, s[70:71]
	s_mov_b32 m0, s47
	s_nop 0
	global_load_lds_dwordx4 v[148:149], off
	s_waitcnt vmcnt(8)
	s_waitcnt lgkmcnt(0)
	s_setprio 1
	s_barrier
	v_mfma_f32_16x16x32_bf16 v[94:97], v[144:147], v[184:187], v[94:97]
	v_mfma_f32_16x16x32_bf16 v[90:93], v[156:159], v[184:187], v[90:93]
	v_mfma_f32_16x16x32_bf16 v[86:89], v[144:147], v[192:195], v[86:89]
	v_mfma_f32_16x16x32_bf16 v[82:85], v[156:159], v[192:195], v[82:85]
	v_mfma_f32_16x16x32_bf16 v[78:81], v[144:147], v[200:203], v[78:81]
	v_mfma_f32_16x16x32_bf16 v[74:77], v[156:159], v[200:203], v[74:77]
	v_mfma_f32_16x16x32_bf16 v[70:73], v[144:147], v[208:211], v[70:73]
	v_mfma_f32_16x16x32_bf16 v[66:69], v[156:159], v[208:211], v[66:69]
	v_mfma_f32_16x16x32_bf16 v[94:97], v[152:155], v[188:191], v[94:97]
	v_mfma_f32_16x16x32_bf16 v[90:93], v[160:163], v[188:191], v[90:93]
	v_mfma_f32_16x16x32_bf16 v[86:89], v[152:155], v[196:199], v[86:89]
	v_mfma_f32_16x16x32_bf16 v[82:85], v[160:163], v[196:199], v[82:85]
	v_mfma_f32_16x16x32_bf16 v[78:81], v[152:155], v[204:207], v[78:81]
	v_mfma_f32_16x16x32_bf16 v[74:77], v[160:163], v[204:207], v[74:77]
	v_mfma_f32_16x16x32_bf16 v[70:73], v[152:155], v[212:215], v[70:73]
	v_mfma_f32_16x16x32_bf16 v[66:69], v[160:163], v[212:215], v[66:69]
	v_mfma_f32_16x16x32_bf16 v[30:33], v[164:167], v[184:187], v[30:33]
	v_mfma_f32_16x16x32_bf16 v[26:29], v[172:175], v[184:187], v[26:29]
	v_mfma_f32_16x16x32_bf16 v[22:25], v[164:167], v[192:195], v[22:25]
	v_mfma_f32_16x16x32_bf16 v[18:21], v[172:175], v[192:195], v[18:21]
	v_mfma_f32_16x16x32_bf16 v[14:17], v[164:167], v[200:203], v[14:17]
	v_mfma_f32_16x16x32_bf16 v[10:13], v[172:175], v[200:203], v[10:13]
	v_mfma_f32_16x16x32_bf16 v[6:9], v[164:167], v[208:211], v[6:9]
	v_mfma_f32_16x16x32_bf16 v[2:5], v[172:175], v[208:211], v[2:5]
	v_mfma_f32_16x16x32_bf16 v[30:33], v[168:171], v[188:191], v[30:33]
	v_mfma_f32_16x16x32_bf16 v[26:29], v[180:183], v[188:191], v[26:29]
	v_mfma_f32_16x16x32_bf16 v[22:25], v[168:171], v[196:199], v[22:25]
	v_mfma_f32_16x16x32_bf16 v[18:21], v[180:183], v[196:199], v[18:21]
	v_mfma_f32_16x16x32_bf16 v[14:17], v[168:171], v[204:207], v[14:17]
	v_mfma_f32_16x16x32_bf16 v[10:13], v[180:183], v[204:207], v[10:13]
	v_mfma_f32_16x16x32_bf16 v[6:9], v[168:171], v[212:215], v[6:9]
	v_mfma_f32_16x16x32_bf16 v[2:5], v[180:183], v[212:215], v[2:5]
	s_barrier
	s_setprio 0
	s_add_i32 s52, s52, 2
	s_add_u32 s14, s14, 0x100
	s_addc_u32 s15, s15, 0
	s_add_u32 s45, s45, 0x100
	s_addc_u32 s51, s51, 0
	s_cmp_gt_u32 s52, 5
	s_cbranch_scc0 .LBB0_2619
	v_readlane_b32 s14, v252, 14
	v_readlane_b32 s15, v252, 15
	s_and_b64 vcc, exec, s[14:15]
	s_cbranch_vccz .LBB0_2622
	s_barrier

; #define PG8_STAGE(bufoff, gbase, voff) do { _Pragma("unroll") for (int _i = 0; _i < 2; ++_i) \
;         __builtin_amdgcn_global_load_lds((const unsigned*)((const char*)(gbase) + (voff)[_i]), (LAS unsigned*)(lds + (bufoff) + ldsw + _i * 8192), 16, 0, 0); } while (0)
; #define PG8_LDA(dst, b, h) do { _Pragma("unroll") for (int m = 0; m < 4; ++m) _Pragma("unroll") for (int k = 0; k < 2; ++k) dst[m][k] = *(const LAS bf16x8*)(lds + PG8_SA(b, h) + aoff + m * 2048 + k * 1024); } while (0)
; #define PG8_LDB(dst, b, h) do { _Pragma("unroll") for (int n = 0; n < 2; ++n) _Pragma("unroll") for (int k = 0; k < 2; ++k) dst[n][k] = *(const LAS bf16x8*)(lds + PG8_SB(b, h) + boff + n * 2048 + k * 1024); } while (0)
; #define PG8_MMA(ai, bj, At, Bt) do { __builtin_amdgcn_s_setprio(1); _Pragma("unroll") for (int m = 0; m < 4; ++m) _Pragma("unroll") for (int n = 0; n < 2; ++n) _Pragma("unroll") for (int k = 0; k < 2; ++k) \
;         acc[ai][bj][m][n] = __builtin_amdgcn_mfma_f32_16x16x32_bf16(Bt[n][k], At[m][k], acc[ai][bj][m][n], 0, 0, 0); __builtin_amdgcn_s_setprio(0); } while (0)
; #define PG8_WAIT_V(n) asm volatile("s_waitcnt vmcnt(" #n ")" ::: "memory")
; #define PG8_WAIT_L(n) asm volatile("s_waitcnt lgkmcnt(" #n ")" ::: "memory")
; #define PG8_BAR __builtin_amdgcn_s_barrier()
; #define PG8_SCHED __builtin_amdgcn_sched_barrier(0)
; template <class Epi, class Sched, int LDA, int LDB, bool ALIGN_EPI = true>
; __device__ __forceinline__ void gemm_phase(LAS unsigned char* lds, const Gemm g, const Sched& S, const Epi& E, int wave) {
;     ...
;             const bool last = (t == nt - 2);
;             const char* a1 = cA + (size_t)(t + 1) * kstep;
;             const char* a2 = last ? nA : cA + (size_t)(t + 2) * kstep; const char* b2 = last ? nB : cB + (size_t)(t + 2) * kstep;
;             const char* a3 = a2 + kstep; const char* b3 = b2 + kstep;
;             PG8_LDB(B0, 0, 0); PG8_LDB(B1, 0, 1); PG8_SCHED; PG8_LDA(At, 0, 0); PG8_STAGE(PG8_SA(1, 1), a1 + hstepA, voffA);
;             PG8_WAIT_V(8); PG8_WAIT_L(0); PG8_BAR; PG8_MMA(0, 0, At, B0); PG8_MMA(0, 1, At, B1); PG8_BAR; PG8_SCHED;
;             PG8_LDA(At, 0, 1); PG8_STAGE(PG8_SB(0, 0), b2, voffB); PG8_STAGE(PG8_SB(0, 1), b2 + hstepB, voffB); PG8_STAGE(PG8_SA(0, 0), a2, voffA);
;             PG8_WAIT_V(8); PG8_WAIT_L(0); PG8_BAR; PG8_MMA(1, 0, At, B0); PG8_MMA(1, 1, At, B1); PG8_BAR; PG8_SCHED;
.LBB0_2649:
	s_add_u32 s18, s16, 0xfffe0080
	s_addc_u32 s19, s17, -1
	s_add_i32 s48, 0, 0x10000
	s_cmp_eq_u32 s47, 4
	s_cselect_b32 s25, s7, s19
	s_cselect_b32 s24, s13, s18
	s_cselect_b32 s19, s3, s46
	s_cselect_b32 s18, s44, s45
	s_add_i32 s50, 0, 0x14000
	v_add_u32_e32 v152, s48, v161
	v_add_u32_e32 v172, s50, v161
	ds_read_b128 v[130:133], v152
	ds_read_b128 v[134:137], v152 offset:1024
	ds_read_b128 v[148:151], v152 offset:2048
	ds_read_b128 v[152:155], v152 offset:3072
	ds_read_b128 v[156:159], v172
	ds_read_b128 v[164:167], v172 offset:1024
	ds_read_b128 v[168:171], v172 offset:2048
	ds_read_b128 v[172:175], v172 offset:3072
	v_lshl_add_u64 v[212:213], s[16:17], 0, v[144:145]
	s_add_i32 m0, s15, 0xc000
	ds_read_b128 v[180:183], v163
	ds_read_b128 v[184:187], v163 offset:1024
	ds_read_b128 v[188:191], v163 offset:2048
	ds_read_b128 v[192:195], v163 offset:3072
	ds_read_b128 v[196:199], v163 offset:4096
	ds_read_b128 v[200:203], v163 offset:5120
	ds_read_b128 v[204:207], v163 offset:6144
	ds_read_b128 v[208:211], v163 offset:7168
	global_load_lds_dwordx4 v[212:213], off
	v_lshl_add_u64 v[212:213], s[16:17], 0, v[146:147]
	s_add_i32 m0, s15, 0xe000
	s_nop 0
	global_load_lds_dwordx4 v[212:213], off
	s_waitcnt vmcnt(8)
	s_waitcnt lgkmcnt(0)
	s_setprio 1
	s_barrier
	v_mfma_f32_16x16x32_bf16 v[126:129], v[130:133], v[180:183], v[126:129]
	v_mfma_f32_16x16x32_bf16 v[122:125], v[148:151], v[180:183], v[122:125]
	v_mfma_f32_16x16x32_bf16 v[110:113], v[130:133], v[188:191], v[110:113]
	v_mfma_f32_16x16x32_bf16 v[106:109], v[148:151], v[188:191], v[106:109]
	v_mfma_f32_16x16x32_bf16 v[94:97], v[130:133], v[196:199], v[94:97]
	v_mfma_f32_16x16x32_bf16 v[90:93], v[148:151], v[196:199], v[90:93]
	v_mfma_f32_16x16x32_bf16 v[78:81], v[130:133], v[204:207], v[78:81]
	v_mfma_f32_16x16x32_bf16 v[74:77], v[148:151], v[204:207], v[74:77]
	v_mfma_f32_16x16x32_bf16 v[126:129], v[134:137], v[184:187], v[126:129]
	v_mfma_f32_16x16x32_bf16 v[122:125], v[152:155], v[184:187], v[122:125]
	v_mfma_f32_16x16x32_bf16 v[110:113], v[134:137], v[192:195], v[110:113]
	v_mfma_f32_16x16x32_bf16 v[106:109], v[152:155], v[192:195], v[106:109]
	v_mfma_f32_16x16x32_bf16 v[94:97], v[134:137], v[200:203], v[94:97]
	v_mfma_f32_16x16x32_bf16 v[90:93], v[152:155], v[200:203], v[90:93]
	v_mfma_f32_16x16x32_bf16 v[78:81], v[134:137], v[208:211], v[78:81]
	v_mfma_f32_16x16x32_bf16 v[74:77], v[152:155], v[208:211], v[74:77]
	v_mfma_f32_16x16x32_bf16 v[118:121], v[156:159], v[180:183], v[118:121]
	v_mfma_f32_16x16x32_bf16 v[114:117], v[168:171], v[180:183], v[114:117]
	v_mfma_f32_16x16x32_bf16 v[102:105], v[156:159], v[188:191], v[102:105]
	v_mfma_f32_16x16x32_bf16 v[98:101], v[168:171], v[188:191], v[98:101]
	v_mfma_f32_16x16x32_bf16 v[86:89], v[156:159], v[196:199], v[86:89]
	v_mfma_f32_16x16x32_bf16 v[82:85], v[168:171], v[196:199], v[82:85]
	v_mfma_f32_16x16x32_bf16 v[70:73], v[156:159], v[204:207], v[70:73]
	v_mfma_f32_16x16x32_bf16 v[66:69], v[168:171], v[204:207], v[66:69]
	v_mfma_f32_16x16x32_bf16 v[118:121], v[164:167], v[184:187], v[118:121]
	v_mfma_f32_16x16x32_bf16 v[114:117], v[172:175], v[184:187], v[114:117]
	v_mfma_f32_16x16x32_bf16 v[102:105], v[164:167], v[192:195], v[102:105]
	v_mfma_f32_16x16x32_bf16 v[98:101], v[172:175], v[192:195], v[98:101]
	v_mfma_f32_16x16x32_bf16 v[86:89], v[164:167], v[200:203], v[86:89]
	v_mfma_f32_16x16x32_bf16 v[82:85], v[172:175], v[200:203], v[82:85]
	v_mfma_f32_16x16x32_bf16 v[70:73], v[164:167], v[208:211], v[70:73]
	v_mfma_f32_16x16x32_bf16 v[66:69], v[172:175], v[208:211], v[66:69]
	s_barrier
	s_setprio 0
	s_add_i32 s48, s48, s51
	v_lshl_add_u64 v[212:213], s[18:19], 0, v[0:1]
	s_mov_b32 m0, s48
	ds_read_b128 v[180:183], v163 offset:16384
	ds_read_b128 v[184:187], v163 offset:17408
	ds_read_b128 v[188:191], v163 offset:18432
	ds_read_b128 v[192:195], v163 offset:19456
	ds_read_b128 v[196:199], v163 offset:20480
	ds_read_b128 v[200:203], v163 offset:21504
	ds_read_b128 v[204:207], v163 offset:22528
	ds_read_b128 v[208:211], v163 offset:23552
	global_load_lds_dwordx4 v[212:213], off
	s_add_i32 m0, s48, 0x2000
	s_add_u32 s48, s18, 0x20000
	v_lshl_add_u64 v[214:215], s[18:19], 0, v[142:143]
	s_addc_u32 s49, s19, 0
	s_add_i32 s50, s50, s51
	global_load_lds_dwordx4 v[214:215], off
	v_lshl_add_u64 v[216:217], s[48:49], 0, v[0:1]
	s_mov_b32 m0, s50
	v_lshl_add_u64 v[218:219], s[24:25], 0, v[140:141]
	global_load_lds_dwordx4 v[216:217], off
	v_lshl_add_u64 v[216:217], s[48:49], 0, v[142:143]
	s_add_i32 m0, s50, 0x2000
	s_nop 0
	global_load_lds_dwordx4 v[216:217], off
	v_lshl_add_u64 v[216:217], s[24:25], 0, v[138:139]
	s_mov_b32 m0, s15
	s_nop 0
	global_load_lds_dwordx4 v[216:217], off
	s_mov_b32 m0, s28
	s_nop 0
	global_load_lds_dwordx4 v[218:219], off
	s_waitcnt vmcnt(8)
	s_waitcnt lgkmcnt(0)
	s_setprio 1
	s_barrier
; #define PG8_STAGE(bufoff, gbase, voff) do { _Pragma("unroll") for (int _i = 0; _i < 2; ++_i) \
;         __builtin_amdgcn_global_load_lds((const unsigned*)((const char*)(gbase) + (voff)[_i]), (LAS unsigned*)(lds + (bufoff) + ldsw + _i * 8192), 16, 0, 0); } while (0)
; #define PG8_LDA(dst, b, h) do { _Pragma("unroll") for (int m = 0; m < 4; ++m) _Pragma("unroll") for (int k = 0; k < 2; ++k) dst[m][k] = *(const LAS bf16x8*)(lds + PG8_SA(b, h) + aoff + m * 2048 + k * 1024); } while (0)
; #define PG8_LDB(dst, b, h) do { _Pragma("unroll") for (int n = 0; n < 2; ++n) _Pragma("unroll") for (int k = 0; k < 2; ++k) dst[n][k] = *(const LAS bf16x8*)(lds + PG8_SB(b, h) + boff + n * 2048 + k * 1024); } while (0)
; #define PG8_MMA(ai, bj, At, Bt) do { __builtin_amdgcn_s_setprio(1); _Pragma("unroll") for (int m = 0; m < 4; ++m) _Pragma("unroll") for (int n = 0; n < 2; ++n) _Pragma("unroll") for (int k = 0; k < 2; ++k) \
;         acc[ai][bj][m][n] = __builtin_amdgcn_mfma_f32_16x16x32_bf16(Bt[n][k], At[m][k], acc[ai][bj][m][n], 0, 0, 0); __builtin_amdgcn_s_setprio(0); } while (0)
; #define PG8_WAIT_V(n) asm volatile("s_waitcnt vmcnt(" #n ")" ::: "memory")
; #define PG8_WAIT_L(n) asm volatile("s_waitcnt lgkmcnt(" #n ")" ::: "memory")
; #define PG8_BAR __builtin_amdgcn_s_barrier()
; #define PG8_SCHED __builtin_amdgcn_sched_barrier(0)
; template <class Epi, class Sched, int LDA, int LDB, bool ALIGN_EPI = true>
; __device__ __forceinline__ void gemm_phase(LAS unsigned char* lds, const Gemm g, const Sched& S, const Epi& E, int wave) {
;     ...
;             PG8_WAIT_V(8); PG8_WAIT_L(0); PG8_BAR; PG8_MMA(1, 0, At, B0); PG8_MMA(1, 1, At, B1); PG8_BAR; PG8_SCHED;
;             PG8_LDB(B0, 1, 0); PG8_LDB(B1, 1, 1); PG8_SCHED; PG8_LDA(At, 1, 0); PG8_STAGE(PG8_SA(0, 1), a2 + hstepA, voffA);
;             PG8_WAIT_V(8); PG8_WAIT_L(0); PG8_BAR; PG8_MMA(0, 0, At, B0); PG8_MMA(0, 1, At, B1); PG8_BAR; PG8_SCHED;
	v_mfma_f32_16x16x32_bf16 v[62:65], v[130:133], v[180:183], v[62:65]
	v_mfma_f32_16x16x32_bf16 v[58:61], v[148:151], v[180:183], v[58:61]
	v_mfma_f32_16x16x32_bf16 v[46:49], v[130:133], v[188:191], v[46:49]
	v_mfma_f32_16x16x32_bf16 v[42:45], v[148:151], v[188:191], v[42:45]
	v_mfma_f32_16x16x32_bf16 v[30:33], v[130:133], v[196:199], v[30:33]
	v_mfma_f32_16x16x32_bf16 v[26:29], v[148:151], v[196:199], v[26:29]
	v_mfma_f32_16x16x32_bf16 v[14:17], v[130:133], v[204:207], v[14:17]
	v_mfma_f32_16x16x32_bf16 v[10:13], v[148:151], v[204:207], v[10:13]
	v_mfma_f32_16x16x32_bf16 v[62:65], v[134:137], v[184:187], v[62:65]
	v_mfma_f32_16x16x32_bf16 v[58:61], v[152:155], v[184:187], v[58:61]
	v_mfma_f32_16x16x32_bf16 v[46:49], v[134:137], v[192:195], v[46:49]
	v_mfma_f32_16x16x32_bf16 v[42:45], v[152:155], v[192:195], v[42:45]
	v_mfma_f32_16x16x32_bf16 v[30:33], v[134:137], v[200:203], v[30:33]
	v_mfma_f32_16x16x32_bf16 v[26:29], v[152:155], v[200:203], v[26:29]
	v_mfma_f32_16x16x32_bf16 v[14:17], v[134:137], v[208:211], v[14:17]
	v_mfma_f32_16x16x32_bf16 v[10:13], v[152:155], v[208:211], v[10:13]
	v_mfma_f32_16x16x32_bf16 v[54:57], v[156:159], v[180:183], v[54:57]
	v_mfma_f32_16x16x32_bf16 v[50:53], v[168:171], v[180:183], v[50:53]
	v_mfma_f32_16x16x32_bf16 v[38:41], v[156:159], v[188:191], v[38:41]
	v_mfma_f32_16x16x32_bf16 v[34:37], v[168:171], v[188:191], v[34:37]
	v_mfma_f32_16x16x32_bf16 v[22:25], v[156:159], v[196:199], v[22:25]
	v_mfma_f32_16x16x32_bf16 v[18:21], v[168:171], v[196:199], v[18:21]
	v_mfma_f32_16x16x32_bf16 v[6:9], v[156:159], v[204:207], v[6:9]
	v_mfma_f32_16x16x32_bf16 v[2:5], v[168:171], v[204:207], v[2:5]
	v_mfma_f32_16x16x32_bf16 v[54:57], v[164:167], v[184:187], v[54:57]
	v_mfma_f32_16x16x32_bf16 v[50:53], v[172:175], v[184:187], v[50:53]
	v_mfma_f32_16x16x32_bf16 v[38:41], v[164:167], v[192:195], v[38:41]
	v_mfma_f32_16x16x32_bf16 v[34:37], v[172:175], v[192:195], v[34:37]
	v_mfma_f32_16x16x32_bf16 v[22:25], v[164:167], v[200:203], v[22:25]
	v_mfma_f32_16x16x32_bf16 v[18:21], v[172:175], v[200:203], v[18:21]
	v_mfma_f32_16x16x32_bf16 v[6:9], v[164:167], v[208:211], v[6:9]
	v_mfma_f32_16x16x32_bf16 v[2:5], v[172:175], v[208:211], v[2:5]
	s_barrier
	s_setprio 0
	s_add_i32 s48, 0, 0x18000
	s_add_i32 s49, 0, 0x1c000
	v_add_u32_e32 v152, s48, v161
	v_add_u32_e32 v172, s49, v161
	ds_read_b128 v[130:133], v152
	ds_read_b128 v[134:137], v152 offset:1024
	ds_read_b128 v[148:151], v152 offset:2048
	ds_read_b128 v[152:155], v152 offset:3072
	ds_read_b128 v[156:159], v172
	ds_read_b128 v[164:167], v172 offset:1024
	ds_read_b128 v[168:171], v172 offset:2048
	ds_read_b128 v[172:175], v172 offset:3072
	s_add_u32 s24, s24, 0x20000
	s_addc_u32 s25, s25, 0
	s_mov_b32 m0, s29
	v_lshl_add_u64 v[220:221], s[24:25], 0, v[138:139]
	ds_read_b128 v[180:183], v163 offset:32768
	ds_read_b128 v[184:187], v163 offset:33792
	ds_read_b128 v[188:191], v163 offset:34816
	ds_read_b128 v[192:195], v163 offset:35840
	ds_read_b128 v[196:199], v163 offset:36864
	ds_read_b128 v[200:203], v163 offset:37888
	ds_read_b128 v[204:207], v163 offset:38912
	ds_read_b128 v[208:211], v163 offset:39936
	global_load_lds_dwordx4 v[220:221], off
	v_lshl_add_u64 v[220:221], s[24:25], 0, v[140:141]
	s_mov_b32 m0, s34
	s_nop 0
	global_load_lds_dwordx4 v[220:221], off
	s_waitcnt vmcnt(8)
	s_waitcnt lgkmcnt(0)
	s_setprio 1
	s_barrier
	v_mfma_f32_16x16x32_bf16 v[126:129], v[130:133], v[180:183], v[126:129]
	v_mfma_f32_16x16x32_bf16 v[122:125], v[148:151], v[180:183], v[122:125]
	v_mfma_f32_16x16x32_bf16 v[110:113], v[130:133], v[188:191], v[110:113]
	v_mfma_f32_16x16x32_bf16 v[106:109], v[148:151], v[188:191], v[106:109]
	v_mfma_f32_16x16x32_bf16 v[94:97], v[130:133], v[196:199], v[94:97]
	v_mfma_f32_16x16x32_bf16 v[90:93], v[148:151], v[196:199], v[90:93]
	v_mfma_f32_16x16x32_bf16 v[78:81], v[130:133], v[204:207], v[78:81]
	v_mfma_f32_16x16x32_bf16 v[74:77], v[148:151], v[204:207], v[74:77]
	v_mfma_f32_16x16x32_bf16 v[126:129], v[134:137], v[184:187], v[126:129]
	v_mfma_f32_16x16x32_bf16 v[122:125], v[152:155], v[184:187], v[122:125]
	v_mfma_f32_16x16x32_bf16 v[110:113], v[134:137], v[192:195], v[110:113]
	v_mfma_f32_16x16x32_bf16 v[106:109], v[152:155], v[192:195], v[106:109]
	v_mfma_f32_16x16x32_bf16 v[94:97], v[134:137], v[200:203], v[94:97]
	v_mfma_f32_16x16x32_bf16 v[90:93], v[152:155], v[200:203], v[90:93]
	v_mfma_f32_16x16x32_bf16 v[78:81], v[134:137], v[208:211], v[78:81]
	v_mfma_f32_16x16x32_bf16 v[74:77], v[152:155], v[208:211], v[74:77]
	v_mfma_f32_16x16x32_bf16 v[118:121], v[156:159], v[180:183], v[118:121]
	v_mfma_f32_16x16x32_bf16 v[114:117], v[168:171], v[180:183], v[114:117]
	v_mfma_f32_16x16x32_bf16 v[102:105], v[156:159], v[188:191], v[102:105]
	v_mfma_f32_16x16x32_bf16 v[98:101], v[168:171], v[188:191], v[98:101]
	v_mfma_f32_16x16x32_bf16 v[86:89], v[156:159], v[196:199], v[86:89]
	v_mfma_f32_16x16x32_bf16 v[82:85], v[168:171], v[196:199], v[82:85]
	v_mfma_f32_16x16x32_bf16 v[70:73], v[156:159], v[204:207], v[70:73]
	v_mfma_f32_16x16x32_bf16 v[66:69], v[168:171], v[204:207], v[66:69]
	v_mfma_f32_16x16x32_bf16 v[118:121], v[164:167], v[184:187], v[118:121]
	v_mfma_f32_16x16x32_bf16 v[114:117], v[172:175], v[184:187], v[114:117]
	v_mfma_f32_16x16x32_bf16 v[102:105], v[164:167], v[192:195], v[102:105]
	v_mfma_f32_16x16x32_bf16 v[98:101], v[172:175], v[192:195], v[98:101]
	v_mfma_f32_16x16x32_bf16 v[86:89], v[164:167], v[200:203], v[86:89]
	v_mfma_f32_16x16x32_bf16 v[82:85], v[172:175], v[200:203], v[82:85]
	v_mfma_f32_16x16x32_bf16 v[70:73], v[164:167], v[208:211], v[70:73]
	v_mfma_f32_16x16x32_bf16 v[66:69], v[172:175], v[208:211], v[66:69]
	s_barrier
; #define PG8_STAGE(bufoff, gbase, voff) do { _Pragma("unroll") for (int _i = 0; _i < 2; ++_i) \
;         __builtin_amdgcn_global_load_lds((const unsigned*)((const char*)(gbase) + (voff)[_i]), (LAS unsigned*)(lds + (bufoff) + ldsw + _i * 8192), 16, 0, 0); } while (0)
; #define PG8_LDA(dst, b, h) do { _Pragma("unroll") for (int m = 0; m < 4; ++m) _Pragma("unroll") for (int k = 0; k < 2; ++k) dst[m][k] = *(const LAS bf16x8*)(lds + PG8_SA(b, h) + aoff + m * 2048 + k * 1024); } while (0)
; #define PG8_MMA(ai, bj, At, Bt) do { __builtin_amdgcn_s_setprio(1); _Pragma("unroll") for (int m = 0; m < 4; ++m) _Pragma("unroll") for (int n = 0; n < 2; ++n) _Pragma("unroll") for (int k = 0; k < 2; ++k) \
;         acc[ai][bj][m][n] = __builtin_amdgcn_mfma_f32_16x16x32_bf16(Bt[n][k], At[m][k], acc[ai][bj][m][n], 0, 0, 0); __builtin_amdgcn_s_setprio(0); } while (0)
; #define PG8_WAIT_V(n) asm volatile("s_waitcnt vmcnt(" #n ")" ::: "memory")
; #define PG8_WAIT_L(n) asm volatile("s_waitcnt lgkmcnt(" #n ")" ::: "memory")
; #define PG8_BAR __builtin_amdgcn_s_barrier()
; #define PG8_SCHED __builtin_amdgcn_sched_barrier(0)
; template <class Epi, class Sched, int LDA, int LDB, bool ALIGN_EPI = true>
; __device__ __forceinline__ void gemm_phase(LAS unsigned char* lds, const Gemm g, const Sched& S, const Epi& E, int wave) {
;     ...
;             PG8_LDA(At, 1, 1); PG8_STAGE(PG8_SB(1, 0), b3, voffB); PG8_STAGE(PG8_SB(1, 1), b3 + hstepB, voffB); PG8_STAGE(PG8_SA(1, 0), a3, voffA);
;             PG8_WAIT_V(8); PG8_WAIT_L(0); PG8_BAR; PG8_MMA(1, 0, At, B0); PG8_MMA(1, 1, At, B1); PG8_BAR; PG8_SCHED;
;         }
	s_setprio 0
	s_add_i32 s24, s48, s51
	v_lshl_add_u64 v[212:213], v[212:213], 0, s[52:53]
	s_mov_b32 m0, s24
	ds_read_b128 v[180:183], v163 offset:49152
	ds_read_b128 v[184:187], v163 offset:50176
	ds_read_b128 v[188:191], v163 offset:51200
	ds_read_b128 v[192:195], v163 offset:52224
	ds_read_b128 v[196:199], v163 offset:53248
	ds_read_b128 v[200:203], v163 offset:54272
	ds_read_b128 v[204:207], v163 offset:55296
	ds_read_b128 v[208:211], v163 offset:56320
	global_load_lds_dwordx4 v[212:213], off
	s_add_i32 m0, s24, 0x2000
	s_add_u32 s18, s18, 0x20080
	v_lshl_add_u64 v[212:213], v[214:215], 0, s[52:53]
	s_addc_u32 s19, s19, 0
	s_add_i32 s24, s49, s51
	global_load_lds_dwordx4 v[212:213], off
	v_lshl_add_u64 v[212:213], s[18:19], 0, v[0:1]
	s_mov_b32 m0, s24
	s_nop 0
	global_load_lds_dwordx4 v[212:213], off
	v_lshl_add_u64 v[212:213], s[18:19], 0, v[142:143]
	s_add_i32 m0, s24, 0x2000
	s_nop 0
	global_load_lds_dwordx4 v[212:213], off
	v_lshl_add_u64 v[212:213], v[216:217], 0, s[52:53]
	s_mov_b32 m0, s35
	s_nop 0
	global_load_lds_dwordx4 v[212:213], off
	v_lshl_add_u64 v[212:213], v[218:219], 0, s[52:53]
	s_mov_b32 m0, s36
	s_nop 0
	global_load_lds_dwordx4 v[212:213], off
	s_waitcnt vmcnt(8)
	s_waitcnt lgkmcnt(0)
	s_setprio 1
	s_barrier
	v_mfma_f32_16x16x32_bf16 v[62:65], v[130:133], v[180:183], v[62:65]
	v_mfma_f32_16x16x32_bf16 v[58:61], v[148:151], v[180:183], v[58:61]
	v_mfma_f32_16x16x32_bf16 v[46:49], v[130:133], v[188:191], v[46:49]
	v_mfma_f32_16x16x32_bf16 v[42:45], v[148:151], v[188:191], v[42:45]
	v_mfma_f32_16x16x32_bf16 v[30:33], v[130:133], v[196:199], v[30:33]
	v_mfma_f32_16x16x32_bf16 v[26:29], v[148:151], v[196:199], v[26:29]
	v_mfma_f32_16x16x32_bf16 v[14:17], v[130:133], v[204:207], v[14:17]
	v_mfma_f32_16x16x32_bf16 v[10:13], v[148:151], v[204:207], v[10:13]
	v_mfma_f32_16x16x32_bf16 v[62:65], v[134:137], v[184:187], v[62:65]
	v_mfma_f32_16x16x32_bf16 v[58:61], v[152:155], v[184:187], v[58:61]
	v_mfma_f32_16x16x32_bf16 v[46:49], v[134:137], v[192:195], v[46:49]
	v_mfma_f32_16x16x32_bf16 v[42:45], v[152:155], v[192:195], v[42:45]
	v_mfma_f32_16x16x32_bf16 v[30:33], v[134:137], v[200:203], v[30:33]
	v_mfma_f32_16x16x32_bf16 v[26:29], v[152:155], v[200:203], v[26:29]
	v_mfma_f32_16x16x32_bf16 v[14:17], v[134:137], v[208:211], v[14:17]
	v_mfma_f32_16x16x32_bf16 v[10:13], v[152:155], v[208:211], v[10:13]
	v_mfma_f32_16x16x32_bf16 v[54:57], v[156:159], v[180:183], v[54:57]
	v_mfma_f32_16x16x32_bf16 v[50:53], v[168:171], v[180:183], v[50:53]
	v_mfma_f32_16x16x32_bf16 v[38:41], v[156:159], v[188:191], v[38:41]
	v_mfma_f32_16x16x32_bf16 v[34:37], v[168:171], v[188:191], v[34:37]
	v_mfma_f32_16x16x32_bf16 v[22:25], v[156:159], v[196:199], v[22:25]
	v_mfma_f32_16x16x32_bf16 v[18:21], v[168:171], v[196:199], v[18:21]
	v_mfma_f32_16x16x32_bf16 v[6:9], v[156:159], v[204:207], v[6:9]
	v_mfma_f32_16x16x32_bf16 v[2:5], v[168:171], v[204:207], v[2:5]
	v_mfma_f32_16x16x32_bf16 v[54:57], v[164:167], v[184:187], v[54:57]
	v_mfma_f32_16x16x32_bf16 v[50:53], v[172:175], v[184:187], v[50:53]
	v_mfma_f32_16x16x32_bf16 v[38:41], v[164:167], v[192:195], v[38:41]
	v_mfma_f32_16x16x32_bf16 v[34:37], v[172:175], v[192:195], v[34:37]
	v_mfma_f32_16x16x32_bf16 v[22:25], v[164:167], v[200:203], v[22:25]
	v_mfma_f32_16x16x32_bf16 v[18:21], v[172:175], v[200:203], v[18:21]
	v_mfma_f32_16x16x32_bf16 v[6:9], v[164:167], v[208:211], v[6:9]
	v_mfma_f32_16x16x32_bf16 v[2:5], v[172:175], v[208:211], v[2:5]
	s_barrier
	s_setprio 0
	s_add_i32 s47, s47, 2
	s_add_u32 s16, s16, 0x100
	s_addc_u32 s17, s17, 0
	s_add_u32 s45, s45, 0x100
	s_addc_u32 s46, s46, 0
	s_cmp_gt_u32 s47, 5
	s_cbranch_scc0 .LBB0_2649
	v_readlane_b32 s16, v252, 14
	v_readlane_b32 s17, v252, 15
	s_and_b64 vcc, exec, s[16:17]
	s_cbranch_vccz .LBB0_2652
	s_barrier

; #define PG8_STAGE(bufoff, gbase, voff) do { _Pragma("unroll") for (int _i = 0; _i < 2; ++_i) \
;         __builtin_amdgcn_global_load_lds((const unsigned*)((const char*)(gbase) + (voff)[_i]), (LAS unsigned*)(lds + (bufoff) + ldsw + _i * 8192), 16, 0, 0); } while (0)
; #define PG8_LDA(dst, b, h) do { _Pragma("unroll") for (int m = 0; m < 4; ++m) _Pragma("unroll") for (int k = 0; k < 2; ++k) dst[m][k] = *(const LAS bf16x8*)(lds + PG8_SA(b, h) + aoff + m * 2048 + k * 1024); } while (0)
; #define PG8_LDB(dst, b, h) do { _Pragma("unroll") for (int n = 0; n < 2; ++n) _Pragma("unroll") for (int k = 0; k < 2; ++k) dst[n][k] = *(const LAS bf16x8*)(lds + PG8_SB(b, h) + boff + n * 2048 + k * 1024); } while (0)
; #define PG8_MMA(ai, bj, At, Bt) do { __builtin_amdgcn_s_setprio(1); _Pragma("unroll") for (int m = 0; m < 4; ++m) _Pragma("unroll") for (int n = 0; n < 2; ++n) _Pragma("unroll") for (int k = 0; k < 2; ++k) \
;         acc[ai][bj][m][n] = __builtin_amdgcn_mfma_f32_16x16x32_bf16(Bt[n][k], At[m][k], acc[ai][bj][m][n], 0, 0, 0); __builtin_amdgcn_s_setprio(0); } while (0)
; #define PG8_WAIT_V(n) asm volatile("s_waitcnt vmcnt(" #n ")" ::: "memory")
; #define PG8_WAIT_L(n) asm volatile("s_waitcnt lgkmcnt(" #n ")" ::: "memory")
; #define PG8_BAR __builtin_amdgcn_s_barrier()
; #define PG8_SCHED __builtin_amdgcn_sched_barrier(0)
; template <class Epi, class Sched, int LDA, int LDB, bool ALIGN_EPI = true>
; __device__ __forceinline__ void gemm_phase(LAS unsigned char* lds, const Gemm g, const Sched& S, const Epi& E, int wave) {
;     ...
;             const bool last = (t == nt - 2);
;             const char* a1 = cA + (size_t)(t + 1) * kstep;
;             const char* a2 = last ? nA : cA + (size_t)(t + 2) * kstep; const char* b2 = last ? nB : cB + (size_t)(t + 2) * kstep;
;             const char* a3 = a2 + kstep; const char* b3 = b2 + kstep;
;             PG8_LDB(B0, 0, 0); PG8_LDB(B1, 0, 1); PG8_SCHED; PG8_LDA(At, 0, 0); PG8_STAGE(PG8_SA(1, 1), a1 + hstepA, voffA);
;             PG8_WAIT_V(8); PG8_WAIT_L(0); PG8_BAR; PG8_MMA(0, 0, At, B0); PG8_MMA(0, 1, At, B1); PG8_BAR; PG8_SCHED;
;             PG8_LDA(At, 0, 1); PG8_STAGE(PG8_SB(0, 0), b2, voffB); PG8_STAGE(PG8_SB(0, 1), b2 + hstepB, voffB); PG8_STAGE(PG8_SA(0, 0), a2, voffA);
;             PG8_WAIT_V(8); PG8_WAIT_L(0); PG8_BAR; PG8_MMA(1, 0, At, B0); PG8_MMA(1, 1, At, B1); PG8_BAR; PG8_SCHED;
.LBB0_4715:
	s_add_i32 s49, s24, 2
	s_add_u32 s25, s18, 0xfff80080
	s_addc_u32 s28, s19, -1
	s_add_i32 s50, 0, 0x10000
	s_cmp_eq_u32 s17, s24
	s_cselect_b32 s29, s1, s28
	s_cselect_b32 s28, s7, s25
	v_add_u32_e32 v0, s50, v153
	s_cselect_b32 s25, s3, s45
	s_cselect_b32 s24, s15, s44
	s_add_i32 s52, 0, 0x14000
	ds_read_b128 v[144:147], v0
	ds_read_b128 v[148:151], v0 offset:1024
	ds_read_b128 v[156:159], v0 offset:2048
	ds_read_b128 v[160:163], v0 offset:3072
	v_add_u32_e32 v0, s52, v153
	ds_read_b128 v[164:167], v0
	ds_read_b128 v[168:171], v0 offset:1024
	ds_read_b128 v[172:175], v0 offset:2048
	ds_read_b128 v[180:183], v0 offset:3072
	v_lshl_add_u64 v[216:217], s[18:19], 0, v[140:141]
	s_add_i32 m0, s27, 0xc000
	ds_read_b128 v[184:187], v155
	ds_read_b128 v[188:191], v155 offset:1024
	ds_read_b128 v[192:195], v155 offset:2048
	ds_read_b128 v[196:199], v155 offset:3072
	ds_read_b128 v[200:203], v155 offset:4096
	ds_read_b128 v[204:207], v155 offset:5120
	ds_read_b128 v[208:211], v155 offset:6144
	ds_read_b128 v[212:215], v155 offset:7168
	global_load_lds_dwordx4 v[216:217], off
	v_lshl_add_u64 v[216:217], s[18:19], 0, v[142:143]
	s_add_i32 m0, s27, 0xe000
	s_nop 0
	global_load_lds_dwordx4 v[216:217], off
	s_waitcnt vmcnt(8)
	s_waitcnt lgkmcnt(0)
	s_setprio 1
	s_barrier
	v_mfma_f32_16x16x32_bf16 v[126:129], v[144:147], v[184:187], v[126:129]
	v_mfma_f32_16x16x32_bf16 v[122:125], v[156:159], v[184:187], v[122:125]
	v_mfma_f32_16x16x32_bf16 v[110:113], v[144:147], v[192:195], v[110:113]
	v_mfma_f32_16x16x32_bf16 v[106:109], v[156:159], v[192:195], v[106:109]
	v_mfma_f32_16x16x32_bf16 v[94:97], v[144:147], v[200:203], v[94:97]
	v_mfma_f32_16x16x32_bf16 v[90:93], v[156:159], v[200:203], v[90:93]
	v_mfma_f32_16x16x32_bf16 v[78:81], v[144:147], v[208:211], v[78:81]
	v_mfma_f32_16x16x32_bf16 v[74:77], v[156:159], v[208:211], v[74:77]
	v_mfma_f32_16x16x32_bf16 v[126:129], v[148:151], v[188:191], v[126:129]
	v_mfma_f32_16x16x32_bf16 v[122:125], v[160:163], v[188:191], v[122:125]
	v_mfma_f32_16x16x32_bf16 v[110:113], v[148:151], v[196:199], v[110:113]
	v_mfma_f32_16x16x32_bf16 v[106:109], v[160:163], v[196:199], v[106:109]
	v_mfma_f32_16x16x32_bf16 v[94:97], v[148:151], v[204:207], v[94:97]
	v_mfma_f32_16x16x32_bf16 v[90:93], v[160:163], v[204:207], v[90:93]
	v_mfma_f32_16x16x32_bf16 v[78:81], v[148:151], v[212:215], v[78:81]
	v_mfma_f32_16x16x32_bf16 v[74:77], v[160:163], v[212:215], v[74:77]
	v_mfma_f32_16x16x32_bf16 v[118:121], v[164:167], v[184:187], v[118:121]
	v_mfma_f32_16x16x32_bf16 v[114:117], v[172:175], v[184:187], v[114:117]
	v_mfma_f32_16x16x32_bf16 v[102:105], v[164:167], v[192:195], v[102:105]
	v_mfma_f32_16x16x32_bf16 v[98:101], v[172:175], v[192:195], v[98:101]
	v_mfma_f32_16x16x32_bf16 v[86:89], v[164:167], v[200:203], v[86:89]
	v_mfma_f32_16x16x32_bf16 v[82:85], v[172:175], v[200:203], v[82:85]
	v_mfma_f32_16x16x32_bf16 v[70:73], v[164:167], v[208:211], v[70:73]
	v_mfma_f32_16x16x32_bf16 v[66:69], v[172:175], v[208:211], v[66:69]
	v_mfma_f32_16x16x32_bf16 v[118:121], v[168:171], v[188:191], v[118:121]
	v_mfma_f32_16x16x32_bf16 v[114:117], v[180:183], v[188:191], v[114:117]
	v_mfma_f32_16x16x32_bf16 v[102:105], v[168:171], v[196:199], v[102:105]
	v_mfma_f32_16x16x32_bf16 v[98:101], v[180:183], v[196:199], v[98:101]
	v_mfma_f32_16x16x32_bf16 v[86:89], v[168:171], v[204:207], v[86:89]
	v_mfma_f32_16x16x32_bf16 v[82:85], v[180:183], v[204:207], v[82:85]
	v_mfma_f32_16x16x32_bf16 v[70:73], v[168:171], v[212:215], v[70:73]
	v_mfma_f32_16x16x32_bf16 v[66:69], v[180:183], v[212:215], v[66:69]
	s_barrier
	s_setprio 0
	s_add_i32 s50, s50, s53
	v_lshl_add_u64 v[216:217], s[24:25], 0, v[132:133]
	s_mov_b32 m0, s50
	ds_read_b128 v[184:187], v155 offset:16384
	ds_read_b128 v[188:191], v155 offset:17408
	ds_read_b128 v[192:195], v155 offset:18432
	ds_read_b128 v[196:199], v155 offset:19456
	ds_read_b128 v[200:203], v155 offset:20480
	ds_read_b128 v[204:207], v155 offset:21504
	ds_read_b128 v[208:211], v155 offset:22528
	ds_read_b128 v[212:215], v155 offset:23552
	global_load_lds_dwordx4 v[216:217], off
	s_add_i32 m0, s50, 0x2000
	s_add_u32 s50, s24, 0x80000
	v_lshl_add_u64 v[218:219], s[24:25], 0, v[136:137]
	s_addc_u32 s51, s25, 0
	s_add_i32 s52, s52, s53
	global_load_lds_dwordx4 v[218:219], off
	v_lshl_add_u64 v[220:221], s[50:51], 0, v[132:133]
	s_mov_b32 m0, s52
	v_lshl_add_u64 v[222:223], s[28:29], 0, v[134:135]
	global_load_lds_dwordx4 v[220:221], off
	v_lshl_add_u64 v[220:221], s[50:51], 0, v[136:137]
	s_add_i32 m0, s52, 0x2000
	s_nop 0
	global_load_lds_dwordx4 v[220:221], off
	v_lshl_add_u64 v[220:221], s[28:29], 0, v[130:131]
	s_mov_b32 m0, s27
	s_nop 0
	global_load_lds_dwordx4 v[220:221], off
	s_mov_b32 m0, s34
	s_nop 0
	global_load_lds_dwordx4 v[222:223], off
	s_waitcnt vmcnt(8)
	s_waitcnt lgkmcnt(0)
	s_setprio 1
	s_barrier
; #define PG8_STAGE(bufoff, gbase, voff) do { _Pragma("unroll") for (int _i = 0; _i < 2; ++_i) \
;         __builtin_amdgcn_global_load_lds((const unsigned*)((const char*)(gbase) + (voff)[_i]), (LAS unsigned*)(lds + (bufoff) + ldsw + _i * 8192), 16, 0, 0); } while (0)
; #define PG8_LDA(dst, b, h) do { _Pragma("unroll") for (int m = 0; m < 4; ++m) _Pragma("unroll") for (int k = 0; k < 2; ++k) dst[m][k] = *(const LAS bf16x8*)(lds + PG8_SA(b, h) + aoff + m * 2048 + k * 1024); } while (0)
; #define PG8_LDB(dst, b, h) do { _Pragma("unroll") for (int n = 0; n < 2; ++n) _Pragma("unroll") for (int k = 0; k < 2; ++k) dst[n][k] = *(const LAS bf16x8*)(lds + PG8_SB(b, h) + boff + n * 2048 + k * 1024); } while (0)
; #define PG8_MMA(ai, bj, At, Bt) do { __builtin_amdgcn_s_setprio(1); _Pragma("unroll") for (int m = 0; m < 4; ++m) _Pragma("unroll") for (int n = 0; n < 2; ++n) _Pragma("unroll") for (int k = 0; k < 2; ++k) \
;         acc[ai][bj][m][n] = __builtin_amdgcn_mfma_f32_16x16x32_bf16(Bt[n][k], At[m][k], acc[ai][bj][m][n], 0, 0, 0); __builtin_amdgcn_s_setprio(0); } while (0)
; #define PG8_WAIT_V(n) asm volatile("s_waitcnt vmcnt(" #n ")" ::: "memory")
; #define PG8_WAIT_L(n) asm volatile("s_waitcnt lgkmcnt(" #n ")" ::: "memory")
; #define PG8_BAR __builtin_amdgcn_s_barrier()
; #define PG8_SCHED __builtin_amdgcn_sched_barrier(0)
; template <class Epi, class Sched, int LDA, int LDB, bool ALIGN_EPI = true>
; __device__ __forceinline__ void gemm_phase(LAS unsigned char* lds, const Gemm g, const Sched& S, const Epi& E, int wave) {
;     ...
;             PG8_WAIT_V(8); PG8_WAIT_L(0); PG8_BAR; PG8_MMA(1, 0, At, B0); PG8_MMA(1, 1, At, B1); PG8_BAR; PG8_SCHED;
;             PG8_LDB(B0, 1, 0); PG8_LDB(B1, 1, 1); PG8_SCHED; PG8_LDA(At, 1, 0); PG8_STAGE(PG8_SA(0, 1), a2 + hstepA, voffA);
;             PG8_WAIT_V(8); PG8_WAIT_L(0); PG8_BAR; PG8_MMA(0, 0, At, B0); PG8_MMA(0, 1, At, B1); PG8_BAR; PG8_SCHED;
	v_mfma_f32_16x16x32_bf16 v[62:65], v[144:147], v[184:187], v[62:65]
	v_mfma_f32_16x16x32_bf16 v[58:61], v[156:159], v[184:187], v[58:61]
	v_mfma_f32_16x16x32_bf16 v[46:49], v[144:147], v[192:195], v[46:49]
	v_mfma_f32_16x16x32_bf16 v[42:45], v[156:159], v[192:195], v[42:45]
	v_mfma_f32_16x16x32_bf16 v[30:33], v[144:147], v[200:203], v[30:33]
	v_mfma_f32_16x16x32_bf16 v[26:29], v[156:159], v[200:203], v[26:29]
	v_mfma_f32_16x16x32_bf16 v[14:17], v[144:147], v[208:211], v[14:17]
	v_mfma_f32_16x16x32_bf16 v[10:13], v[156:159], v[208:211], v[10:13]
	v_mfma_f32_16x16x32_bf16 v[62:65], v[148:151], v[188:191], v[62:65]
	v_mfma_f32_16x16x32_bf16 v[58:61], v[160:163], v[188:191], v[58:61]
	v_mfma_f32_16x16x32_bf16 v[46:49], v[148:151], v[196:199], v[46:49]
	v_mfma_f32_16x16x32_bf16 v[42:45], v[160:163], v[196:199], v[42:45]
	v_mfma_f32_16x16x32_bf16 v[30:33], v[148:151], v[204:207], v[30:33]
	v_mfma_f32_16x16x32_bf16 v[26:29], v[160:163], v[204:207], v[26:29]
	v_mfma_f32_16x16x32_bf16 v[14:17], v[148:151], v[212:215], v[14:17]
	v_mfma_f32_16x16x32_bf16 v[10:13], v[160:163], v[212:215], v[10:13]
	v_mfma_f32_16x16x32_bf16 v[54:57], v[164:167], v[184:187], v[54:57]
	v_mfma_f32_16x16x32_bf16 v[50:53], v[172:175], v[184:187], v[50:53]
	v_mfma_f32_16x16x32_bf16 v[38:41], v[164:167], v[192:195], v[38:41]
	v_mfma_f32_16x16x32_bf16 v[34:37], v[172:175], v[192:195], v[34:37]
	v_mfma_f32_16x16x32_bf16 v[22:25], v[164:167], v[200:203], v[22:25]
	v_mfma_f32_16x16x32_bf16 v[18:21], v[172:175], v[200:203], v[18:21]
	v_mfma_f32_16x16x32_bf16 v[6:9], v[164:167], v[208:211], v[6:9]
	v_mfma_f32_16x16x32_bf16 v[2:5], v[172:175], v[208:211], v[2:5]
	v_mfma_f32_16x16x32_bf16 v[54:57], v[168:171], v[188:191], v[54:57]
	v_mfma_f32_16x16x32_bf16 v[50:53], v[180:183], v[188:191], v[50:53]
	v_mfma_f32_16x16x32_bf16 v[38:41], v[168:171], v[196:199], v[38:41]
	v_mfma_f32_16x16x32_bf16 v[34:37], v[180:183], v[196:199], v[34:37]
	v_mfma_f32_16x16x32_bf16 v[22:25], v[168:171], v[204:207], v[22:25]
	v_mfma_f32_16x16x32_bf16 v[18:21], v[180:183], v[204:207], v[18:21]
	v_mfma_f32_16x16x32_bf16 v[6:9], v[168:171], v[212:215], v[6:9]
	v_mfma_f32_16x16x32_bf16 v[2:5], v[180:183], v[212:215], v[2:5]
	s_barrier
	s_setprio 0
	s_add_i32 s50, 0, 0x18000
	v_add_u32_e32 v0, s50, v153
	s_add_i32 s51, 0, 0x1c000
	ds_read_b128 v[144:147], v0
	ds_read_b128 v[148:151], v0 offset:1024
	ds_read_b128 v[156:159], v0 offset:2048
	ds_read_b128 v[160:163], v0 offset:3072
	v_add_u32_e32 v0, s51, v153
	ds_read_b128 v[164:167], v0
	ds_read_b128 v[168:171], v0 offset:1024
	ds_read_b128 v[172:175], v0 offset:2048
	ds_read_b128 v[180:183], v0 offset:3072
	s_add_u32 s28, s28, 0x80000
	s_addc_u32 s29, s29, 0
	s_mov_b32 m0, s35
	v_lshl_add_u64 v[224:225], s[28:29], 0, v[130:131]
	ds_read_b128 v[184:187], v155 offset:32768
	ds_read_b128 v[188:191], v155 offset:33792
	ds_read_b128 v[192:195], v155 offset:34816
	ds_read_b128 v[196:199], v155 offset:35840
	ds_read_b128 v[200:203], v155 offset:36864
	ds_read_b128 v[204:207], v155 offset:37888
	ds_read_b128 v[208:211], v155 offset:38912
	ds_read_b128 v[212:215], v155 offset:39936
	global_load_lds_dwordx4 v[224:225], off
	v_lshl_add_u64 v[224:225], s[28:29], 0, v[134:135]
	s_mov_b32 m0, s36
	s_nop 0
	global_load_lds_dwordx4 v[224:225], off
	s_waitcnt vmcnt(8)
	s_waitcnt lgkmcnt(0)
	s_setprio 1
	s_barrier
	v_mfma_f32_16x16x32_bf16 v[126:129], v[144:147], v[184:187], v[126:129]
	v_mfma_f32_16x16x32_bf16 v[122:125], v[156:159], v[184:187], v[122:125]
	v_mfma_f32_16x16x32_bf16 v[110:113], v[144:147], v[192:195], v[110:113]
	v_mfma_f32_16x16x32_bf16 v[106:109], v[156:159], v[192:195], v[106:109]
	v_mfma_f32_16x16x32_bf16 v[94:97], v[144:147], v[200:203], v[94:97]
	v_mfma_f32_16x16x32_bf16 v[90:93], v[156:159], v[200:203], v[90:93]
	v_mfma_f32_16x16x32_bf16 v[78:81], v[144:147], v[208:211], v[78:81]
	v_mfma_f32_16x16x32_bf16 v[74:77], v[156:159], v[208:211], v[74:77]
	v_mfma_f32_16x16x32_bf16 v[126:129], v[148:151], v[188:191], v[126:129]
	v_mfma_f32_16x16x32_bf16 v[122:125], v[160:163], v[188:191], v[122:125]
	v_mfma_f32_16x16x32_bf16 v[110:113], v[148:151], v[196:199], v[110:113]
	v_mfma_f32_16x16x32_bf16 v[106:109], v[160:163], v[196:199], v[106:109]
	v_mfma_f32_16x16x32_bf16 v[94:97], v[148:151], v[204:207], v[94:97]
	v_mfma_f32_16x16x32_bf16 v[90:93], v[160:163], v[204:207], v[90:93]
	v_mfma_f32_16x16x32_bf16 v[78:81], v[148:151], v[212:215], v[78:81]
	v_mfma_f32_16x16x32_bf16 v[74:77], v[160:163], v[212:215], v[74:77]
	v_mfma_f32_16x16x32_bf16 v[118:121], v[164:167], v[184:187], v[118:121]
	v_mfma_f32_16x16x32_bf16 v[114:117], v[172:175], v[184:187], v[114:117]
	v_mfma_f32_16x16x32_bf16 v[102:105], v[164:167], v[192:195], v[102:105]
	v_mfma_f32_16x16x32_bf16 v[98:101], v[172:175], v[192:195], v[98:101]
	v_mfma_f32_16x16x32_bf16 v[86:89], v[164:167], v[200:203], v[86:89]
	v_mfma_f32_16x16x32_bf16 v[82:85], v[172:175], v[200:203], v[82:85]
	v_mfma_f32_16x16x32_bf16 v[70:73], v[164:167], v[208:211], v[70:73]
	v_mfma_f32_16x16x32_bf16 v[66:69], v[172:175], v[208:211], v[66:69]
	v_mfma_f32_16x16x32_bf16 v[118:121], v[168:171], v[188:191], v[118:121]
	v_mfma_f32_16x16x32_bf16 v[114:117], v[180:183], v[188:191], v[114:117]
	v_mfma_f32_16x16x32_bf16 v[102:105], v[168:171], v[196:199], v[102:105]
	v_mfma_f32_16x16x32_bf16 v[98:101], v[180:183], v[196:199], v[98:101]
	v_mfma_f32_16x16x32_bf16 v[86:89], v[168:171], v[204:207], v[86:89]
	v_mfma_f32_16x16x32_bf16 v[82:85], v[180:183], v[204:207], v[82:85]
	v_mfma_f32_16x16x32_bf16 v[70:73], v[168:171], v[212:215], v[70:73]
	v_mfma_f32_16x16x32_bf16 v[66:69], v[180:183], v[212:215], v[66:69]
	s_barrier
; #define PG8_STAGE(bufoff, gbase, voff) do { _Pragma("unroll") for (int _i = 0; _i < 2; ++_i) \
;         __builtin_amdgcn_global_load_lds((const unsigned*)((const char*)(gbase) + (voff)[_i]), (LAS unsigned*)(lds + (bufoff) + ldsw + _i * 8192), 16, 0, 0); } while (0)
; #define PG8_LDA(dst, b, h) do { _Pragma("unroll") for (int m = 0; m < 4; ++m) _Pragma("unroll") for (int k = 0; k < 2; ++k) dst[m][k] = *(const LAS bf16x8*)(lds + PG8_SA(b, h) + aoff + m * 2048 + k * 1024); } while (0)
; #define PG8_MMA(ai, bj, At, Bt) do { __builtin_amdgcn_s_setprio(1); _Pragma("unroll") for (int m = 0; m < 4; ++m) _Pragma("unroll") for (int n = 0; n < 2; ++n) _Pragma("unroll") for (int k = 0; k < 2; ++k) \
;         acc[ai][bj][m][n] = __builtin_amdgcn_mfma_f32_16x16x32_bf16(Bt[n][k], At[m][k], acc[ai][bj][m][n], 0, 0, 0); __builtin_amdgcn_s_setprio(0); } while (0)
; #define PG8_WAIT_V(n) asm volatile("s_waitcnt vmcnt(" #n ")" ::: "memory")
; #define PG8_WAIT_L(n) asm volatile("s_waitcnt lgkmcnt(" #n ")" ::: "memory")
; #define PG8_BAR __builtin_amdgcn_s_barrier()
; #define PG8_SCHED __builtin_amdgcn_sched_barrier(0)
; template <class Epi, class Sched, int LDA, int LDB, bool ALIGN_EPI = true>
; __device__ __forceinline__ void gemm_phase(LAS unsigned char* lds, const Gemm g, const Sched& S, const Epi& E, int wave) {
;     ...
;             PG8_LDA(At, 1, 1); PG8_STAGE(PG8_SB(1, 0), b3, voffB); PG8_STAGE(PG8_SB(1, 1), b3 + hstepB, voffB); PG8_STAGE(PG8_SA(1, 0), a3, voffA);
;             PG8_WAIT_V(8); PG8_WAIT_L(0); PG8_BAR; PG8_MMA(1, 0, At, B0); PG8_MMA(1, 1, At, B1); PG8_BAR; PG8_SCHED;
;         }
	s_setprio 0
	s_add_i32 s28, s50, s53
	v_lshl_add_u64 v[216:217], v[216:217], 0, s[54:55]
	s_mov_b32 m0, s28
	ds_read_b128 v[184:187], v155 offset:49152
	ds_read_b128 v[188:191], v155 offset:50176
	ds_read_b128 v[192:195], v155 offset:51200
	ds_read_b128 v[196:199], v155 offset:52224
	ds_read_b128 v[200:203], v155 offset:53248
	ds_read_b128 v[204:207], v155 offset:54272
	ds_read_b128 v[208:211], v155 offset:55296
	ds_read_b128 v[212:215], v155 offset:56320
	global_load_lds_dwordx4 v[216:217], off
	s_add_i32 m0, s28, 0x2000
	s_add_u32 s24, s24, 0x80080
	v_lshl_add_u64 v[216:217], v[218:219], 0, s[54:55]
	s_addc_u32 s25, s25, 0
	s_add_i32 s28, s51, s53
	global_load_lds_dwordx4 v[216:217], off
	v_lshl_add_u64 v[216:217], s[24:25], 0, v[132:133]
	s_mov_b32 m0, s28
	s_nop 0
	global_load_lds_dwordx4 v[216:217], off
	v_lshl_add_u64 v[216:217], s[24:25], 0, v[136:137]
	s_add_i32 m0, s28, 0x2000
	s_nop 0
	global_load_lds_dwordx4 v[216:217], off
	v_lshl_add_u64 v[216:217], v[220:221], 0, s[54:55]
	s_mov_b32 m0, s37
	s_nop 0
	global_load_lds_dwordx4 v[216:217], off
	v_lshl_add_u64 v[216:217], v[222:223], 0, s[54:55]
	s_mov_b32 m0, s38
	s_nop 0
	global_load_lds_dwordx4 v[216:217], off
	s_waitcnt vmcnt(8)
	s_waitcnt lgkmcnt(0)
	s_setprio 1
	s_barrier
	v_mfma_f32_16x16x32_bf16 v[62:65], v[144:147], v[184:187], v[62:65]
	v_mfma_f32_16x16x32_bf16 v[58:61], v[156:159], v[184:187], v[58:61]
	v_mfma_f32_16x16x32_bf16 v[46:49], v[144:147], v[192:195], v[46:49]
	v_mfma_f32_16x16x32_bf16 v[42:45], v[156:159], v[192:195], v[42:45]
	v_mfma_f32_16x16x32_bf16 v[30:33], v[144:147], v[200:203], v[30:33]
	v_mfma_f32_16x16x32_bf16 v[26:29], v[156:159], v[200:203], v[26:29]
	v_mfma_f32_16x16x32_bf16 v[14:17], v[144:147], v[208:211], v[14:17]
	v_mfma_f32_16x16x32_bf16 v[10:13], v[156:159], v[208:211], v[10:13]
	v_mfma_f32_16x16x32_bf16 v[62:65], v[148:151], v[188:191], v[62:65]
	v_mfma_f32_16x16x32_bf16 v[58:61], v[160:163], v[188:191], v[58:61]
	v_mfma_f32_16x16x32_bf16 v[46:49], v[148:151], v[196:199], v[46:49]
	v_mfma_f32_16x16x32_bf16 v[42:45], v[160:163], v[196:199], v[42:45]
	v_mfma_f32_16x16x32_bf16 v[30:33], v[148:151], v[204:207], v[30:33]
	v_mfma_f32_16x16x32_bf16 v[26:29], v[160:163], v[204:207], v[26:29]
	v_mfma_f32_16x16x32_bf16 v[14:17], v[148:151], v[212:215], v[14:17]
	v_mfma_f32_16x16x32_bf16 v[10:13], v[160:163], v[212:215], v[10:13]
	v_mfma_f32_16x16x32_bf16 v[54:57], v[164:167], v[184:187], v[54:57]
	v_mfma_f32_16x16x32_bf16 v[50:53], v[172:175], v[184:187], v[50:53]
	v_mfma_f32_16x16x32_bf16 v[38:41], v[164:167], v[192:195], v[38:41]
	v_mfma_f32_16x16x32_bf16 v[34:37], v[172:175], v[192:195], v[34:37]
	v_mfma_f32_16x16x32_bf16 v[22:25], v[164:167], v[200:203], v[22:25]
	v_mfma_f32_16x16x32_bf16 v[18:21], v[172:175], v[200:203], v[18:21]
	v_mfma_f32_16x16x32_bf16 v[6:9], v[164:167], v[208:211], v[6:9]
	v_mfma_f32_16x16x32_bf16 v[2:5], v[172:175], v[208:211], v[2:5]
	v_mfma_f32_16x16x32_bf16 v[54:57], v[168:171], v[188:191], v[54:57]
	v_mfma_f32_16x16x32_bf16 v[50:53], v[180:183], v[188:191], v[50:53]
	v_mfma_f32_16x16x32_bf16 v[38:41], v[168:171], v[196:199], v[38:41]
	v_mfma_f32_16x16x32_bf16 v[34:37], v[180:183], v[196:199], v[34:37]
	v_mfma_f32_16x16x32_bf16 v[22:25], v[168:171], v[204:207], v[22:25]
	v_mfma_f32_16x16x32_bf16 v[18:21], v[180:183], v[204:207], v[18:21]
	v_mfma_f32_16x16x32_bf16 v[6:9], v[168:171], v[212:215], v[6:9]
	v_mfma_f32_16x16x32_bf16 v[2:5], v[180:183], v[212:215], v[2:5]
	s_barrier
	s_setprio 0
	s_add_u32 s18, s18, 0x100
	s_addc_u32 s19, s19, 0
	s_add_u32 s44, s44, 0x100
	s_addc_u32 s45, s45, 0
	s_cmp_ge_i32 s49, s43
	s_mov_b32 s24, s49
	s_cbranch_scc0 .LBB0_4715
	v_readlane_b32 s18, v252, 14
	v_readlane_b32 s19, v252, 15
	s_and_b64 vcc, exec, s[18:19]
	s_cbranch_vccz .LBB0_4718
	s_barrier

; #define PG8_STAGE(bufoff, gbase, voff) do { _Pragma("unroll") for (int _i = 0; _i < 2; ++_i) \
;         __builtin_amdgcn_global_load_lds((const unsigned*)((const char*)(gbase) + (voff)[_i]), (LAS unsigned*)(lds + (bufoff) + ldsw + _i * 8192), 16, 0, 0); } while (0)
; #define PG8_LDA(dst, b, h) do { _Pragma("unroll") for (int m = 0; m < 4; ++m) _Pragma("unroll") for (int k = 0; k < 2; ++k) dst[m][k] = *(const LAS bf16x8*)(lds + PG8_SA(b, h) + aoff + m * 2048 + k * 1024); } while (0)
; #define PG8_LDB(dst, b, h) do { _Pragma("unroll") for (int n = 0; n < 2; ++n) _Pragma("unroll") for (int k = 0; k < 2; ++k) dst[n][k] = *(const LAS bf16x8*)(lds + PG8_SB(b, h) + boff + n * 2048 + k * 1024); } while (0)
; #define PG8_MMA(ai, bj, At, Bt) do { __builtin_amdgcn_s_setprio(1); _Pragma("unroll") for (int m = 0; m < 4; ++m) _Pragma("unroll") for (int n = 0; n < 2; ++n) _Pragma("unroll") for (int k = 0; k < 2; ++k) \
;         acc[ai][bj][m][n] = __builtin_amdgcn_mfma_f32_16x16x32_bf16(Bt[n][k], At[m][k], acc[ai][bj][m][n], 0, 0, 0); __builtin_amdgcn_s_setprio(0); } while (0)
; #define PG8_WAIT_V(n) asm volatile("s_waitcnt vmcnt(" #n ")" ::: "memory")
; #define PG8_WAIT_L(n) asm volatile("s_waitcnt lgkmcnt(" #n ")" ::: "memory")
; #define PG8_BAR __builtin_amdgcn_s_barrier()
; #define PG8_SCHED __builtin_amdgcn_sched_barrier(0)
; template <class Epi, class Sched, int LDA, int LDB, bool ALIGN_EPI = true>
; __device__ __forceinline__ void gemm_phase(LAS unsigned char* lds, const Gemm g, const Sched& S, const Epi& E, int wave) {
;     ...
;             const bool last = (t == nt - 2);
;             const char* a1 = cA + (size_t)(t + 1) * kstep;
;             const char* a2 = last ? nA : cA + (size_t)(t + 2) * kstep; const char* b2 = last ? nB : cB + (size_t)(t + 2) * kstep;
;             const char* a3 = a2 + kstep; const char* b3 = b2 + kstep;
;             PG8_LDB(B0, 0, 0); PG8_LDB(B1, 0, 1); PG8_SCHED; PG8_LDA(At, 0, 0); PG8_STAGE(PG8_SA(1, 1), a1 + hstepA, voffA);
;             PG8_WAIT_V(8); PG8_WAIT_L(0); PG8_BAR; PG8_MMA(0, 0, At, B0); PG8_MMA(0, 1, At, B1); PG8_BAR; PG8_SCHED;
;             PG8_LDA(At, 0, 1); PG8_STAGE(PG8_SB(0, 0), b2, voffB); PG8_STAGE(PG8_SB(0, 1), b2 + hstepB, voffB); PG8_STAGE(PG8_SA(0, 0), a2, voffA);
;             PG8_WAIT_V(8); PG8_WAIT_L(0); PG8_BAR; PG8_MMA(1, 0, At, B0); PG8_MMA(1, 1, At, B1); PG8_BAR; PG8_SCHED;
.LBB0_4901:
	s_add_i32 s65, s36, 2
	s_add_u32 s37, s34, 0xfff80080
	s_addc_u32 s38, s35, -1
	s_add_i32 s66, 0, 0x10000
	s_cmp_eq_u32 s29, s36
	s_cselect_b32 s39, s9, s38
	s_cselect_b32 s38, s13, s37
	s_cselect_b32 s37, s11, s64
	s_cselect_b32 s36, s25, s59
	s_add_i32 s72, 0, 0x14000
	v_add_u32_e32 v70, s66, v213
	v_add_u32_e32 v168, s72, v213
	ds_read_b128 v[50:53], v70
	ds_read_b128 v[54:57], v70 offset:1024
	ds_read_b128 v[66:69], v70 offset:2048
	ds_read_b128 v[70:73], v70 offset:3072
	ds_read_b128 v[156:159], v168
	ds_read_b128 v[160:163], v168 offset:1024
	ds_read_b128 v[164:167], v168 offset:2048
	ds_read_b128 v[168:171], v168 offset:3072
	v_lshl_add_u64 v[208:209], s[34:35], 0, v[152:153]
	s_add_i32 m0, s27, 0xc000
	ds_read_b128 v[172:175], v215
	ds_read_b128 v[180:183], v215 offset:1024
	ds_read_b128 v[184:187], v215 offset:2048
	ds_read_b128 v[188:191], v215 offset:3072
	ds_read_b128 v[192:195], v215 offset:4096
	ds_read_b128 v[196:199], v215 offset:5120
	ds_read_b128 v[200:203], v215 offset:6144
	ds_read_b128 v[204:207], v215 offset:7168
	global_load_lds_dwordx4 v[208:209], off
	v_lshl_add_u64 v[208:209], s[34:35], 0, v[154:155]
	s_add_i32 m0, s27, 0xe000
	s_nop 0
	global_load_lds_dwordx4 v[208:209], off
	s_waitcnt vmcnt(8)
	s_waitcnt lgkmcnt(0)
	s_setprio 1
	s_barrier
	v_mfma_f32_16x16x32_bf16 v[142:145], v[50:53], v[172:175], v[142:145]
	v_mfma_f32_16x16x32_bf16 v[138:141], v[66:69], v[172:175], v[138:141]
	v_mfma_f32_16x16x32_bf16 v[126:129], v[50:53], v[184:187], v[126:129]
	v_mfma_f32_16x16x32_bf16 v[122:125], v[66:69], v[184:187], v[122:125]
	v_mfma_f32_16x16x32_bf16 v[110:113], v[50:53], v[192:195], v[110:113]
	v_mfma_f32_16x16x32_bf16 v[106:109], v[66:69], v[192:195], v[106:109]
	v_mfma_f32_16x16x32_bf16 v[94:97], v[50:53], v[200:203], v[94:97]
	v_mfma_f32_16x16x32_bf16 v[90:93], v[66:69], v[200:203], v[90:93]
	v_mfma_f32_16x16x32_bf16 v[142:145], v[54:57], v[180:183], v[142:145]
	v_mfma_f32_16x16x32_bf16 v[138:141], v[70:73], v[180:183], v[138:141]
	v_mfma_f32_16x16x32_bf16 v[126:129], v[54:57], v[188:191], v[126:129]
	v_mfma_f32_16x16x32_bf16 v[122:125], v[70:73], v[188:191], v[122:125]
	v_mfma_f32_16x16x32_bf16 v[110:113], v[54:57], v[196:199], v[110:113]
	v_mfma_f32_16x16x32_bf16 v[106:109], v[70:73], v[196:199], v[106:109]
	v_mfma_f32_16x16x32_bf16 v[94:97], v[54:57], v[204:207], v[94:97]
	v_mfma_f32_16x16x32_bf16 v[90:93], v[70:73], v[204:207], v[90:93]
	v_mfma_f32_16x16x32_bf16 v[134:137], v[156:159], v[172:175], v[134:137]
	v_mfma_f32_16x16x32_bf16 v[130:133], v[164:167], v[172:175], v[130:133]
	v_mfma_f32_16x16x32_bf16 v[118:121], v[156:159], v[184:187], v[118:121]
	v_mfma_f32_16x16x32_bf16 v[114:117], v[164:167], v[184:187], v[114:117]
	v_mfma_f32_16x16x32_bf16 v[102:105], v[156:159], v[192:195], v[102:105]
	v_mfma_f32_16x16x32_bf16 v[98:101], v[164:167], v[192:195], v[98:101]
	v_mfma_f32_16x16x32_bf16 v[86:89], v[156:159], v[200:203], v[86:89]
	v_mfma_f32_16x16x32_bf16 v[82:85], v[164:167], v[200:203], v[82:85]
	v_mfma_f32_16x16x32_bf16 v[134:137], v[160:163], v[180:183], v[134:137]
	v_mfma_f32_16x16x32_bf16 v[130:133], v[168:171], v[180:183], v[130:133]
	v_mfma_f32_16x16x32_bf16 v[118:121], v[160:163], v[188:191], v[118:121]
	v_mfma_f32_16x16x32_bf16 v[114:117], v[168:171], v[188:191], v[114:117]
	v_mfma_f32_16x16x32_bf16 v[102:105], v[160:163], v[196:199], v[102:105]
	v_mfma_f32_16x16x32_bf16 v[98:101], v[168:171], v[196:199], v[98:101]
	v_mfma_f32_16x16x32_bf16 v[86:89], v[160:163], v[204:207], v[86:89]
	v_mfma_f32_16x16x32_bf16 v[82:85], v[168:171], v[204:207], v[82:85]
	s_barrier
	s_setprio 0
	s_add_i32 s66, s66, s60
	v_lshl_add_u64 v[208:209], s[36:37], 0, v[0:1]
	s_mov_b32 m0, s66
	ds_read_b128 v[172:175], v215 offset:16384
	ds_read_b128 v[180:183], v215 offset:17408
	ds_read_b128 v[184:187], v215 offset:18432
	ds_read_b128 v[188:191], v215 offset:19456
	ds_read_b128 v[192:195], v215 offset:20480
	ds_read_b128 v[196:199], v215 offset:21504
	ds_read_b128 v[200:203], v215 offset:22528
	ds_read_b128 v[204:207], v215 offset:23552
	global_load_lds_dwordx4 v[208:209], off
	s_add_i32 m0, s66, 0x2000
	s_add_u32 s66, s36, 0x80000
	v_lshl_add_u64 v[210:211], s[36:37], 0, v[150:151]
	s_addc_u32 s67, s37, 0
	s_add_i32 s72, s72, s60
	global_load_lds_dwordx4 v[210:211], off
	v_lshl_add_u64 v[216:217], s[66:67], 0, v[0:1]
	s_mov_b32 m0, s72
	v_lshl_add_u64 v[218:219], s[38:39], 0, v[148:149]
	global_load_lds_dwordx4 v[216:217], off
	v_lshl_add_u64 v[216:217], s[66:67], 0, v[150:151]
	s_add_i32 m0, s72, 0x2000
	s_nop 0
	global_load_lds_dwordx4 v[216:217], off
	v_lshl_add_u64 v[216:217], s[38:39], 0, v[146:147]
	s_mov_b32 m0, s27
	s_nop 0
	global_load_lds_dwordx4 v[216:217], off
	s_mov_b32 m0, s44
	s_nop 0
	global_load_lds_dwordx4 v[218:219], off
	s_waitcnt vmcnt(8)
	s_waitcnt lgkmcnt(0)
	s_setprio 1
	s_barrier
; #define PG8_STAGE(bufoff, gbase, voff) do { _Pragma("unroll") for (int _i = 0; _i < 2; ++_i) \
;         __builtin_amdgcn_global_load_lds((const unsigned*)((const char*)(gbase) + (voff)[_i]), (LAS unsigned*)(lds + (bufoff) + ldsw + _i * 8192), 16, 0, 0); } while (0)
; #define PG8_LDA(dst, b, h) do { _Pragma("unroll") for (int m = 0; m < 4; ++m) _Pragma("unroll") for (int k = 0; k < 2; ++k) dst[m][k] = *(const LAS bf16x8*)(lds + PG8_SA(b, h) + aoff + m * 2048 + k * 1024); } while (0)
; #define PG8_LDB(dst, b, h) do { _Pragma("unroll") for (int n = 0; n < 2; ++n) _Pragma("unroll") for (int k = 0; k < 2; ++k) dst[n][k] = *(const LAS bf16x8*)(lds + PG8_SB(b, h) + boff + n * 2048 + k * 1024); } while (0)
; #define PG8_MMA(ai, bj, At, Bt) do { __builtin_amdgcn_s_setprio(1); _Pragma("unroll") for (int m = 0; m < 4; ++m) _Pragma("unroll") for (int n = 0; n < 2; ++n) _Pragma("unroll") for (int k = 0; k < 2; ++k) \
;         acc[ai][bj][m][n] = __builtin_amdgcn_mfma_f32_16x16x32_bf16(Bt[n][k], At[m][k], acc[ai][bj][m][n], 0, 0, 0); __builtin_amdgcn_s_setprio(0); } while (0)
; #define PG8_WAIT_V(n) asm volatile("s_waitcnt vmcnt(" #n ")" ::: "memory")
; #define PG8_WAIT_L(n) asm volatile("s_waitcnt lgkmcnt(" #n ")" ::: "memory")
; #define PG8_BAR __builtin_amdgcn_s_barrier()
; #define PG8_SCHED __builtin_amdgcn_sched_barrier(0)
; template <class Epi, class Sched, int LDA, int LDB, bool ALIGN_EPI = true>
; __device__ __forceinline__ void gemm_phase(LAS unsigned char* lds, const Gemm g, const Sched& S, const Epi& E, int wave) {
;     ...
;             PG8_WAIT_V(8); PG8_WAIT_L(0); PG8_BAR; PG8_MMA(1, 0, At, B0); PG8_MMA(1, 1, At, B1); PG8_BAR; PG8_SCHED;
;             PG8_LDB(B0, 1, 0); PG8_LDB(B1, 1, 1); PG8_SCHED; PG8_LDA(At, 1, 0); PG8_STAGE(PG8_SA(0, 1), a2 + hstepA, voffA);
;             PG8_WAIT_V(8); PG8_WAIT_L(0); PG8_BAR; PG8_MMA(0, 0, At, B0); PG8_MMA(0, 1, At, B1); PG8_BAR; PG8_SCHED;
	v_mfma_f32_16x16x32_bf16 v[78:81], v[50:53], v[172:175], v[78:81]
	v_mfma_f32_16x16x32_bf16 v[74:77], v[66:69], v[172:175], v[74:77]
	v_mfma_f32_16x16x32_bf16 v[46:49], v[50:53], v[184:187], v[46:49]
	v_mfma_f32_16x16x32_bf16 v[42:45], v[66:69], v[184:187], v[42:45]
	v_mfma_f32_16x16x32_bf16 v[30:33], v[50:53], v[192:195], v[30:33]
	v_mfma_f32_16x16x32_bf16 v[26:29], v[66:69], v[192:195], v[26:29]
	v_mfma_f32_16x16x32_bf16 v[14:17], v[50:53], v[200:203], v[14:17]
	v_mfma_f32_16x16x32_bf16 v[10:13], v[66:69], v[200:203], v[10:13]
	v_mfma_f32_16x16x32_bf16 v[78:81], v[54:57], v[180:183], v[78:81]
	v_mfma_f32_16x16x32_bf16 v[74:77], v[70:73], v[180:183], v[74:77]
	v_mfma_f32_16x16x32_bf16 v[46:49], v[54:57], v[188:191], v[46:49]
	v_mfma_f32_16x16x32_bf16 v[42:45], v[70:73], v[188:191], v[42:45]
	v_mfma_f32_16x16x32_bf16 v[30:33], v[54:57], v[196:199], v[30:33]
	v_mfma_f32_16x16x32_bf16 v[26:29], v[70:73], v[196:199], v[26:29]
	v_mfma_f32_16x16x32_bf16 v[14:17], v[54:57], v[204:207], v[14:17]
	v_mfma_f32_16x16x32_bf16 v[10:13], v[70:73], v[204:207], v[10:13]
	v_mfma_f32_16x16x32_bf16 v[38:41], v[156:159], v[184:187], v[38:41]
	v_mfma_f32_16x16x32_bf16 v[34:37], v[164:167], v[184:187], v[34:37]
	v_mfma_f32_16x16x32_bf16 v[22:25], v[156:159], v[192:195], v[22:25]
	v_mfma_f32_16x16x32_bf16 v[18:21], v[164:167], v[192:195], v[18:21]
	v_mfma_f32_16x16x32_bf16 v[6:9], v[156:159], v[200:203], v[6:9]
	v_mfma_f32_16x16x32_bf16 v[2:5], v[164:167], v[200:203], v[2:5]
	v_mfma_f32_16x16x32_bf16 v[50:53], v[156:159], v[172:175], v[62:65]
	v_mfma_f32_16x16x32_bf16 v[54:57], v[164:167], v[172:175], v[58:61]
	v_mfma_f32_16x16x32_bf16 v[38:41], v[160:163], v[188:191], v[38:41]
	v_mfma_f32_16x16x32_bf16 v[34:37], v[168:171], v[188:191], v[34:37]
	v_mfma_f32_16x16x32_bf16 v[22:25], v[160:163], v[196:199], v[22:25]
	v_mfma_f32_16x16x32_bf16 v[18:21], v[168:171], v[196:199], v[18:21]
	v_mfma_f32_16x16x32_bf16 v[6:9], v[160:163], v[204:207], v[6:9]
	v_mfma_f32_16x16x32_bf16 v[2:5], v[168:171], v[204:207], v[2:5]
	v_mfma_f32_16x16x32_bf16 v[50:53], v[160:163], v[180:183], v[50:53]
	v_mfma_f32_16x16x32_bf16 v[54:57], v[168:171], v[180:183], v[54:57]
	s_barrier
	s_setprio 0
	s_add_i32 s66, 0, 0x18000
	s_add_i32 s67, 0, 0x1c000
	v_add_u32_e32 v70, s66, v213
	v_add_u32_e32 v168, s67, v213
	ds_read_b128 v[58:61], v70
	ds_read_b128 v[62:65], v70 offset:1024
	ds_read_b128 v[66:69], v70 offset:2048
	ds_read_b128 v[70:73], v70 offset:3072
	ds_read_b128 v[156:159], v168
	ds_read_b128 v[160:163], v168 offset:1024
	ds_read_b128 v[164:167], v168 offset:2048
	ds_read_b128 v[168:171], v168 offset:3072
	s_add_u32 s38, s38, 0x80000
	s_addc_u32 s39, s39, 0
	s_mov_b32 m0, s45
	v_lshl_add_u64 v[220:221], s[38:39], 0, v[146:147]
	ds_read_b128 v[172:175], v215 offset:32768
	ds_read_b128 v[180:183], v215 offset:33792
	ds_read_b128 v[184:187], v215 offset:34816
	ds_read_b128 v[188:191], v215 offset:35840
	ds_read_b128 v[192:195], v215 offset:36864
	ds_read_b128 v[196:199], v215 offset:37888
	ds_read_b128 v[200:203], v215 offset:38912
	ds_read_b128 v[204:207], v215 offset:39936
	global_load_lds_dwordx4 v[220:221], off
	v_lshl_add_u64 v[220:221], s[38:39], 0, v[148:149]
	s_mov_b32 m0, s46
	s_nop 0
	global_load_lds_dwordx4 v[220:221], off
	s_waitcnt vmcnt(8)
	s_waitcnt lgkmcnt(0)
	s_setprio 1
	s_barrier
	v_mfma_f32_16x16x32_bf16 v[142:145], v[58:61], v[172:175], v[142:145]
	v_mfma_f32_16x16x32_bf16 v[138:141], v[66:69], v[172:175], v[138:141]
	v_mfma_f32_16x16x32_bf16 v[126:129], v[58:61], v[184:187], v[126:129]
	v_mfma_f32_16x16x32_bf16 v[122:125], v[66:69], v[184:187], v[122:125]
	v_mfma_f32_16x16x32_bf16 v[110:113], v[58:61], v[192:195], v[110:113]
	v_mfma_f32_16x16x32_bf16 v[106:109], v[66:69], v[192:195], v[106:109]
	v_mfma_f32_16x16x32_bf16 v[94:97], v[58:61], v[200:203], v[94:97]
	v_mfma_f32_16x16x32_bf16 v[90:93], v[66:69], v[200:203], v[90:93]
	v_mfma_f32_16x16x32_bf16 v[142:145], v[62:65], v[180:183], v[142:145]
	v_mfma_f32_16x16x32_bf16 v[138:141], v[70:73], v[180:183], v[138:141]
	v_mfma_f32_16x16x32_bf16 v[126:129], v[62:65], v[188:191], v[126:129]
	v_mfma_f32_16x16x32_bf16 v[122:125], v[70:73], v[188:191], v[122:125]
	v_mfma_f32_16x16x32_bf16 v[110:113], v[62:65], v[196:199], v[110:113]
	v_mfma_f32_16x16x32_bf16 v[106:109], v[70:73], v[196:199], v[106:109]
	v_mfma_f32_16x16x32_bf16 v[94:97], v[62:65], v[204:207], v[94:97]
	v_mfma_f32_16x16x32_bf16 v[90:93], v[70:73], v[204:207], v[90:93]
	v_mfma_f32_16x16x32_bf16 v[134:137], v[156:159], v[172:175], v[134:137]
	v_mfma_f32_16x16x32_bf16 v[130:133], v[164:167], v[172:175], v[130:133]
	v_mfma_f32_16x16x32_bf16 v[118:121], v[156:159], v[184:187], v[118:121]
	v_mfma_f32_16x16x32_bf16 v[114:117], v[164:167], v[184:187], v[114:117]
	v_mfma_f32_16x16x32_bf16 v[102:105], v[156:159], v[192:195], v[102:105]
	v_mfma_f32_16x16x32_bf16 v[98:101], v[164:167], v[192:195], v[98:101]
	v_mfma_f32_16x16x32_bf16 v[86:89], v[156:159], v[200:203], v[86:89]
	v_mfma_f32_16x16x32_bf16 v[82:85], v[164:167], v[200:203], v[82:85]
	v_mfma_f32_16x16x32_bf16 v[134:137], v[160:163], v[180:183], v[134:137]
	v_mfma_f32_16x16x32_bf16 v[130:133], v[168:171], v[180:183], v[130:133]
	v_mfma_f32_16x16x32_bf16 v[118:121], v[160:163], v[188:191], v[118:121]
	v_mfma_f32_16x16x32_bf16 v[114:117], v[168:171], v[188:191], v[114:117]
	v_mfma_f32_16x16x32_bf16 v[102:105], v[160:163], v[196:199], v[102:105]
	v_mfma_f32_16x16x32_bf16 v[98:101], v[168:171], v[196:199], v[98:101]
	v_mfma_f32_16x16x32_bf16 v[86:89], v[160:163], v[204:207], v[86:89]
	v_mfma_f32_16x16x32_bf16 v[82:85], v[168:171], v[204:207], v[82:85]
	s_barrier
; #define PG8_STAGE(bufoff, gbase, voff) do { _Pragma("unroll") for (int _i = 0; _i < 2; ++_i) \
;         __builtin_amdgcn_global_load_lds((const unsigned*)((const char*)(gbase) + (voff)[_i]), (LAS unsigned*)(lds + (bufoff) + ldsw + _i * 8192), 16, 0, 0); } while (0)
; #define PG8_LDA(dst, b, h) do { _Pragma("unroll") for (int m = 0; m < 4; ++m) _Pragma("unroll") for (int k = 0; k < 2; ++k) dst[m][k] = *(const LAS bf16x8*)(lds + PG8_SA(b, h) + aoff + m * 2048 + k * 1024); } while (0)
; #define PG8_MMA(ai, bj, At, Bt) do { __builtin_amdgcn_s_setprio(1); _Pragma("unroll") for (int m = 0; m < 4; ++m) _Pragma("unroll") for (int n = 0; n < 2; ++n) _Pragma("unroll") for (int k = 0; k < 2; ++k) \
;         acc[ai][bj][m][n] = __builtin_amdgcn_mfma_f32_16x16x32_bf16(Bt[n][k], At[m][k], acc[ai][bj][m][n], 0, 0, 0); __builtin_amdgcn_s_setprio(0); } while (0)
; #define PG8_WAIT_V(n) asm volatile("s_waitcnt vmcnt(" #n ")" ::: "memory")
; #define PG8_WAIT_L(n) asm volatile("s_waitcnt lgkmcnt(" #n ")" ::: "memory")
; #define PG8_BAR __builtin_amdgcn_s_barrier()
; #define PG8_SCHED __builtin_amdgcn_sched_barrier(0)
; template <class Epi, class Sched, int LDA, int LDB, bool ALIGN_EPI = true>
; __device__ __forceinline__ void gemm_phase(LAS unsigned char* lds, const Gemm g, const Sched& S, const Epi& E, int wave) {
;     ...
;             PG8_LDA(At, 1, 1); PG8_STAGE(PG8_SB(1, 0), b3, voffB); PG8_STAGE(PG8_SB(1, 1), b3 + hstepB, voffB); PG8_STAGE(PG8_SA(1, 0), a3, voffA);
;             PG8_WAIT_V(8); PG8_WAIT_L(0); PG8_BAR; PG8_MMA(1, 0, At, B0); PG8_MMA(1, 1, At, B1); PG8_BAR; PG8_SCHED;
;         }
	s_setprio 0
	s_add_i32 s38, s66, s60
	v_lshl_add_u64 v[208:209], v[208:209], 0, s[70:71]
	s_mov_b32 m0, s38
	ds_read_b128 v[172:175], v215 offset:49152
	ds_read_b128 v[180:183], v215 offset:50176
	ds_read_b128 v[184:187], v215 offset:51200
	ds_read_b128 v[188:191], v215 offset:52224
	ds_read_b128 v[192:195], v215 offset:53248
	ds_read_b128 v[196:199], v215 offset:54272
	ds_read_b128 v[200:203], v215 offset:55296
	ds_read_b128 v[204:207], v215 offset:56320
	global_load_lds_dwordx4 v[208:209], off
	s_add_i32 m0, s38, 0x2000
	s_add_u32 s36, s36, 0x80080
	v_lshl_add_u64 v[208:209], v[210:211], 0, s[70:71]
	s_addc_u32 s37, s37, 0
	s_add_i32 s38, s67, s60
	global_load_lds_dwordx4 v[208:209], off
	v_lshl_add_u64 v[208:209], s[36:37], 0, v[0:1]
	s_mov_b32 m0, s38
	s_nop 0
	global_load_lds_dwordx4 v[208:209], off
	v_lshl_add_u64 v[208:209], s[36:37], 0, v[150:151]
	s_add_i32 m0, s38, 0x2000
	s_nop 0
	global_load_lds_dwordx4 v[208:209], off
	v_lshl_add_u64 v[208:209], v[216:217], 0, s[70:71]
	s_mov_b32 m0, s51
	s_nop 0
	global_load_lds_dwordx4 v[208:209], off
	v_lshl_add_u64 v[208:209], v[218:219], 0, s[70:71]
	s_mov_b32 m0, s52
	s_nop 0
	global_load_lds_dwordx4 v[208:209], off
	s_waitcnt vmcnt(8)
	s_waitcnt lgkmcnt(0)
	s_setprio 1
	s_barrier
	v_mfma_f32_16x16x32_bf16 v[78:81], v[58:61], v[172:175], v[78:81]
	v_mfma_f32_16x16x32_bf16 v[74:77], v[66:69], v[172:175], v[74:77]
	v_mfma_f32_16x16x32_bf16 v[46:49], v[58:61], v[184:187], v[46:49]
	v_mfma_f32_16x16x32_bf16 v[42:45], v[66:69], v[184:187], v[42:45]
	v_mfma_f32_16x16x32_bf16 v[30:33], v[58:61], v[192:195], v[30:33]
	v_mfma_f32_16x16x32_bf16 v[26:29], v[66:69], v[192:195], v[26:29]
	v_mfma_f32_16x16x32_bf16 v[14:17], v[58:61], v[200:203], v[14:17]
	v_mfma_f32_16x16x32_bf16 v[10:13], v[66:69], v[200:203], v[10:13]
	v_mfma_f32_16x16x32_bf16 v[78:81], v[62:65], v[180:183], v[78:81]
	v_mfma_f32_16x16x32_bf16 v[74:77], v[70:73], v[180:183], v[74:77]
	v_mfma_f32_16x16x32_bf16 v[46:49], v[62:65], v[188:191], v[46:49]
	v_mfma_f32_16x16x32_bf16 v[42:45], v[70:73], v[188:191], v[42:45]
	v_mfma_f32_16x16x32_bf16 v[30:33], v[62:65], v[196:199], v[30:33]
	v_mfma_f32_16x16x32_bf16 v[26:29], v[70:73], v[196:199], v[26:29]
	v_mfma_f32_16x16x32_bf16 v[14:17], v[62:65], v[204:207], v[14:17]
	v_mfma_f32_16x16x32_bf16 v[10:13], v[70:73], v[204:207], v[10:13]
	v_mfma_f32_16x16x32_bf16 v[50:53], v[156:159], v[172:175], v[50:53]
	v_mfma_f32_16x16x32_bf16 v[62:65], v[160:163], v[180:183], v[50:53]
	v_mfma_f32_16x16x32_bf16 v[50:53], v[164:167], v[172:175], v[54:57]
	v_mfma_f32_16x16x32_bf16 v[38:41], v[156:159], v[184:187], v[38:41]
	v_mfma_f32_16x16x32_bf16 v[34:37], v[164:167], v[184:187], v[34:37]
	v_mfma_f32_16x16x32_bf16 v[22:25], v[156:159], v[192:195], v[22:25]
	v_mfma_f32_16x16x32_bf16 v[18:21], v[164:167], v[192:195], v[18:21]
	v_mfma_f32_16x16x32_bf16 v[6:9], v[156:159], v[200:203], v[6:9]
	v_mfma_f32_16x16x32_bf16 v[2:5], v[164:167], v[200:203], v[2:5]
	v_mfma_f32_16x16x32_bf16 v[58:61], v[168:171], v[180:183], v[50:53]
	v_mfma_f32_16x16x32_bf16 v[38:41], v[160:163], v[188:191], v[38:41]
	v_mfma_f32_16x16x32_bf16 v[34:37], v[168:171], v[188:191], v[34:37]
	v_mfma_f32_16x16x32_bf16 v[22:25], v[160:163], v[196:199], v[22:25]
	v_mfma_f32_16x16x32_bf16 v[18:21], v[168:171], v[196:199], v[18:21]
	v_mfma_f32_16x16x32_bf16 v[6:9], v[160:163], v[204:207], v[6:9]
	v_mfma_f32_16x16x32_bf16 v[2:5], v[168:171], v[204:207], v[2:5]
	s_barrier
	s_setprio 0
	s_add_u32 s34, s34, 0x100
	s_addc_u32 s35, s35, 0
	s_add_u32 s59, s59, 0x100
	s_addc_u32 s64, s64, 0
	s_cmp_ge_i32 s65, s43
	s_mov_b32 s36, s65
	s_cbranch_scc0 .LBB0_4901
	v_readlane_b32 s34, v252, 14
	v_readlane_b32 s35, v252, 15
	s_and_b64 vcc, exec, s[34:35]
	s_cbranch_vccz .LBB0_4904
	s_barrier
